# q and k GEMM epilogues: per-row norm-sum and cos/sin loads hoisted to the top of the epilogue (no per-row wait on stores)
# speedup vs baseline: 1.0102x; 1.0012x over previous
; #define PG8_STAGE(bufoff, gbase, voff) do { _Pragma("unroll") for (int _i = 0; _i < 2; ++_i) { const char* _gb = (const char*)(gbase) + (size_t)_i * (voff##_q); asm volatile("" : "+s"(_gb)); \
;         __builtin_amdgcn_global_load_lds((const unsigned*)(_gb + (voff)), (LAS unsigned*)(lds + (bufoff) + ldsw + _i * 8192), 16, 0, 0); } } while (0)
; #define PG8_WAIT_V(n) asm volatile("s_waitcnt vmcnt(" #n ")" ::: "memory")
; #define PG8_WAIT_L(n) asm volatile("s_waitcnt lgkmcnt(" #n ")" ::: "memory")
; template <class Epi, class Sched>
; __device__ __forceinline__ void gemm_phase(int wv, LAS unsigned char* lds, const Gemm g, const Sched& S, const Epi& E) { LIDS
;     ...
;         for (int t = 0; t < nt; t += 2) {
;             const bool last = (t == nt - 2);
;             const char* a1 = cA + (size_t)(t + 1) * kstepA;
;             const char* a2 = last ? nA : cA + (size_t)(t + 2) * kstepA; const char* b2 = last ? nB : cB + (size_t)(t + 2) * kstepB;
;             const char* a3 = a2 + kstepA; const char* b3 = b2 + kstepB;
;             asm volatile("" : "+s"(a1), "+s"(a2), "+s"(b2), "+s"(a3), "+s"(b3));
;             PG8_LDB(B0, 0, 0); PG8_SCHED; PG8_LDA(At, 0, 0); PG8_STAGE(PG8_SA(1, 1), a1 + hstepA, voffA);
;             PG8_WAIT_L(8); PG8_BAR; PG8_WAIT_L(0); PG8_MMA(0, 0, At, B0); PG8_BAR; PG8_SCHED;
;             PG8_LDB(B1, 0, 1); PG8_STAGE(PG8_SB(0, 0), b2, voffB);
;             PG8_BAR; PG8_WAIT_L(0); PG8_MMA(0, 1, At, B1); PG8_BAR;
;             PG8_LDA(At, 0, 1); PG8_STAGE(PG8_SA(0, 0), a2, voffA);
;             PG8_BAR; PG8_WAIT_L(0); PG8_MMA(1, 0, At, B0); PG8_BAR; PG8_SCHED;
;             PG8_STAGE(PG8_SB(0, 1), b2 + hstepB, voffB);
;             PG8_WAIT_V(6); PG8_BAR; PG8_MMA(1, 1, At, B1); PG8_BAR;
;             PG8_LDB(B0, 1, 0); PG8_SCHED; PG8_LDA(At, 1, 0); PG8_STAGE(PG8_SA(0, 1), a2 + hstepA, voffA);
;             PG8_WAIT_L(8); PG8_BAR; PG8_WAIT_L(0); PG8_MMA(0, 0, At, B0); PG8_BAR; PG8_SCHED;
;             PG8_LDB(B1, 1, 1); PG8_STAGE(PG8_SB(1, 0), b3, voffB);
;             PG8_BAR; PG8_WAIT_L(0); PG8_MMA(0, 1, At, B1); PG8_BAR;
;             PG8_LDA(At, 1, 1); PG8_STAGE(PG8_SA(1, 0), a3, voffA);
;             PG8_BAR; PG8_WAIT_L(0); PG8_MMA(1, 0, At, B0); PG8_BAR; PG8_SCHED;
;             PG8_STAGE(PG8_SB(1, 1), b3 + hstepB, voffB);
;             PG8_WAIT_V(6); PG8_BAR; PG8_MMA(1, 1, At, B1); PG8_BAR;
.LBB0_123:
	s_add_u32 s20, s68, 0x80
	s_addc_u32 s21, s69, 0
	s_add_u32 s68, s68, 0x100
	s_addc_u32 s69, s69, 0
	s_cmp_eq_u32 s18, 4
	s_cselect_b32 s84, s9, s68
	s_cselect_b32 s85, s7, s69
	s_cselect_b32 s89, s11, s17
	s_cselect_b32 s88, s13, s16
	s_add_u32 s86, s84, 0x80
	s_addc_u32 s87, s85, 0
	s_add_u32 s78, s88, 0x80
	s_addc_u32 s79, s89, 0
	s_add_i32 s19, 16, 0x10000
	v_add_u32_e32 v144, s19, v149
	ds_read_b128 v[128:131], v144
	ds_read_b128 v[132:135], v144 offset:1024
	ds_read_b128 v[140:143], v144 offset:2048
	ds_read_b128 v[144:147], v144 offset:3072
	s_add_u32 s22, s20, 0x100000
	s_addc_u32 s23, s21, 0
	s_add_i32 m0, s91, 0xc000
	s_add_u32 s20, s20, 0x180000
	ds_read_b128 v[152:155], v150
	ds_read_b128 v[156:159], v150 offset:1024
	ds_read_b128 v[160:163], v150 offset:2048
	ds_read_b128 v[164:167], v150 offset:3072
	ds_read_b128 v[168:171], v150 offset:4096
	ds_read_b128 v[172:175], v150 offset:5120
	ds_read_b128 v[194:197], v150 offset:6144
	ds_read_b128 v[198:201], v150 offset:7168
	s_addc_u32 s21, s21, 0
	v_lshl_add_u64 v[178:179], s[22:23], 0, v[136:137]
	global_load_lds_dwordx4 v[178:179], off
	s_add_i32 m0, s91, 0xe000
	v_lshl_add_u64 v[178:179], s[20:21], 0, v[136:137]
	global_load_lds_dwordx4 v[178:179], off
	s_waitcnt lgkmcnt(8)
	s_barrier
	s_waitcnt lgkmcnt(0)
	s_setprio 1
	s_waitcnt lgkmcnt(0)
	v_mfma_f32_16x16x32_bf16 v[124:127], v[128:131], v[152:155], v[124:127]
	v_mfma_f32_16x16x32_bf16 v[120:123], v[140:143], v[152:155], v[120:123]
	v_mfma_f32_16x16x32_bf16 v[108:111], v[128:131], v[160:163], v[108:111]
	v_mfma_f32_16x16x32_bf16 v[104:107], v[140:143], v[160:163], v[104:107]
	v_mfma_f32_16x16x32_bf16 v[92:95], v[128:131], v[168:171], v[92:95]
	v_mfma_f32_16x16x32_bf16 v[88:91], v[140:143], v[168:171], v[88:91]
	v_mfma_f32_16x16x32_bf16 v[76:79], v[128:131], v[194:197], v[76:79]
	v_mfma_f32_16x16x32_bf16 v[72:75], v[140:143], v[194:197], v[72:75]
	v_mfma_f32_16x16x32_bf16 v[124:127], v[132:135], v[156:159], v[124:127]
	v_mfma_f32_16x16x32_bf16 v[120:123], v[144:147], v[156:159], v[120:123]
	v_mfma_f32_16x16x32_bf16 v[108:111], v[132:135], v[164:167], v[108:111]
	v_mfma_f32_16x16x32_bf16 v[104:107], v[144:147], v[164:167], v[104:107]
	v_mfma_f32_16x16x32_bf16 v[92:95], v[132:135], v[172:175], v[92:95]
	v_mfma_f32_16x16x32_bf16 v[88:91], v[144:147], v[172:175], v[88:91]
	v_mfma_f32_16x16x32_bf16 v[76:79], v[132:135], v[198:201], v[76:79]
	v_mfma_f32_16x16x32_bf16 v[72:75], v[144:147], v[198:201], v[72:75]
	s_setprio 0
	s_barrier
	s_add_i32 s22, 16, 0x14000
	v_add_u32_e32 v151, s22, v149
	s_mov_b64 s[20:21], s[88:89]
	ds_read_b128 v[202:205], v151
	ds_read_b128 v[206:209], v151 offset:1024
	ds_read_b128 v[218:221], v151 offset:2048
	ds_read_b128 v[222:225], v151 offset:3072
	s_add_i32 s19, s19, s90
	v_lshl_add_u64 v[178:179], s[20:21], 0, v[138:139]
	s_add_u32 s20, s88, 0x10000
	s_mov_b32 m0, s19
	s_addc_u32 s21, s89, 0
	global_load_lds_dwordx4 v[178:179], off
	s_add_i32 m0, s19, 0x2000
	v_lshl_add_u64 v[178:179], s[20:21], 0, v[138:139]
	global_load_lds_dwordx4 v[178:179], off
	s_barrier
	s_waitcnt lgkmcnt(0)
	s_setprio 1
	s_waitcnt lgkmcnt(0)
	v_mfma_f32_16x16x32_bf16 v[116:119], v[202:205], v[152:155], v[116:119]
	v_mfma_f32_16x16x32_bf16 v[112:115], v[218:221], v[152:155], v[112:115]
	v_mfma_f32_16x16x32_bf16 v[100:103], v[202:205], v[160:163], v[100:103]
	v_mfma_f32_16x16x32_bf16 v[96:99], v[218:221], v[160:163], v[96:99]
	v_mfma_f32_16x16x32_bf16 v[84:87], v[202:205], v[168:171], v[84:87]
	v_mfma_f32_16x16x32_bf16 v[80:83], v[218:221], v[168:171], v[80:83]
	v_mfma_f32_16x16x32_bf16 v[68:71], v[202:205], v[194:197], v[68:71]
	v_mfma_f32_16x16x32_bf16 v[64:67], v[218:221], v[194:197], v[64:67]
	v_mfma_f32_16x16x32_bf16 v[116:119], v[206:209], v[156:159], v[116:119]
	v_mfma_f32_16x16x32_bf16 v[112:115], v[222:225], v[156:159], v[112:115]
	v_mfma_f32_16x16x32_bf16 v[100:103], v[206:209], v[164:167], v[100:103]
	v_mfma_f32_16x16x32_bf16 v[96:99], v[222:225], v[164:167], v[96:99]
	v_mfma_f32_16x16x32_bf16 v[84:87], v[206:209], v[172:175], v[84:87]
	v_mfma_f32_16x16x32_bf16 v[80:83], v[222:225], v[172:175], v[80:83]
	v_mfma_f32_16x16x32_bf16 v[68:71], v[206:209], v[198:201], v[68:71]
	v_mfma_f32_16x16x32_bf16 v[64:67], v[222:225], v[198:201], v[64:67]
	s_setprio 0
	s_mov_b64 s[20:21], s[84:85]
	s_barrier
	ds_read_b128 v[152:155], v150 offset:16384
	ds_read_b128 v[156:159], v150 offset:17408
	ds_read_b128 v[160:163], v150 offset:18432
	ds_read_b128 v[164:167], v150 offset:19456
	ds_read_b128 v[168:171], v150 offset:20480
	ds_read_b128 v[172:175], v150 offset:21504
	ds_read_b128 v[194:197], v150 offset:22528
	ds_read_b128 v[198:201], v150 offset:23552
	s_mov_b32 m0, s91
	v_lshl_add_u64 v[178:179], s[20:21], 0, v[136:137]
	s_add_u32 s20, s84, 0x80000
	s_addc_u32 s21, s85, 0
	global_load_lds_dwordx4 v[178:179], off
	s_mov_b32 m0, s94
	v_lshl_add_u64 v[178:179], s[20:21], 0, v[136:137]
	global_load_lds_dwordx4 v[178:179], off
	s_barrier
	s_waitcnt lgkmcnt(0)
	s_setprio 1
	s_waitcnt lgkmcnt(0)
	v_mfma_f32_16x16x32_bf16 v[60:63], v[128:131], v[152:155], v[60:63]
	v_mfma_f32_16x16x32_bf16 v[56:59], v[140:143], v[152:155], v[56:59]
	v_mfma_f32_16x16x32_bf16 v[44:47], v[128:131], v[160:163], v[44:47]
	v_mfma_f32_16x16x32_bf16 v[40:43], v[140:143], v[160:163], v[40:43]
	v_mfma_f32_16x16x32_bf16 v[28:31], v[128:131], v[168:171], v[28:31]
	v_mfma_f32_16x16x32_bf16 v[24:27], v[140:143], v[168:171], v[24:27]
	v_mfma_f32_16x16x32_bf16 v[12:15], v[128:131], v[194:197], v[12:15]
	v_mfma_f32_16x16x32_bf16 v[8:11], v[140:143], v[194:197], v[8:11]
	v_mfma_f32_16x16x32_bf16 v[60:63], v[132:135], v[156:159], v[60:63]
	v_mfma_f32_16x16x32_bf16 v[56:59], v[144:147], v[156:159], v[56:59]
	v_mfma_f32_16x16x32_bf16 v[44:47], v[132:135], v[164:167], v[44:47]
	v_mfma_f32_16x16x32_bf16 v[40:43], v[144:147], v[164:167], v[40:43]
	v_mfma_f32_16x16x32_bf16 v[28:31], v[132:135], v[172:175], v[28:31]
	v_mfma_f32_16x16x32_bf16 v[24:27], v[144:147], v[172:175], v[24:27]
	v_mfma_f32_16x16x32_bf16 v[12:15], v[132:135], v[198:201], v[12:15]
	v_mfma_f32_16x16x32_bf16 v[8:11], v[144:147], v[198:201], v[8:11]
	s_setprio 0
	s_barrier
; #define PG8_STAGE(bufoff, gbase, voff) do { _Pragma("unroll") for (int _i = 0; _i < 2; ++_i) { const char* _gb = (const char*)(gbase) + (size_t)_i * (voff##_q); asm volatile("" : "+s"(_gb)); \
;         __builtin_amdgcn_global_load_lds((const unsigned*)(_gb + (voff)), (LAS unsigned*)(lds + (bufoff) + ldsw + _i * 8192), 16, 0, 0); } } while (0)
; #define PG8_LDA(dst, b, h) do { _Pragma("unroll") for (int m = 0; m < 4; ++m) _Pragma("unroll") for (int k = 0; k < 2; ++k) dst[m][k] = *(const LAS bf16x8*)(lds + PG8_SA(b, h) + aoff + m * 2048 + k * 1024); } while (0)
; #define PG8_LDB(dst, b, h) do { _Pragma("unroll") for (int n = 0; n < 2; ++n) _Pragma("unroll") for (int k = 0; k < 2; ++k) dst[n][k] = *(const LAS bf16x8*)(lds + PG8_SB(b, h) + boff + n * 2048 + k * 1024); } while (0)
; #define PG8_MMA(ai, bj, At, Bt) do { __builtin_amdgcn_s_setprio(1); _Pragma("unroll") for (int m = 0; m < 4; ++m) _Pragma("unroll") for (int n = 0; n < 2; ++n) _Pragma("unroll") for (int k = 0; k < 2; ++k) \
;         acc[ai][bj][m][n] = __builtin_amdgcn_mfma_f32_16x16x32_bf16(Bt[n][k], At[m][k], acc[ai][bj][m][n], 0, 0, 0); __builtin_amdgcn_s_setprio(0); } while (0)
; template <class Epi, class Sched>
; __device__ __forceinline__ void gemm_phase(int wv, LAS unsigned char* lds, const Gemm g, const Sched& S, const Epi& E) { LIDS
;     ...
;             PG8_LDB(B1, 0, 1); PG8_STAGE(PG8_SB(0, 0), b2, voffB);
;             PG8_BAR; PG8_WAIT_L(0); PG8_MMA(0, 1, At, B1); PG8_BAR;
;             PG8_LDA(At, 0, 1); PG8_STAGE(PG8_SA(0, 0), a2, voffA);
;             PG8_BAR; PG8_WAIT_L(0); PG8_MMA(1, 0, At, B0); PG8_BAR; PG8_SCHED;
;             PG8_STAGE(PG8_SB(0, 1), b2 + hstepB, voffB);
;             PG8_WAIT_V(6); PG8_BAR; PG8_MMA(1, 1, At, B1); PG8_BAR;
;             PG8_LDB(B0, 1, 0); PG8_SCHED; PG8_LDA(At, 1, 0); PG8_STAGE(PG8_SA(0, 1), a2 + hstepA, voffA);
;             PG8_WAIT_L(8); PG8_BAR; PG8_WAIT_L(0); PG8_MMA(0, 0, At, B0); PG8_BAR; PG8_SCHED;
;             PG8_LDB(B1, 1, 1); PG8_STAGE(PG8_SB(1, 0), b3, voffB);
;             PG8_BAR; PG8_WAIT_L(0); PG8_MMA(0, 1, At, B1); PG8_BAR;
;             PG8_LDA(At, 1, 1); PG8_STAGE(PG8_SA(1, 0), a3, voffA);
;             PG8_BAR; PG8_WAIT_L(0); PG8_MMA(1, 0, At, B0); PG8_BAR; PG8_SCHED;
;             PG8_STAGE(PG8_SB(1, 1), b3 + hstepB, voffB);
;             PG8_WAIT_V(6); PG8_BAR; PG8_MMA(1, 1, At, B1); PG8_BAR;
	s_add_u32 s20, s88, 0x20000
	s_addc_u32 s21, s89, 0
	s_add_i32 s19, s22, s90
	v_lshl_add_u64 v[128:129], s[20:21], 0, v[138:139]
	s_add_u32 s20, s88, 0x30000
	s_mov_b32 m0, s19
	s_addc_u32 s21, s89, 0
	global_load_lds_dwordx4 v[128:129], off
	s_add_i32 m0, s19, 0x2000
	v_lshl_add_u64 v[128:129], s[20:21], 0, v[138:139]
	global_load_lds_dwordx4 v[128:129], off
	s_waitcnt vmcnt(6)
	s_barrier
	s_setprio 1
	v_mfma_f32_16x16x32_bf16 v[52:55], v[202:205], v[152:155], v[52:55]
	v_mfma_f32_16x16x32_bf16 v[48:51], v[218:221], v[152:155], v[48:51]
	v_mfma_f32_16x16x32_bf16 v[36:39], v[202:205], v[160:163], v[36:39]
	v_mfma_f32_16x16x32_bf16 v[32:35], v[218:221], v[160:163], v[32:35]
	v_mfma_f32_16x16x32_bf16 v[20:23], v[202:205], v[168:171], v[20:23]
	v_mfma_f32_16x16x32_bf16 v[16:19], v[218:221], v[168:171], v[16:19]
	v_mfma_f32_16x16x32_bf16 v[4:7], v[202:205], v[194:197], v[4:7]
	v_mfma_f32_16x16x32_bf16 v[0:3], v[218:221], v[194:197], v[0:3]
	v_mfma_f32_16x16x32_bf16 v[52:55], v[206:209], v[156:159], v[52:55]
	v_mfma_f32_16x16x32_bf16 v[48:51], v[222:225], v[156:159], v[48:51]
	v_mfma_f32_16x16x32_bf16 v[36:39], v[206:209], v[164:167], v[36:39]
	v_mfma_f32_16x16x32_bf16 v[32:35], v[222:225], v[164:167], v[32:35]
	v_mfma_f32_16x16x32_bf16 v[20:23], v[206:209], v[172:175], v[20:23]
	v_mfma_f32_16x16x32_bf16 v[16:19], v[222:225], v[172:175], v[16:19]
	v_mfma_f32_16x16x32_bf16 v[4:7], v[206:209], v[198:201], v[4:7]
	v_mfma_f32_16x16x32_bf16 v[0:3], v[222:225], v[198:201], v[0:3]
	s_setprio 0
	s_add_i32 s19, 16, 0x18000
	v_add_u32_e32 v144, s19, v149
	s_barrier
	ds_read_b128 v[128:131], v144
	ds_read_b128 v[132:135], v144 offset:1024
	ds_read_b128 v[140:143], v144 offset:2048
	ds_read_b128 v[144:147], v144 offset:3072
	s_add_u32 s20, s84, 0x100000
	s_addc_u32 s21, s85, 0
	ds_read_b128 v[152:155], v150 offset:32768
	ds_read_b128 v[156:159], v150 offset:33792
	ds_read_b128 v[160:163], v150 offset:34816
	ds_read_b128 v[164:167], v150 offset:35840
	ds_read_b128 v[168:171], v150 offset:36864
	ds_read_b128 v[172:175], v150 offset:37888
	ds_read_b128 v[194:197], v150 offset:38912
	ds_read_b128 v[198:201], v150 offset:39936
	s_mov_b32 m0, s95
	v_lshl_add_u64 v[178:179], s[20:21], 0, v[136:137]
	s_add_u32 s20, s84, 0x180000
	s_addc_u32 s21, s85, 0
	global_load_lds_dwordx4 v[178:179], off
	s_mov_b32 m0, s59
	v_lshl_add_u64 v[178:179], s[20:21], 0, v[136:137]
	global_load_lds_dwordx4 v[178:179], off
	s_waitcnt lgkmcnt(8)
	s_barrier
	s_waitcnt lgkmcnt(0)
	s_setprio 1
	s_waitcnt lgkmcnt(0)
	v_mfma_f32_16x16x32_bf16 v[124:127], v[128:131], v[152:155], v[124:127]
	v_mfma_f32_16x16x32_bf16 v[120:123], v[140:143], v[152:155], v[120:123]
	v_mfma_f32_16x16x32_bf16 v[108:111], v[128:131], v[160:163], v[108:111]
	v_mfma_f32_16x16x32_bf16 v[104:107], v[140:143], v[160:163], v[104:107]
	v_mfma_f32_16x16x32_bf16 v[92:95], v[128:131], v[168:171], v[92:95]
	v_mfma_f32_16x16x32_bf16 v[88:91], v[140:143], v[168:171], v[88:91]
	v_mfma_f32_16x16x32_bf16 v[76:79], v[128:131], v[194:197], v[76:79]
	v_mfma_f32_16x16x32_bf16 v[72:75], v[140:143], v[194:197], v[72:75]
	v_mfma_f32_16x16x32_bf16 v[124:127], v[132:135], v[156:159], v[124:127]
	v_mfma_f32_16x16x32_bf16 v[120:123], v[144:147], v[156:159], v[120:123]
	v_mfma_f32_16x16x32_bf16 v[108:111], v[132:135], v[164:167], v[108:111]
	v_mfma_f32_16x16x32_bf16 v[104:107], v[144:147], v[164:167], v[104:107]
	v_mfma_f32_16x16x32_bf16 v[92:95], v[132:135], v[172:175], v[92:95]
	v_mfma_f32_16x16x32_bf16 v[88:91], v[144:147], v[172:175], v[88:91]
	v_mfma_f32_16x16x32_bf16 v[76:79], v[132:135], v[198:201], v[76:79]
	v_mfma_f32_16x16x32_bf16 v[72:75], v[144:147], v[198:201], v[72:75]
	s_setprio 0
	s_barrier
	s_add_i32 s22, 16, 0x1c000
	v_add_u32_e32 v151, s22, v149
	s_mov_b64 s[20:21], s[78:79]
	ds_read_b128 v[202:205], v151
	ds_read_b128 v[206:209], v151 offset:1024
	ds_read_b128 v[218:221], v151 offset:2048
	ds_read_b128 v[222:225], v151 offset:3072
	s_add_i32 s19, s19, s90
	v_lshl_add_u64 v[178:179], s[20:21], 0, v[138:139]
	s_add_u32 s20, s78, 0x10000
	s_mov_b32 m0, s19
	s_addc_u32 s21, s79, 0
	global_load_lds_dwordx4 v[178:179], off
	s_add_i32 m0, s19, 0x2000
	v_lshl_add_u64 v[178:179], s[20:21], 0, v[138:139]
	global_load_lds_dwordx4 v[178:179], off
	s_barrier
	s_waitcnt lgkmcnt(0)
	s_setprio 1
	s_waitcnt lgkmcnt(0)
	v_mfma_f32_16x16x32_bf16 v[116:119], v[202:205], v[152:155], v[116:119]
	v_mfma_f32_16x16x32_bf16 v[112:115], v[218:221], v[152:155], v[112:115]
	v_mfma_f32_16x16x32_bf16 v[100:103], v[202:205], v[160:163], v[100:103]
	v_mfma_f32_16x16x32_bf16 v[96:99], v[218:221], v[160:163], v[96:99]
	v_mfma_f32_16x16x32_bf16 v[84:87], v[202:205], v[168:171], v[84:87]
	v_mfma_f32_16x16x32_bf16 v[80:83], v[218:221], v[168:171], v[80:83]
	v_mfma_f32_16x16x32_bf16 v[68:71], v[202:205], v[194:197], v[68:71]
	v_mfma_f32_16x16x32_bf16 v[64:67], v[218:221], v[194:197], v[64:67]
	v_mfma_f32_16x16x32_bf16 v[116:119], v[206:209], v[156:159], v[116:119]
	v_mfma_f32_16x16x32_bf16 v[112:115], v[222:225], v[156:159], v[112:115]
	v_mfma_f32_16x16x32_bf16 v[100:103], v[206:209], v[164:167], v[100:103]
	v_mfma_f32_16x16x32_bf16 v[96:99], v[222:225], v[164:167], v[96:99]
	v_mfma_f32_16x16x32_bf16 v[84:87], v[206:209], v[172:175], v[84:87]
	v_mfma_f32_16x16x32_bf16 v[80:83], v[222:225], v[172:175], v[80:83]
	v_mfma_f32_16x16x32_bf16 v[68:71], v[206:209], v[198:201], v[68:71]
	v_mfma_f32_16x16x32_bf16 v[64:67], v[222:225], v[198:201], v[64:67]
	s_setprio 0
	s_mov_b64 s[20:21], s[86:87]
	s_barrier
; #define PG8_STAGE(bufoff, gbase, voff) do { _Pragma("unroll") for (int _i = 0; _i < 2; ++_i) { const char* _gb = (const char*)(gbase) + (size_t)_i * (voff##_q); asm volatile("" : "+s"(_gb)); \
;         __builtin_amdgcn_global_load_lds((const unsigned*)(_gb + (voff)), (LAS unsigned*)(lds + (bufoff) + ldsw + _i * 8192), 16, 0, 0); } } while (0)
; #define PG8_LDA(dst, b, h) do { _Pragma("unroll") for (int m = 0; m < 4; ++m) _Pragma("unroll") for (int k = 0; k < 2; ++k) dst[m][k] = *(const LAS bf16x8*)(lds + PG8_SA(b, h) + aoff + m * 2048 + k * 1024); } while (0)
; #define PG8_LDB(dst, b, h) do { _Pragma("unroll") for (int n = 0; n < 2; ++n) _Pragma("unroll") for (int k = 0; k < 2; ++k) dst[n][k] = *(const LAS bf16x8*)(lds + PG8_SB(b, h) + boff + n * 2048 + k * 1024); } while (0)
; #define PG8_WAIT_V(n) asm volatile("s_waitcnt vmcnt(" #n ")" ::: "memory")
; #define PG8_BAR __builtin_amdgcn_s_barrier()
; template <class Epi, class Sched>
; __device__ __forceinline__ void gemm_phase(int wv, LAS unsigned char* lds, const Gemm g, const Sched& S, const Epi& E) { LIDS
;     ...
;             PG8_LDB(B0, 1, 0); PG8_SCHED; PG8_LDA(At, 1, 0); PG8_STAGE(PG8_SA(0, 1), a2 + hstepA, voffA);
;             PG8_WAIT_L(8); PG8_BAR; PG8_WAIT_L(0); PG8_MMA(0, 0, At, B0); PG8_BAR; PG8_SCHED;
;             PG8_LDB(B1, 1, 1); PG8_STAGE(PG8_SB(1, 0), b3, voffB);
;             PG8_BAR; PG8_WAIT_L(0); PG8_MMA(0, 1, At, B1); PG8_BAR;
;             PG8_LDA(At, 1, 1); PG8_STAGE(PG8_SA(1, 0), a3, voffA);
;             PG8_BAR; PG8_WAIT_L(0); PG8_MMA(1, 0, At, B0); PG8_BAR; PG8_SCHED;
;             PG8_STAGE(PG8_SB(1, 1), b3 + hstepB, voffB);
;             PG8_WAIT_V(6); PG8_BAR; PG8_MMA(1, 1, At, B1); PG8_BAR;
;     __device__ __forceinline__ void operator()(const AccT& acc, const Unit& u, int wr, int wc, int fr, int fq) const {
;         EPI_ROWS(u)
; #pragma unroll
;         for (int ai = 0; ai < 2; ++ai)
; #pragma unroll
;             for (int m = 0; m < 4; ++m) {
;                 const int row = row0 + ai * HALF + m * 16;
;                 const f32x4 pa = *(const f32x4*)(ssp + (size_t)row * 16), pb = *(const f32x4*)(ssp + (size_t)row * 16 + 4);
;                 const float ssr = ((pa[0] + pa[1]) + (pa[2] + pa[3])) + ((pb[0] + pb[1]) + (pb[2] + pb[3]));
;                 const float sc = rsqrtf(ssr * (1.0f / 512.0f) + EPS) * (1.4426950408889634f * 0.07216878364870322f);
	ds_read_b128 v[152:155], v150 offset:49152
	ds_read_b128 v[156:159], v150 offset:50176
	ds_read_b128 v[160:163], v150 offset:51200
	ds_read_b128 v[164:167], v150 offset:52224
	ds_read_b128 v[168:171], v150 offset:53248
	ds_read_b128 v[172:175], v150 offset:54272
	ds_read_b128 v[194:197], v150 offset:55296
	ds_read_b128 v[198:201], v150 offset:56320
	s_mov_b32 m0, s55
	v_lshl_add_u64 v[178:179], s[20:21], 0, v[136:137]
	s_add_u32 s20, s86, 0x80000
	s_addc_u32 s21, s87, 0
	global_load_lds_dwordx4 v[178:179], off
	s_mov_b32 m0, s57
	v_lshl_add_u64 v[178:179], s[20:21], 0, v[136:137]
	global_load_lds_dwordx4 v[178:179], off
	s_barrier
	s_waitcnt lgkmcnt(0)
	s_setprio 1
	s_waitcnt lgkmcnt(0)
	v_mfma_f32_16x16x32_bf16 v[60:63], v[128:131], v[152:155], v[60:63]
	v_mfma_f32_16x16x32_bf16 v[56:59], v[140:143], v[152:155], v[56:59]
	v_mfma_f32_16x16x32_bf16 v[44:47], v[128:131], v[160:163], v[44:47]
	v_mfma_f32_16x16x32_bf16 v[40:43], v[140:143], v[160:163], v[40:43]
	v_mfma_f32_16x16x32_bf16 v[28:31], v[128:131], v[168:171], v[28:31]
	v_mfma_f32_16x16x32_bf16 v[24:27], v[140:143], v[168:171], v[24:27]
	v_mfma_f32_16x16x32_bf16 v[12:15], v[128:131], v[194:197], v[12:15]
	v_mfma_f32_16x16x32_bf16 v[8:11], v[140:143], v[194:197], v[8:11]
	v_mfma_f32_16x16x32_bf16 v[60:63], v[132:135], v[156:159], v[60:63]
	v_mfma_f32_16x16x32_bf16 v[56:59], v[144:147], v[156:159], v[56:59]
	v_mfma_f32_16x16x32_bf16 v[44:47], v[132:135], v[164:167], v[44:47]
	v_mfma_f32_16x16x32_bf16 v[40:43], v[144:147], v[164:167], v[40:43]
	v_mfma_f32_16x16x32_bf16 v[28:31], v[132:135], v[172:175], v[28:31]
	v_mfma_f32_16x16x32_bf16 v[24:27], v[144:147], v[172:175], v[24:27]
	v_mfma_f32_16x16x32_bf16 v[12:15], v[132:135], v[198:201], v[12:15]
	v_mfma_f32_16x16x32_bf16 v[8:11], v[144:147], v[198:201], v[8:11]
	s_setprio 0
	s_barrier
	s_add_u32 s20, s78, 0x20000
	s_addc_u32 s21, s79, 0
	s_add_i32 s19, s22, s90
	v_lshl_add_u64 v[128:129], s[20:21], 0, v[138:139]
	s_add_u32 s20, s78, 0x30000
	s_mov_b32 m0, s19
	s_addc_u32 s21, s79, 0
	global_load_lds_dwordx4 v[128:129], off
	s_add_i32 m0, s19, 0x2000
	v_lshl_add_u64 v[128:129], s[20:21], 0, v[138:139]
	global_load_lds_dwordx4 v[128:129], off
	s_waitcnt vmcnt(6)
	s_barrier
	s_setprio 1
	v_mfma_f32_16x16x32_bf16 v[52:55], v[202:205], v[152:155], v[52:55]
	v_mfma_f32_16x16x32_bf16 v[48:51], v[218:221], v[152:155], v[48:51]
	v_mfma_f32_16x16x32_bf16 v[36:39], v[202:205], v[160:163], v[36:39]
	v_mfma_f32_16x16x32_bf16 v[32:35], v[218:221], v[160:163], v[32:35]
	v_mfma_f32_16x16x32_bf16 v[20:23], v[202:205], v[168:171], v[20:23]
	v_mfma_f32_16x16x32_bf16 v[16:19], v[218:221], v[168:171], v[16:19]
	v_mfma_f32_16x16x32_bf16 v[4:7], v[202:205], v[194:197], v[4:7]
	v_mfma_f32_16x16x32_bf16 v[0:3], v[218:221], v[194:197], v[0:3]
	v_mfma_f32_16x16x32_bf16 v[52:55], v[206:209], v[156:159], v[52:55]
	v_mfma_f32_16x16x32_bf16 v[48:51], v[222:225], v[156:159], v[48:51]
	v_mfma_f32_16x16x32_bf16 v[36:39], v[206:209], v[164:167], v[36:39]
	v_mfma_f32_16x16x32_bf16 v[32:35], v[222:225], v[164:167], v[32:35]
	v_mfma_f32_16x16x32_bf16 v[20:23], v[206:209], v[172:175], v[20:23]
	v_mfma_f32_16x16x32_bf16 v[16:19], v[222:225], v[172:175], v[16:19]
	v_mfma_f32_16x16x32_bf16 v[4:7], v[206:209], v[198:201], v[4:7]
	v_mfma_f32_16x16x32_bf16 v[0:3], v[222:225], v[198:201], v[0:3]
	s_setprio 0
	s_add_i32 s18, s18, 2
	s_add_u32 s16, s16, 0x100
	s_addc_u32 s17, s17, 0
	s_cmp_gt_u32 s18, 5
	s_barrier
	s_cbranch_scc0 .LBB0_123
	s_lshl_b32 s7, s8, 8
	s_add_i32 s7, s7, s52
	v_mbcnt_lo_u32_b32 v140, -1, 0
	v_mbcnt_hi_u32_b32 v140, -1, v140
	v_readlane_b32 s8, v253, 12
	v_and_or_b32 v142, v140, 15, s7
	v_ashrrev_i32_e32 v143, 31, v142
	v_lshlrev_b64 v[128:129], 6, v[142:143]
	v_readlane_b32 s9, v253, 13
	s_lshl_b32 s6, s6, 8
	v_ashrrev_i32_e32 v140, 1, v140
	v_lshl_add_u64 v[132:133], s[8:9], 0, v[128:129]
	global_load_dwordx4 v[128:131], v[132:133], off offset:16
	s_nop 0
	global_load_dwordx4 v[132:135], v[132:133], off
	s_or_b32 s6, s6, s53
	v_and_b32_e32 v140, -8, v140
	v_add_u32_e32 v140, s6, v140
	v_mul_hi_i32 v141, v140, s33
	v_lshlrev_b64 v[144:145], 5, v[142:143]
	v_lshrrev_b32_e32 v143, 31, v141
	v_lshrrev_b32_e32 v141, 5, v141
	v_add_u32_e32 v141, v141, v143
	s_movk_i32 s6, 0xc0
	v_mul_lo_u32 v141, v141, s6
	v_sub_u32_e32 v141, v140, v141
	s_movk_i32 s6, 0x7f
	v_cmp_lt_i32_e32 vcc, s6, v141
	v_readlane_b32 s6, v254, 48
	v_lshlrev_b64 v[144:145], 2, v[144:145]
	v_readlane_b32 s7, v254, 49
	v_add_u32_e32 v141, 0xffffff80, v141
	v_lshrrev_b32_e32 v176, 1, v141
	v_lshl_add_u64 v[146:147], s[6:7], 0, v[144:145]
	v_readlane_b32 s6, v253, 14
	v_readlane_b32 s7, v253, 15
	s_nop 1
	v_lshl_add_u64 v[144:145], s[6:7], 0, v[144:145]
	v_readlane_b32 s8, v253, 12
	v_readlane_b32 s9, v253, 13
	v_lshlrev_b64 v[188:189], 6, v[142:143]
	s_mov_b32 s6, 0x2000
	s_mov_b32 s7, 0
	v_lshl_add_u64 v[188:189], s[8:9], 0, v[188:189]
	v_lshl_add_u64 v[190:191], v[188:189], 0, s[6:7]
	global_load_dwordx4 v[194:197], v[188:189], off offset:1040
	global_load_dwordx4 v[198:201], v[188:189], off offset:1024
	global_load_dwordx4 v[202:205], v[188:189], off offset:2064
	global_load_dwordx4 v[206:209], v[188:189], off offset:2048
	global_load_dwordx4 v[218:221], v[188:189], off offset:3088
	global_load_dwordx4 v[222:225], v[188:189], off offset:3072
	global_load_dwordx4 v[226:229], v[190:191], off offset:16
	global_load_dwordx4 v[230:233], v[190:191], off
	global_load_dwordx4 v[234:237], v[190:191], off offset:1040
	global_load_dwordx4 v[238:241], v[190:191], off offset:1024
	global_load_dwordx4 v[242:245], v[190:191], off offset:2064
	global_load_dwordx4 v[246:249], v[190:191], off offset:2048
	global_load_dwordx4 v[168:171], v[190:191], off offset:3088
	global_load_dwordx4 v[172:175], v[190:191], off offset:3072
	s_waitcnt vmcnt(0)
;     __device__ __forceinline__ void operator()(const AccT& acc, const Unit& u, int wr, int wc, int fr, int fq) const {
;     ...
;                 const int row = row0 + ai * HALF + m * 16;
;                 const f32x4 pa = *(const f32x4*)(ssp + (size_t)row * 16), pb = *(const f32x4*)(ssp + (size_t)row * 16 + 4);
;                 const float ssr = ((pa[0] + pa[1]) + (pa[2] + pa[3])) + ((pb[0] + pb[1]) + (pb[2] + pb[3]));
;                 const float sc = rsqrtf(ssr * (1.0f / 512.0f) + EPS) * (1.4426950408889634f * 0.07216878364870322f);
; #pragma unroll
;                 for (int bj = 0; bj < 2; ++bj) {
;                     const int col = colbase + bj * HALF; f32x4 v0 = acc[ai][bj][m][0], v1 = acc[ai][bj][m][1];
;                     const int d = col % 192;
;                     if (d >= 128) { const int i0 = (d - 128) >> 1;
;                         const f32x4 c4 = *(const f32x4*)(cosT + (size_t)row * 32 + i0), s4 = *(const f32x4*)(sinT + (size_t)row * 32 + i0);
;                         f32x4 o0, o1;
;                         o0[0] = v0[0] * c4[0] - v0[1] * s4[0]; o0[1] = v0[1] * c4[0] + v0[0] * s4[0];
;                         o0[2] = v0[2] * c4[1] - v0[3] * s4[1]; o0[3] = v0[3] * c4[1] + v0[2] * s4[1];
;                         o1[0] = v1[0] * c4[2] - v1[1] * s4[2]; o1[1] = v1[1] * c4[2] + v1[0] * s4[2];
;                         o1[2] = v1[2] * c4[3] - v1[3] * s4[3]; o1[3] = v1[3] * c4[3] + v1[2] * s4[3];
;                         v0 = o0; v1 = o1; }
	v_add_f32_e32 v198, v198, v199
	v_add_f32_e32 v200, v200, v201
	v_add_f32_e32 v194, v194, v195
	v_add_f32_e32 v196, v196, v197
	v_add_f32_e32 v206, v206, v207
	v_add_f32_e32 v208, v208, v209
	v_add_f32_e32 v202, v202, v203
	v_add_f32_e32 v204, v204, v205
	v_add_f32_e32 v222, v222, v223
	v_add_f32_e32 v224, v224, v225
	v_add_f32_e32 v218, v218, v219
	v_add_f32_e32 v220, v220, v221
	v_add_f32_e32 v230, v230, v231
	v_add_f32_e32 v232, v232, v233
	v_add_f32_e32 v226, v226, v227
	v_add_f32_e32 v228, v228, v229
	v_add_f32_e32 v238, v238, v239
	v_add_f32_e32 v240, v240, v241
	v_add_f32_e32 v234, v234, v235
	v_add_f32_e32 v236, v236, v237
	v_add_f32_e32 v246, v246, v247
	v_add_f32_e32 v248, v248, v249
	v_add_f32_e32 v242, v242, v243
	v_add_f32_e32 v244, v244, v245
	v_add_f32_e32 v172, v172, v173
	v_add_f32_e32 v174, v174, v175
	v_add_f32_e32 v168, v168, v169
	v_add_f32_e32 v170, v170, v171
	v_add_f32_e32 v198, v198, v200
	v_add_f32_e32 v194, v194, v196
	v_add_f32_e32 v206, v206, v208
	v_add_f32_e32 v202, v202, v204
	v_add_f32_e32 v222, v222, v224
	v_add_f32_e32 v218, v218, v220
	v_add_f32_e32 v230, v230, v232
	v_add_f32_e32 v226, v226, v228
	v_add_f32_e32 v238, v238, v240
	v_add_f32_e32 v234, v234, v236
	v_add_f32_e32 v246, v246, v248
	v_add_f32_e32 v242, v242, v244
	v_add_f32_e32 v172, v172, v174
	v_add_f32_e32 v168, v168, v170
	v_add_f32_e32 v180, v198, v194
	v_add_f32_e32 v181, v206, v202
	v_add_f32_e32 v182, v222, v218
	v_add_f32_e32 v183, v230, v226
	v_add_f32_e32 v184, v238, v234
	v_add_f32_e32 v185, v246, v242
	v_add_f32_e32 v186, v172, v168
	v_add_u32_e32 v187, 0x80, v140
	v_mul_hi_i32 v192, v187, s33
	v_lshrrev_b32_e32 v193, 31, v192
	v_lshrrev_b32_e32 v192, 5, v192
	v_add_u32_e32 v192, v192, v193
	s_movk_i32 s6, 0xc0
	v_mul_lo_u32 v192, v192, s6
	v_sub_u32_e32 v187, v187, v192
	s_movk_i32 s6, 0x7f
	v_cmp_lt_i32_e64 s[8:9], s6, v187
	v_add_u32_e32 v187, 0xffffff80, v187
	v_lshrrev_b32_e32 v187, 1, v187
	v_cndmask_b32_e32 v187, v187, v176, vcc
	s_nop 3
	s_or_b64 s[8:9], s[8:9], vcc
	s_and_saveexec_b64 s[6:7], s[8:9]
	s_cbranch_execz .Lq_norope
	v_lshlrev_b32_e32 v210, 2, v187
	v_mov_b32_e32 v211, 0
	s_mov_b32 s8, 0x1000
	s_mov_b32 s9, 0
	v_lshl_add_u64 v[190:191], v[146:147], 0, v[210:211]
	v_lshl_add_u64 v[192:193], v[144:145], 0, v[210:211]
	global_load_dwordx4 v[194:197], v[190:191], off offset:2048
	global_load_dwordx4 v[198:201], v[192:193], off offset:2048
	v_lshl_add_u64 v[190:191], v[190:191], 0, s[8:9]
	v_lshl_add_u64 v[192:193], v[192:193], 0, s[8:9]
	global_load_dwordx4 v[202:205], v[190:191], off
	global_load_dwordx4 v[206:209], v[192:193], off
	global_load_dwordx4 v[218:221], v[190:191], off offset:2048
	global_load_dwordx4 v[222:225], v[192:193], off offset:2048
	s_mov_b32 s8, 0x3000
	v_lshl_add_u64 v[190:191], v[190:191], 0, s[8:9]
	v_lshl_add_u64 v[192:193], v[192:193], 0, s[8:9]
	s_mov_b32 s8, 0x1000
	global_load_dwordx4 v[226:229], v[190:191], off
	global_load_dwordx4 v[230:233], v[192:193], off
	global_load_dwordx4 v[234:237], v[190:191], off offset:2048
	global_load_dwordx4 v[238:241], v[192:193], off offset:2048
	v_lshl_add_u64 v[190:191], v[190:191], 0, s[8:9]
	v_lshl_add_u64 v[192:193], v[192:193], 0, s[8:9]
	global_load_dwordx4 v[242:245], v[190:191], off
	global_load_dwordx4 v[246:249], v[192:193], off
	global_load_dwordx4 v[168:171], v[190:191], off offset:2048
	global_load_dwordx4 v[172:175], v[192:193], off offset:2048
	s_waitcnt vmcnt(0)
.Lq_norope:
	s_or_b64 exec, exec, s[6:7]
	s_and_saveexec_b64 s[6:7], vcc
	s_cbranch_execz .LBB0_126
	v_lshlrev_b64 v[156:157], 2, v[176:177]
	v_lshl_add_u64 v[152:153], v[146:147], 0, v[156:157]
	v_lshl_add_u64 v[156:157], v[144:145], 0, v[156:157]
	global_load_dwordx4 v[152:155], v[152:153], off
	s_nop 0
	global_load_dwordx4 v[156:159], v[156:157], off
	s_waitcnt vmcnt(0)
	v_pk_mul_f32 v[160:161], v[124:125], v[152:153]
	v_pk_mul_f32 v[162:163], v[124:125], v[156:157] op_sel:[1,0] op_sel_hi:[0,0]
	v_pk_fma_f32 v[124:125], v[124:125], v[152:153], v[162:163] op_sel_hi:[1,0,1]
	v_mov_b32_e32 v156, v153
	v_mul_f32_e32 v124, v127, v157
	v_pk_fma_f32 v[164:165], v[126:127], v[156:157], v[124:125] op_sel_hi:[1,1,0] neg_lo:[0,0,1] neg_hi:[0,0,1]
	v_mov_b32_e32 v152, v157
	v_mul_f32_e32 v124, v127, v153
	v_pk_mul_f32 v[156:157], v[120:121], v[158:159] op_sel:[1,0] op_sel_hi:[0,0]
	v_pk_fma_f32 v[152:153], v[126:127], v[152:153], v[124:125] op_sel_hi:[1,1,0]
	v_pk_mul_f32 v[126:127], v[120:121], v[154:155]
	v_pk_fma_f32 v[120:121], v[120:121], v[154:155], v[156:157] op_sel_hi:[1,0,1]
	v_mov_b32_e32 v158, v155
	v_mul_f32_e32 v120, v123, v159
	v_pk_fma_f32 v[166:167], v[122:123], v[158:159], v[120:121] op_sel_hi:[1,1,0] neg_lo:[0,0,1] neg_hi:[0,0,1]
	v_mov_b32_e32 v154, v159
	v_mul_f32_e32 v120, v123, v155
	v_pk_fma_f32 v[154:155], v[122:123], v[154:155], v[120:121] op_sel_hi:[1,1,0]
	v_sub_f32_e32 v124, v160, v162
	v_sub_f32_e32 v120, v126, v156
	v_mov_b32_e32 v126, v164
	v_mov_b32_e32 v127, v152
	v_mov_b32_e32 v122, v166
	v_mov_b32_e32 v123, v154

; __device__ __forceinline__ u32x4 pack8(f32x4 a, f32x4 b) { u32x4 r; r[0] = cvt_pk_bf16(a[0], a[1]); r[1] = cvt_pk_bf16(a[2], a[3]); r[2] = cvt_pk_bf16(b[0], b[1]); r[3] = cvt_pk_bf16(b[2], b[3]); return r; }
;     __device__ __forceinline__ void operator()(const AccT& acc, const Unit& u, int wr, int wc, int fr, int fq) const {
;     ...
;                 const int row = row0 + ai * HALF + m * 16;
;                 const f32x4 pa = *(const f32x4*)(ssp + (size_t)row * 16), pb = *(const f32x4*)(ssp + (size_t)row * 16 + 4);
;                 const float ssr = ((pa[0] + pa[1]) + (pa[2] + pa[3])) + ((pb[0] + pb[1]) + (pb[2] + pb[3]));
;                 const float sc = rsqrtf(ssr * (1.0f / 512.0f) + EPS) * (1.4426950408889634f * 0.07216878364870322f);
; #pragma unroll
;                 for (int bj = 0; bj < 2; ++bj) {
;                     const int col = colbase + bj * HALF; f32x4 v0 = acc[ai][bj][m][0], v1 = acc[ai][bj][m][1];
;                     const int d = col % 192;
;                     if (d >= 128) { const int i0 = (d - 128) >> 1;
;                         const f32x4 c4 = *(const f32x4*)(cosT + (size_t)row * 32 + i0), s4 = *(const f32x4*)(sinT + (size_t)row * 32 + i0);
;                         f32x4 o0, o1;
;                         o0[0] = v0[0] * c4[0] - v0[1] * s4[0]; o0[1] = v0[1] * c4[0] + v0[0] * s4[0];
;                         o0[2] = v0[2] * c4[1] - v0[3] * s4[1]; o0[3] = v0[3] * c4[1] + v0[2] * s4[1];
;                         o1[0] = v1[0] * c4[2] - v1[1] * s4[2]; o1[1] = v1[1] * c4[2] + v1[0] * s4[2];
;                         o1[2] = v1[2] * c4[3] - v1[3] * s4[3]; o1[3] = v1[3] * c4[3] + v1[2] * s4[3];
;                         v0 = o0; v1 = o1; }
;                     *(u32x4*)(Q + (size_t)row * NQ + col) = pack8(v0 * sc, v1 * sc); __builtin_amdgcn_sched_barrier(0);
;                 }
.LBB0_128:
	s_or_b64 exec, exec, s[8:9]
	v_mov_b32_e32 v129, v128
	v_mov_b32_e32 v124, v128
	v_mov_b32_e32 v125, v128
	v_pk_mul_f32 v[118:119], v[124:125], v[118:119]
	v_pk_mul_f32 v[116:117], v[128:129], v[116:117]
	v_pk_mul_f32 v[124:125], v[124:125], v[114:115]
	v_pk_mul_f32 v[114:115], v[128:129], v[112:113]
	v_cvt_pk_bf16_f32 v112, v116, v117
	v_cvt_pk_bf16_f32 v113, v118, v119
	s_nop 0
	v_cvt_pk_bf16_f32 v114, v114, v115
	v_cvt_pk_bf16_f32 v115, v124, v125
	global_store_dwordx4 v[122:123], v[112:115], off offset:256
	v_or_b32_e32 v126, 16, v142
	v_ashrrev_i32_e32 v127, 31, v126
	v_readlane_b32 s8, v253, 12
	v_lshlrev_b64 v[112:113], 6, v[126:127]
	v_readlane_b32 s9, v253, 13
	v_lshlrev_b64 v[122:123], 5, v[126:127]
	v_lshlrev_b64 v[122:123], 2, v[122:123]
	v_lshl_add_u64 v[116:117], s[8:9], 0, v[112:113]
	v_mov_b32_e32 v112, 0
	v_mov_b32_e32 v113, 0
	v_mov_b32_e32 v114, 0
	v_mov_b32_e32 v115, 0
	s_nop 0
	v_mov_b32_e32 v116, v180
	v_mov_b32_e32 v117, 0
	v_mov_b32_e32 v118, 0
	v_mov_b32_e32 v119, 0
	v_readlane_b32 s8, v254, 48
	v_readlane_b32 s9, v254, 49
	s_nop 1
	v_lshl_add_u64 v[124:125], s[8:9], 0, v[122:123]
	v_readlane_b32 s8, v253, 14
	v_readlane_b32 s9, v253, 15
	s_nop 1
	v_lshl_add_u64 v[122:123], s[8:9], 0, v[122:123]
	s_and_saveexec_b64 s[8:9], vcc
	s_cbranch_execz .LBB0_130
	v_lshlrev_b64 v[132:133], 2, v[176:177]
	v_lshl_add_u64 v[128:129], v[124:125], 0, v[132:133]
	v_lshl_add_u64 v[132:133], v[122:123], 0, v[132:133]
	v_mov_b32_e32 v128, v194
	v_mov_b32_e32 v129, v195
	v_mov_b32_e32 v130, v196
	v_mov_b32_e32 v131, v197
	s_nop 0
	v_mov_b32_e32 v132, v198
	v_mov_b32_e32 v133, v199
	v_mov_b32_e32 v134, v200
	v_mov_b32_e32 v135, v201
	v_pk_mul_f32 v[144:145], v[108:109], v[128:129]
	v_pk_mul_f32 v[146:147], v[108:109], v[132:133] op_sel:[1,0] op_sel_hi:[0,0]
	v_pk_fma_f32 v[108:109], v[108:109], v[128:129], v[146:147] op_sel_hi:[1,0,1]
	v_mov_b32_e32 v132, v129
	v_mul_f32_e32 v108, v111, v133
	v_pk_fma_f32 v[152:153], v[110:111], v[132:133], v[108:109] op_sel_hi:[1,1,0] neg_lo:[0,0,1] neg_hi:[0,0,1]
	v_mov_b32_e32 v128, v133
	v_mul_f32_e32 v108, v111, v129
	v_pk_mul_f32 v[132:133], v[104:105], v[134:135] op_sel:[1,0] op_sel_hi:[0,0]
	v_pk_fma_f32 v[128:129], v[110:111], v[128:129], v[108:109] op_sel_hi:[1,1,0]
	v_pk_mul_f32 v[110:111], v[104:105], v[130:131]
	v_pk_fma_f32 v[104:105], v[104:105], v[130:131], v[132:133] op_sel_hi:[1,0,1]
	v_mov_b32_e32 v134, v131
	v_mul_f32_e32 v104, v107, v135
	v_pk_fma_f32 v[154:155], v[106:107], v[134:135], v[104:105] op_sel_hi:[1,1,0] neg_lo:[0,0,1] neg_hi:[0,0,1]
	v_mov_b32_e32 v130, v135
	v_mul_f32_e32 v104, v107, v131
	v_pk_fma_f32 v[130:131], v[106:107], v[130:131], v[104:105] op_sel_hi:[1,1,0]
	v_sub_f32_e32 v108, v144, v146
	v_sub_f32_e32 v104, v110, v132
	v_mov_b32_e32 v110, v152
	v_mov_b32_e32 v111, v128
	v_mov_b32_e32 v106, v154
	v_mov_b32_e32 v107, v130
.LBB0_130:
	s_or_b64 exec, exec, s[8:9]
	v_mov_b32_e32 v128, v116
	v_mov_b32_e32 v129, v112
	v_mov_b32_e32 v112, v117
	v_mov_b32_e32 v116, v118
	v_mov_b32_e32 v117, v114
	v_mov_b32_e32 v114, v119
	v_pk_add_f32 v[112:113], v[128:129], v[112:113]
	v_pk_add_f32 v[114:115], v[116:117], v[114:115]
	s_nop 0
	v_pk_add_f32 v[112:113], v[112:113], v[114:115]
	s_nop 0
	v_add_f32_e32 v112, v112, v113
	v_fmamk_f32 v112, v112, 0x3b000000, v252
	v_mul_f32_e32 v113, 0x4b800000, v112
	v_cmp_gt_f32_e64 s[8:9], s25, v112
	s_nop 1
	v_cndmask_b32_e64 v112, v112, v113, s[8:9]
	v_rsq_f32_e32 v112, v112
	s_nop 0
	v_mul_f32_e32 v113, 0x45800000, v112
	v_cndmask_b32_e64 v112, v112, v113, s[8:9]
	v_mul_f32_e32 v112, 0x3dd53b94, v112
	v_pk_mul_f32 v[108:109], v[112:113], v[108:109] op_sel_hi:[0,1]
	v_pk_mul_f32 v[104:105], v[112:113], v[104:105] op_sel_hi:[0,1]
	v_pk_mul_f32 v[110:111], v[112:113], v[110:111] op_sel_hi:[0,1]
	v_pk_mul_f32 v[114:115], v[112:113], v[106:107] op_sel_hi:[0,1]
	v_cvt_pk_bf16_f32 v106, v108, v109
	v_cvt_pk_bf16_f32 v107, v110, v111
	v_cvt_pk_bf16_f32 v108, v104, v105
	v_mov_b64_e32 v[104:105], s[28:29]
	v_mad_i64_i32 v[104:105], s[8:9], v126, s24, v[104:105]
	v_lshl_add_u64 v[104:105], v[140:141], 1, v[104:105]
	v_cvt_pk_bf16_f32 v109, v114, v115
	global_store_dwordx4 v[104:105], v[106:109], off
	s_and_saveexec_b64 s[8:9], s[6:7]
	s_cbranch_execz .LBB0_132
	v_mov_b32_e32 v121, v177
	v_lshlrev_b64 v[110:111], 2, v[120:121]
	v_lshl_add_u64 v[106:107], v[124:125], 0, v[110:111]
	v_lshl_add_u64 v[110:111], v[122:123], 0, v[110:111]
	v_mov_b32_e32 v106, v194
	v_mov_b32_e32 v107, v195
	v_mov_b32_e32 v108, v196
	v_mov_b32_e32 v109, v197
	s_nop 0
	v_mov_b32_e32 v114, v198
	v_mov_b32_e32 v115, v199
	v_mov_b32_e32 v116, v200
	v_mov_b32_e32 v117, v201
	v_pk_mul_f32 v[110:111], v[100:101], v[106:107]
	v_pk_mul_f32 v[118:119], v[100:101], v[114:115] op_sel:[1,0] op_sel_hi:[0,0]
	v_pk_fma_f32 v[100:101], v[100:101], v[106:107], v[118:119] op_sel_hi:[1,0,1]
	v_mov_b32_e32 v114, v107
	v_mul_f32_e32 v100, v103, v115
	v_pk_fma_f32 v[122:123], v[102:103], v[114:115], v[100:101] op_sel_hi:[1,1,0] neg_lo:[0,0,1] neg_hi:[0,0,1]
	v_mov_b32_e32 v106, v115
	v_mul_f32_e32 v100, v103, v107
	v_pk_mul_f32 v[114:115], v[96:97], v[116:117] op_sel:[1,0] op_sel_hi:[0,0]
	v_pk_fma_f32 v[106:107], v[102:103], v[106:107], v[100:101] op_sel_hi:[1,1,0]
	v_pk_mul_f32 v[102:103], v[96:97], v[108:109]
	v_pk_fma_f32 v[96:97], v[96:97], v[108:109], v[114:115] op_sel_hi:[1,0,1]
	v_mov_b32_e32 v116, v109
	v_mul_f32_e32 v96, v99, v117
	v_pk_fma_f32 v[124:125], v[98:99], v[116:117], v[96:97] op_sel_hi:[1,1,0] neg_lo:[0,0,1] neg_hi:[0,0,1]
	v_mov_b32_e32 v108, v117
	v_mul_f32_e32 v96, v99, v109
	v_pk_fma_f32 v[108:109], v[98:99], v[108:109], v[96:97] op_sel_hi:[1,1,0]
	v_sub_f32_e32 v100, v110, v118
	v_sub_f32_e32 v96, v102, v114
	v_mov_b32_e32 v102, v122
	v_mov_b32_e32 v103, v106
	v_mov_b32_e32 v98, v124
	v_mov_b32_e32 v99, v108
; __device__ __forceinline__ u32x4 pack8(f32x4 a, f32x4 b) { u32x4 r; r[0] = cvt_pk_bf16(a[0], a[1]); r[1] = cvt_pk_bf16(a[2], a[3]); r[2] = cvt_pk_bf16(b[0], b[1]); r[3] = cvt_pk_bf16(b[2], b[3]); return r; }
;     __device__ __forceinline__ void operator()(const AccT& acc, const Unit& u, int wr, int wc, int fr, int fq) const {
;     ...
;                 const int row = row0 + ai * HALF + m * 16;
;                 const f32x4 pa = *(const f32x4*)(ssp + (size_t)row * 16), pb = *(const f32x4*)(ssp + (size_t)row * 16 + 4);
;                 const float ssr = ((pa[0] + pa[1]) + (pa[2] + pa[3])) + ((pb[0] + pb[1]) + (pb[2] + pb[3]));
;                 const float sc = rsqrtf(ssr * (1.0f / 512.0f) + EPS) * (1.4426950408889634f * 0.07216878364870322f);
; #pragma unroll
;                 for (int bj = 0; bj < 2; ++bj) {
;                     const int col = colbase + bj * HALF; f32x4 v0 = acc[ai][bj][m][0], v1 = acc[ai][bj][m][1];
;                     const int d = col % 192;
;                     if (d >= 128) { const int i0 = (d - 128) >> 1;
;                         const f32x4 c4 = *(const f32x4*)(cosT + (size_t)row * 32 + i0), s4 = *(const f32x4*)(sinT + (size_t)row * 32 + i0);
;                         f32x4 o0, o1;
;                         o0[0] = v0[0] * c4[0] - v0[1] * s4[0]; o0[1] = v0[1] * c4[0] + v0[0] * s4[0];
;                         o0[2] = v0[2] * c4[1] - v0[3] * s4[1]; o0[3] = v0[3] * c4[1] + v0[2] * s4[1];
;                         o1[0] = v1[0] * c4[2] - v1[1] * s4[2]; o1[1] = v1[1] * c4[2] + v1[0] * s4[2];
;                         o1[2] = v1[2] * c4[3] - v1[3] * s4[3]; o1[3] = v1[3] * c4[3] + v1[2] * s4[3];
;                         v0 = o0; v1 = o1; }
;                     *(u32x4*)(Q + (size_t)row * NQ + col) = pack8(v0 * sc, v1 * sc); __builtin_amdgcn_sched_barrier(0);
;                 }
.LBB0_132:
	s_or_b64 exec, exec, s[8:9]
	v_mov_b32_e32 v113, v112
	v_mov_b32_e32 v106, v112
	v_mov_b32_e32 v107, v112
	v_pk_mul_f32 v[102:103], v[106:107], v[102:103]
	v_pk_mul_f32 v[100:101], v[112:113], v[100:101]
	v_pk_mul_f32 v[106:107], v[106:107], v[98:99]
	v_pk_mul_f32 v[98:99], v[112:113], v[96:97]
	v_cvt_pk_bf16_f32 v96, v100, v101
	v_cvt_pk_bf16_f32 v97, v102, v103
	s_nop 0
	v_cvt_pk_bf16_f32 v98, v98, v99
	v_cvt_pk_bf16_f32 v99, v106, v107
	global_store_dwordx4 v[104:105], v[96:99], off offset:256
	v_or_b32_e32 v108, 32, v142
	v_ashrrev_i32_e32 v109, 31, v108
	v_readlane_b32 s8, v253, 12
	v_lshlrev_b64 v[96:97], 6, v[108:109]
	v_readlane_b32 s9, v253, 13
	v_lshlrev_b64 v[104:105], 5, v[108:109]
	v_lshlrev_b64 v[104:105], 2, v[104:105]
	v_lshl_add_u64 v[100:101], s[8:9], 0, v[96:97]
	v_mov_b32_e32 v96, 0
	v_mov_b32_e32 v97, 0
	v_mov_b32_e32 v98, 0
	v_mov_b32_e32 v99, 0
	s_nop 0
	v_mov_b32_e32 v100, v181
	v_mov_b32_e32 v101, 0
	v_mov_b32_e32 v102, 0
	v_mov_b32_e32 v103, 0
	v_readlane_b32 s8, v254, 48
	v_readlane_b32 s9, v254, 49
	s_nop 1
	v_lshl_add_u64 v[106:107], s[8:9], 0, v[104:105]
	v_readlane_b32 s8, v253, 14
	v_readlane_b32 s9, v253, 15
	s_nop 1
	v_lshl_add_u64 v[104:105], s[8:9], 0, v[104:105]
	s_and_saveexec_b64 s[8:9], vcc
	s_cbranch_execz .LBB0_134
	v_lshlrev_b64 v[114:115], 2, v[176:177]
	v_lshl_add_u64 v[110:111], v[106:107], 0, v[114:115]
	v_lshl_add_u64 v[114:115], v[104:105], 0, v[114:115]
	v_mov_b32_e32 v110, v202
	v_mov_b32_e32 v111, v203
	v_mov_b32_e32 v112, v204
	v_mov_b32_e32 v113, v205
	s_nop 0
	v_mov_b32_e32 v114, v206
	v_mov_b32_e32 v115, v207
	v_mov_b32_e32 v116, v208
	v_mov_b32_e32 v117, v209
	v_pk_mul_f32 v[118:119], v[92:93], v[110:111]
	v_pk_mul_f32 v[122:123], v[92:93], v[114:115] op_sel:[1,0] op_sel_hi:[0,0]
	v_pk_fma_f32 v[92:93], v[92:93], v[110:111], v[122:123] op_sel_hi:[1,0,1]
	v_mov_b32_e32 v114, v111
	v_mul_f32_e32 v92, v95, v115
	v_pk_fma_f32 v[124:125], v[94:95], v[114:115], v[92:93] op_sel_hi:[1,1,0] neg_lo:[0,0,1] neg_hi:[0,0,1]
	v_mov_b32_e32 v110, v115
	v_mul_f32_e32 v92, v95, v111
	v_pk_mul_f32 v[114:115], v[88:89], v[116:117] op_sel:[1,0] op_sel_hi:[0,0]
	v_pk_fma_f32 v[110:111], v[94:95], v[110:111], v[92:93] op_sel_hi:[1,1,0]
	v_pk_mul_f32 v[94:95], v[88:89], v[112:113]
	v_pk_fma_f32 v[88:89], v[88:89], v[112:113], v[114:115] op_sel_hi:[1,0,1]
	v_mov_b32_e32 v116, v113
	v_mul_f32_e32 v88, v91, v117
	v_pk_fma_f32 v[126:127], v[90:91], v[116:117], v[88:89] op_sel_hi:[1,1,0] neg_lo:[0,0,1] neg_hi:[0,0,1]
	v_mov_b32_e32 v112, v117
	v_mul_f32_e32 v88, v91, v113
	v_pk_fma_f32 v[112:113], v[90:91], v[112:113], v[88:89] op_sel_hi:[1,1,0]
	v_sub_f32_e32 v92, v118, v122
	v_sub_f32_e32 v88, v94, v114
	v_mov_b32_e32 v94, v124
	v_mov_b32_e32 v95, v110
	v_mov_b32_e32 v90, v126
	v_mov_b32_e32 v91, v112
.LBB0_134:
	s_or_b64 exec, exec, s[8:9]
	v_mov_b32_e32 v110, v100
	v_mov_b32_e32 v111, v96
	v_mov_b32_e32 v96, v101
	v_mov_b32_e32 v100, v102
	v_mov_b32_e32 v101, v98
	v_mov_b32_e32 v98, v103
	v_pk_add_f32 v[96:97], v[110:111], v[96:97]
	v_pk_add_f32 v[98:99], v[100:101], v[98:99]
	s_nop 0
	v_pk_add_f32 v[96:97], v[96:97], v[98:99]
	s_nop 0
	v_add_f32_e32 v96, v96, v97
	v_fmamk_f32 v96, v96, 0x3b000000, v252
	v_mul_f32_e32 v97, 0x4b800000, v96
	v_cmp_gt_f32_e64 s[8:9], s25, v96
	s_nop 1
	v_cndmask_b32_e64 v96, v96, v97, s[8:9]
	v_rsq_f32_e32 v96, v96
	s_nop 0
	v_mul_f32_e32 v97, 0x45800000, v96
	v_cndmask_b32_e64 v96, v96, v97, s[8:9]
	v_mul_f32_e32 v96, 0x3dd53b94, v96
	v_pk_mul_f32 v[92:93], v[96:97], v[92:93] op_sel_hi:[0,1]
	v_pk_mul_f32 v[88:89], v[96:97], v[88:89] op_sel_hi:[0,1]
	v_pk_mul_f32 v[94:95], v[96:97], v[94:95] op_sel_hi:[0,1]
	v_pk_mul_f32 v[98:99], v[96:97], v[90:91] op_sel_hi:[0,1]
	v_cvt_pk_bf16_f32 v90, v92, v93
	v_cvt_pk_bf16_f32 v91, v94, v95
	v_cvt_pk_bf16_f32 v92, v88, v89
	v_mov_b64_e32 v[88:89], s[28:29]
	v_mad_i64_i32 v[88:89], s[8:9], v108, s24, v[88:89]
	v_lshl_add_u64 v[88:89], v[140:141], 1, v[88:89]
	v_cvt_pk_bf16_f32 v93, v98, v99
	global_store_dwordx4 v[88:89], v[90:93], off
	s_and_saveexec_b64 s[8:9], s[6:7]
	s_cbranch_execz .LBB0_136
	v_mov_b32_e32 v121, v177
	v_lshlrev_b64 v[94:95], 2, v[120:121]
	v_lshl_add_u64 v[90:91], v[106:107], 0, v[94:95]
	v_lshl_add_u64 v[94:95], v[104:105], 0, v[94:95]
	v_mov_b32_e32 v90, v202
	v_mov_b32_e32 v91, v203
	v_mov_b32_e32 v92, v204
	v_mov_b32_e32 v93, v205
	s_nop 0
	v_mov_b32_e32 v98, v206
	v_mov_b32_e32 v99, v207
	v_mov_b32_e32 v100, v208
	v_mov_b32_e32 v101, v209
	v_pk_mul_f32 v[94:95], v[84:85], v[90:91]
	v_pk_mul_f32 v[102:103], v[84:85], v[98:99] op_sel:[1,0] op_sel_hi:[0,0]
	v_pk_fma_f32 v[84:85], v[84:85], v[90:91], v[102:103] op_sel_hi:[1,0,1]
	v_mov_b32_e32 v98, v91
	v_mul_f32_e32 v84, v87, v99
	v_pk_fma_f32 v[104:105], v[86:87], v[98:99], v[84:85] op_sel_hi:[1,1,0] neg_lo:[0,0,1] neg_hi:[0,0,1]
	v_mov_b32_e32 v90, v99
	v_mul_f32_e32 v84, v87, v91
	v_pk_mul_f32 v[98:99], v[80:81], v[100:101] op_sel:[1,0] op_sel_hi:[0,0]
	v_pk_fma_f32 v[90:91], v[86:87], v[90:91], v[84:85] op_sel_hi:[1,1,0]
	v_pk_mul_f32 v[86:87], v[80:81], v[92:93]
	v_pk_fma_f32 v[80:81], v[80:81], v[92:93], v[98:99] op_sel_hi:[1,0,1]
	v_mov_b32_e32 v100, v93
	v_mul_f32_e32 v80, v83, v101
	v_pk_fma_f32 v[106:107], v[82:83], v[100:101], v[80:81] op_sel_hi:[1,1,0] neg_lo:[0,0,1] neg_hi:[0,0,1]
	v_mov_b32_e32 v92, v101
	v_mul_f32_e32 v80, v83, v93
	v_pk_fma_f32 v[92:93], v[82:83], v[92:93], v[80:81] op_sel_hi:[1,1,0]
	v_sub_f32_e32 v84, v94, v102
	v_sub_f32_e32 v80, v86, v98
	v_mov_b32_e32 v86, v104
	v_mov_b32_e32 v87, v90
	v_mov_b32_e32 v82, v106
	v_mov_b32_e32 v83, v92
; __device__ __forceinline__ u32x4 pack8(f32x4 a, f32x4 b) { u32x4 r; r[0] = cvt_pk_bf16(a[0], a[1]); r[1] = cvt_pk_bf16(a[2], a[3]); r[2] = cvt_pk_bf16(b[0], b[1]); r[3] = cvt_pk_bf16(b[2], b[3]); return r; }
;     __device__ __forceinline__ void operator()(const AccT& acc, const Unit& u, int wr, int wc, int fr, int fq) const {
;     ...
;                 const int row = row0 + ai * HALF + m * 16;
;                 const f32x4 pa = *(const f32x4*)(ssp + (size_t)row * 16), pb = *(const f32x4*)(ssp + (size_t)row * 16 + 4);
;                 const float ssr = ((pa[0] + pa[1]) + (pa[2] + pa[3])) + ((pb[0] + pb[1]) + (pb[2] + pb[3]));
;                 const float sc = rsqrtf(ssr * (1.0f / 512.0f) + EPS) * (1.4426950408889634f * 0.07216878364870322f);
; #pragma unroll
;                 for (int bj = 0; bj < 2; ++bj) {
;                     const int col = colbase + bj * HALF; f32x4 v0 = acc[ai][bj][m][0], v1 = acc[ai][bj][m][1];
;                     const int d = col % 192;
;                     if (d >= 128) { const int i0 = (d - 128) >> 1;
;                         const f32x4 c4 = *(const f32x4*)(cosT + (size_t)row * 32 + i0), s4 = *(const f32x4*)(sinT + (size_t)row * 32 + i0);
;                         f32x4 o0, o1;
;                         o0[0] = v0[0] * c4[0] - v0[1] * s4[0]; o0[1] = v0[1] * c4[0] + v0[0] * s4[0];
;                         o0[2] = v0[2] * c4[1] - v0[3] * s4[1]; o0[3] = v0[3] * c4[1] + v0[2] * s4[1];
;                         o1[0] = v1[0] * c4[2] - v1[1] * s4[2]; o1[1] = v1[1] * c4[2] + v1[0] * s4[2];
;                         o1[2] = v1[2] * c4[3] - v1[3] * s4[3]; o1[3] = v1[3] * c4[3] + v1[2] * s4[3];
;                         v0 = o0; v1 = o1; }
;                     *(u32x4*)(Q + (size_t)row * NQ + col) = pack8(v0 * sc, v1 * sc); __builtin_amdgcn_sched_barrier(0);
.LBB0_136:
	s_or_b64 exec, exec, s[8:9]
	v_mov_b32_e32 v97, v96
	v_mov_b32_e32 v90, v96
	v_mov_b32_e32 v91, v96
	v_pk_mul_f32 v[86:87], v[90:91], v[86:87]
	v_pk_mul_f32 v[84:85], v[96:97], v[84:85]
	v_pk_mul_f32 v[90:91], v[90:91], v[82:83]
	v_pk_mul_f32 v[82:83], v[96:97], v[80:81]
	v_cvt_pk_bf16_f32 v80, v84, v85
	v_cvt_pk_bf16_f32 v81, v86, v87
	s_nop 0
	v_cvt_pk_bf16_f32 v82, v82, v83
	v_cvt_pk_bf16_f32 v83, v90, v91
	global_store_dwordx4 v[88:89], v[80:83], off offset:256
	v_or_b32_e32 v92, 48, v142
	v_ashrrev_i32_e32 v93, 31, v92
	v_readlane_b32 s8, v253, 12
	v_lshlrev_b64 v[80:81], 6, v[92:93]
	v_readlane_b32 s9, v253, 13
	v_lshlrev_b64 v[88:89], 5, v[92:93]
	v_lshlrev_b64 v[88:89], 2, v[88:89]
	v_lshl_add_u64 v[84:85], s[8:9], 0, v[80:81]
	v_mov_b32_e32 v80, 0
	v_mov_b32_e32 v81, 0
	v_mov_b32_e32 v82, 0
	v_mov_b32_e32 v83, 0
	s_nop 0
	v_mov_b32_e32 v84, v182
	v_mov_b32_e32 v85, 0
	v_mov_b32_e32 v86, 0
	v_mov_b32_e32 v87, 0
	v_readlane_b32 s8, v254, 48
	v_readlane_b32 s9, v254, 49
	s_nop 1
	v_lshl_add_u64 v[90:91], s[8:9], 0, v[88:89]
	v_readlane_b32 s8, v253, 14
	v_readlane_b32 s9, v253, 15
	s_nop 1
	v_lshl_add_u64 v[88:89], s[8:9], 0, v[88:89]
	s_and_saveexec_b64 s[8:9], vcc
	s_cbranch_execz .LBB0_138
	v_lshlrev_b64 v[98:99], 2, v[176:177]
	v_lshl_add_u64 v[94:95], v[90:91], 0, v[98:99]
	v_lshl_add_u64 v[98:99], v[88:89], 0, v[98:99]
	v_mov_b32_e32 v94, v218
	v_mov_b32_e32 v95, v219
	v_mov_b32_e32 v96, v220
	v_mov_b32_e32 v97, v221
	s_nop 0
	v_mov_b32_e32 v98, v222
	v_mov_b32_e32 v99, v223
	v_mov_b32_e32 v100, v224
	v_mov_b32_e32 v101, v225
	v_pk_mul_f32 v[102:103], v[76:77], v[94:95]
	v_pk_mul_f32 v[104:105], v[76:77], v[98:99] op_sel:[1,0] op_sel_hi:[0,0]
	v_pk_fma_f32 v[76:77], v[76:77], v[94:95], v[104:105] op_sel_hi:[1,0,1]
	v_mov_b32_e32 v98, v95
	v_mul_f32_e32 v76, v79, v99
	v_pk_fma_f32 v[106:107], v[78:79], v[98:99], v[76:77] op_sel_hi:[1,1,0] neg_lo:[0,0,1] neg_hi:[0,0,1]
	v_mov_b32_e32 v94, v99
	v_mul_f32_e32 v76, v79, v95
	v_pk_mul_f32 v[98:99], v[72:73], v[100:101] op_sel:[1,0] op_sel_hi:[0,0]
	v_pk_fma_f32 v[94:95], v[78:79], v[94:95], v[76:77] op_sel_hi:[1,1,0]
	v_pk_mul_f32 v[78:79], v[72:73], v[96:97]
	v_pk_fma_f32 v[72:73], v[72:73], v[96:97], v[98:99] op_sel_hi:[1,0,1]
	v_mov_b32_e32 v100, v97
	v_mul_f32_e32 v72, v75, v101
	v_pk_fma_f32 v[108:109], v[74:75], v[100:101], v[72:73] op_sel_hi:[1,1,0] neg_lo:[0,0,1] neg_hi:[0,0,1]
	v_mov_b32_e32 v96, v101
	v_mul_f32_e32 v72, v75, v97
	v_pk_fma_f32 v[96:97], v[74:75], v[96:97], v[72:73] op_sel_hi:[1,1,0]
	v_sub_f32_e32 v76, v102, v104
	v_sub_f32_e32 v72, v78, v98
	v_mov_b32_e32 v78, v106
	v_mov_b32_e32 v79, v94
	v_mov_b32_e32 v74, v108
	v_mov_b32_e32 v75, v96
.LBB0_138:
	s_or_b64 exec, exec, s[8:9]
	v_mov_b32_e32 v94, v84
	v_mov_b32_e32 v95, v80
	v_mov_b32_e32 v80, v85
	v_mov_b32_e32 v84, v86
	v_mov_b32_e32 v85, v82
	v_mov_b32_e32 v82, v87
	v_pk_add_f32 v[80:81], v[94:95], v[80:81]
	v_pk_add_f32 v[82:83], v[84:85], v[82:83]
	s_nop 0
	v_pk_add_f32 v[80:81], v[80:81], v[82:83]
	s_nop 0
	v_add_f32_e32 v80, v80, v81
	v_fmamk_f32 v80, v80, 0x3b000000, v252
	v_mul_f32_e32 v81, 0x4b800000, v80
	v_cmp_gt_f32_e64 s[8:9], s25, v80
	s_nop 1
	v_cndmask_b32_e64 v80, v80, v81, s[8:9]
	v_rsq_f32_e32 v80, v80
	s_nop 0
	v_mul_f32_e32 v81, 0x45800000, v80
	v_cndmask_b32_e64 v80, v80, v81, s[8:9]
	v_mul_f32_e32 v80, 0x3dd53b94, v80
	v_pk_mul_f32 v[76:77], v[80:81], v[76:77] op_sel_hi:[0,1]
	v_pk_mul_f32 v[72:73], v[80:81], v[72:73] op_sel_hi:[0,1]
	v_pk_mul_f32 v[78:79], v[80:81], v[78:79] op_sel_hi:[0,1]
	v_pk_mul_f32 v[82:83], v[80:81], v[74:75] op_sel_hi:[0,1]
	v_cvt_pk_bf16_f32 v74, v76, v77
	v_cvt_pk_bf16_f32 v75, v78, v79
	v_cvt_pk_bf16_f32 v76, v72, v73
	v_mov_b64_e32 v[72:73], s[28:29]
	v_mad_i64_i32 v[72:73], s[8:9], v92, s24, v[72:73]
	v_lshl_add_u64 v[72:73], v[140:141], 1, v[72:73]
	v_cvt_pk_bf16_f32 v77, v82, v83
	global_store_dwordx4 v[72:73], v[74:77], off
	s_and_saveexec_b64 s[8:9], s[6:7]
	s_cbranch_execz .LBB0_140
	v_mov_b32_e32 v121, v177
	v_lshlrev_b64 v[78:79], 2, v[120:121]
	v_lshl_add_u64 v[74:75], v[90:91], 0, v[78:79]
	v_lshl_add_u64 v[78:79], v[88:89], 0, v[78:79]
	v_mov_b32_e32 v74, v218
	v_mov_b32_e32 v75, v219
	v_mov_b32_e32 v76, v220
	v_mov_b32_e32 v77, v221
	s_nop 0
	v_mov_b32_e32 v82, v222
	v_mov_b32_e32 v83, v223
	v_mov_b32_e32 v84, v224
	v_mov_b32_e32 v85, v225
	v_pk_mul_f32 v[78:79], v[68:69], v[74:75]
	v_pk_mul_f32 v[86:87], v[68:69], v[82:83] op_sel:[1,0] op_sel_hi:[0,0]
	v_pk_fma_f32 v[68:69], v[68:69], v[74:75], v[86:87] op_sel_hi:[1,0,1]
	v_mov_b32_e32 v82, v75
	v_mul_f32_e32 v68, v71, v83
	v_pk_fma_f32 v[88:89], v[70:71], v[82:83], v[68:69] op_sel_hi:[1,1,0] neg_lo:[0,0,1] neg_hi:[0,0,1]
	v_mov_b32_e32 v74, v83
	v_mul_f32_e32 v68, v71, v75
	v_pk_mul_f32 v[82:83], v[64:65], v[84:85] op_sel:[1,0] op_sel_hi:[0,0]
	v_pk_fma_f32 v[74:75], v[70:71], v[74:75], v[68:69] op_sel_hi:[1,1,0]
	v_pk_mul_f32 v[70:71], v[64:65], v[76:77]
	v_pk_fma_f32 v[64:65], v[64:65], v[76:77], v[82:83] op_sel_hi:[1,0,1]
	v_mov_b32_e32 v84, v77
	v_mul_f32_e32 v64, v67, v85
	v_pk_fma_f32 v[90:91], v[66:67], v[84:85], v[64:65] op_sel_hi:[1,1,0] neg_lo:[0,0,1] neg_hi:[0,0,1]
	v_mov_b32_e32 v76, v85
	v_mul_f32_e32 v64, v67, v77
	v_pk_fma_f32 v[76:77], v[66:67], v[76:77], v[64:65] op_sel_hi:[1,1,0]
	v_sub_f32_e32 v68, v78, v86
	v_sub_f32_e32 v64, v70, v82
	v_mov_b32_e32 v70, v88
	v_mov_b32_e32 v71, v74
	v_mov_b32_e32 v66, v90
	v_mov_b32_e32 v67, v76
; __device__ __forceinline__ u32x4 pack8(f32x4 a, f32x4 b) { u32x4 r; r[0] = cvt_pk_bf16(a[0], a[1]); r[1] = cvt_pk_bf16(a[2], a[3]); r[2] = cvt_pk_bf16(b[0], b[1]); r[3] = cvt_pk_bf16(b[2], b[3]); return r; }
;     __device__ __forceinline__ void operator()(const AccT& acc, const Unit& u, int wr, int wc, int fr, int fq) const {
;     ...
;                 const int row = row0 + ai * HALF + m * 16;
;                 const f32x4 pa = *(const f32x4*)(ssp + (size_t)row * 16), pb = *(const f32x4*)(ssp + (size_t)row * 16 + 4);
;                 const float ssr = ((pa[0] + pa[1]) + (pa[2] + pa[3])) + ((pb[0] + pb[1]) + (pb[2] + pb[3]));
;                 const float sc = rsqrtf(ssr * (1.0f / 512.0f) + EPS) * (1.4426950408889634f * 0.07216878364870322f);
; #pragma unroll
;                 for (int bj = 0; bj < 2; ++bj) {
;                     const int col = colbase + bj * HALF; f32x4 v0 = acc[ai][bj][m][0], v1 = acc[ai][bj][m][1];
;                     const int d = col % 192;
;                     if (d >= 128) { const int i0 = (d - 128) >> 1;
;                         const f32x4 c4 = *(const f32x4*)(cosT + (size_t)row * 32 + i0), s4 = *(const f32x4*)(sinT + (size_t)row * 32 + i0);
;                         f32x4 o0, o1;
;                         o0[0] = v0[0] * c4[0] - v0[1] * s4[0]; o0[1] = v0[1] * c4[0] + v0[0] * s4[0];
;                         o0[2] = v0[2] * c4[1] - v0[3] * s4[1]; o0[3] = v0[3] * c4[1] + v0[2] * s4[1];
;                         o1[0] = v1[0] * c4[2] - v1[1] * s4[2]; o1[1] = v1[1] * c4[2] + v1[0] * s4[2];
;                         o1[2] = v1[2] * c4[3] - v1[3] * s4[3]; o1[3] = v1[3] * c4[3] + v1[2] * s4[3];
;                         v0 = o0; v1 = o1; }
;                     *(u32x4*)(Q + (size_t)row * NQ + col) = pack8(v0 * sc, v1 * sc); __builtin_amdgcn_sched_barrier(0);
.LBB0_140:
	s_or_b64 exec, exec, s[8:9]
	v_mov_b32_e32 v81, v80
	v_mov_b32_e32 v74, v80
	v_mov_b32_e32 v75, v80
	v_pk_mul_f32 v[70:71], v[74:75], v[70:71]
	v_pk_mul_f32 v[68:69], v[80:81], v[68:69]
	v_pk_mul_f32 v[74:75], v[74:75], v[66:67]
	v_pk_mul_f32 v[66:67], v[80:81], v[64:65]
	v_cvt_pk_bf16_f32 v64, v68, v69
	v_cvt_pk_bf16_f32 v65, v70, v71
	s_nop 0
	v_cvt_pk_bf16_f32 v66, v66, v67
	v_cvt_pk_bf16_f32 v67, v74, v75
	global_store_dwordx4 v[72:73], v[64:67], off offset:256
	v_add_u32_e32 v76, 0x80, v142
	v_ashrrev_i32_e32 v77, 31, v76
	v_readlane_b32 s8, v253, 12
	v_lshlrev_b64 v[64:65], 6, v[76:77]
	v_readlane_b32 s9, v253, 13
	v_lshlrev_b64 v[72:73], 5, v[76:77]
	v_lshlrev_b64 v[72:73], 2, v[72:73]
	v_lshl_add_u64 v[68:69], s[8:9], 0, v[64:65]
	v_mov_b32_e32 v64, 0
	v_mov_b32_e32 v65, 0
	v_mov_b32_e32 v66, 0
	v_mov_b32_e32 v67, 0
	s_nop 0
	v_mov_b32_e32 v68, v183
	v_mov_b32_e32 v69, 0
	v_mov_b32_e32 v70, 0
	v_mov_b32_e32 v71, 0
	v_readlane_b32 s8, v254, 48
	v_readlane_b32 s9, v254, 49
	s_nop 1
	v_lshl_add_u64 v[74:75], s[8:9], 0, v[72:73]
	v_readlane_b32 s8, v253, 14
	v_readlane_b32 s9, v253, 15
	s_nop 1
	v_lshl_add_u64 v[72:73], s[8:9], 0, v[72:73]
	s_and_saveexec_b64 s[8:9], vcc
	s_cbranch_execz .LBB0_142
	v_lshlrev_b64 v[82:83], 2, v[176:177]
	v_lshl_add_u64 v[78:79], v[74:75], 0, v[82:83]
	v_lshl_add_u64 v[82:83], v[72:73], 0, v[82:83]
	v_mov_b32_e32 v78, v226
	v_mov_b32_e32 v79, v227
	v_mov_b32_e32 v80, v228
	v_mov_b32_e32 v81, v229
	s_nop 0
	v_mov_b32_e32 v82, v230
	v_mov_b32_e32 v83, v231
	v_mov_b32_e32 v84, v232
	v_mov_b32_e32 v85, v233
	v_pk_mul_f32 v[86:87], v[60:61], v[78:79]
	v_pk_mul_f32 v[88:89], v[60:61], v[82:83] op_sel:[1,0] op_sel_hi:[0,0]
	v_pk_fma_f32 v[60:61], v[60:61], v[78:79], v[88:89] op_sel_hi:[1,0,1]
	v_mov_b32_e32 v82, v79
	v_mul_f32_e32 v60, v63, v83
	v_pk_fma_f32 v[90:91], v[62:63], v[82:83], v[60:61] op_sel_hi:[1,1,0] neg_lo:[0,0,1] neg_hi:[0,0,1]
	v_mov_b32_e32 v78, v83
	v_mul_f32_e32 v60, v63, v79
	v_pk_mul_f32 v[82:83], v[56:57], v[84:85] op_sel:[1,0] op_sel_hi:[0,0]
	v_pk_fma_f32 v[78:79], v[62:63], v[78:79], v[60:61] op_sel_hi:[1,1,0]
	v_pk_mul_f32 v[62:63], v[56:57], v[80:81]
	v_pk_fma_f32 v[56:57], v[56:57], v[80:81], v[82:83] op_sel_hi:[1,0,1]
	v_mov_b32_e32 v84, v81
	v_mul_f32_e32 v56, v59, v85
	v_pk_fma_f32 v[92:93], v[58:59], v[84:85], v[56:57] op_sel_hi:[1,1,0] neg_lo:[0,0,1] neg_hi:[0,0,1]
	v_mov_b32_e32 v80, v85
	v_mul_f32_e32 v56, v59, v81
	v_pk_fma_f32 v[80:81], v[58:59], v[80:81], v[56:57] op_sel_hi:[1,1,0]
	v_sub_f32_e32 v60, v86, v88
	v_sub_f32_e32 v56, v62, v82
	v_mov_b32_e32 v62, v90
	v_mov_b32_e32 v63, v78
	v_mov_b32_e32 v58, v92
	v_mov_b32_e32 v59, v80
.LBB0_142:
	s_or_b64 exec, exec, s[8:9]
	v_mov_b32_e32 v78, v68
	v_mov_b32_e32 v79, v64
	v_mov_b32_e32 v64, v69
	v_mov_b32_e32 v68, v70
	v_mov_b32_e32 v69, v66
	v_mov_b32_e32 v66, v71
	v_pk_add_f32 v[64:65], v[78:79], v[64:65]
	v_pk_add_f32 v[66:67], v[68:69], v[66:67]
	s_nop 0
	v_pk_add_f32 v[64:65], v[64:65], v[66:67]
	s_nop 0
	v_add_f32_e32 v64, v64, v65
	v_fmamk_f32 v64, v64, 0x3b000000, v252
	v_mul_f32_e32 v65, 0x4b800000, v64
	v_cmp_gt_f32_e64 s[8:9], s25, v64
	s_nop 1
	v_cndmask_b32_e64 v64, v64, v65, s[8:9]
	v_rsq_f32_e32 v64, v64
	s_nop 0
	v_mul_f32_e32 v65, 0x45800000, v64
	v_cndmask_b32_e64 v64, v64, v65, s[8:9]
	v_mul_f32_e32 v64, 0x3dd53b94, v64
	v_pk_mul_f32 v[60:61], v[64:65], v[60:61] op_sel_hi:[0,1]
	v_pk_mul_f32 v[56:57], v[64:65], v[56:57] op_sel_hi:[0,1]
	v_pk_mul_f32 v[62:63], v[64:65], v[62:63] op_sel_hi:[0,1]
	v_pk_mul_f32 v[66:67], v[64:65], v[58:59] op_sel_hi:[0,1]
	v_cvt_pk_bf16_f32 v58, v60, v61
	v_cvt_pk_bf16_f32 v59, v62, v63
	v_cvt_pk_bf16_f32 v60, v56, v57
	v_mov_b64_e32 v[56:57], s[28:29]
	v_mad_i64_i32 v[56:57], s[8:9], v76, s24, v[56:57]
	v_lshl_add_u64 v[56:57], v[140:141], 1, v[56:57]
	v_cvt_pk_bf16_f32 v61, v66, v67
	global_store_dwordx4 v[56:57], v[58:61], off
	s_and_saveexec_b64 s[8:9], s[6:7]
	s_cbranch_execz .LBB0_144
	v_mov_b32_e32 v121, v177
	v_lshlrev_b64 v[62:63], 2, v[120:121]
	v_lshl_add_u64 v[58:59], v[74:75], 0, v[62:63]
	v_lshl_add_u64 v[62:63], v[72:73], 0, v[62:63]
	v_mov_b32_e32 v58, v226
	v_mov_b32_e32 v59, v227
	v_mov_b32_e32 v60, v228
	v_mov_b32_e32 v61, v229
	s_nop 0
	v_mov_b32_e32 v66, v230
	v_mov_b32_e32 v67, v231
	v_mov_b32_e32 v68, v232
	v_mov_b32_e32 v69, v233
	v_pk_mul_f32 v[62:63], v[52:53], v[58:59]
	v_pk_mul_f32 v[70:71], v[52:53], v[66:67] op_sel:[1,0] op_sel_hi:[0,0]
	v_pk_fma_f32 v[52:53], v[52:53], v[58:59], v[70:71] op_sel_hi:[1,0,1]
	v_mov_b32_e32 v66, v59
	v_mul_f32_e32 v52, v55, v67
	v_pk_fma_f32 v[72:73], v[54:55], v[66:67], v[52:53] op_sel_hi:[1,1,0] neg_lo:[0,0,1] neg_hi:[0,0,1]
	v_mov_b32_e32 v58, v67
	v_mul_f32_e32 v52, v55, v59
	v_pk_mul_f32 v[66:67], v[48:49], v[68:69] op_sel:[1,0] op_sel_hi:[0,0]
	v_pk_fma_f32 v[58:59], v[54:55], v[58:59], v[52:53] op_sel_hi:[1,1,0]
	v_pk_mul_f32 v[54:55], v[48:49], v[60:61]
	v_pk_fma_f32 v[48:49], v[48:49], v[60:61], v[66:67] op_sel_hi:[1,0,1]
	v_mov_b32_e32 v68, v61
	v_mul_f32_e32 v48, v51, v69
	v_pk_fma_f32 v[74:75], v[50:51], v[68:69], v[48:49] op_sel_hi:[1,1,0] neg_lo:[0,0,1] neg_hi:[0,0,1]
	v_mov_b32_e32 v60, v69
	v_mul_f32_e32 v48, v51, v61
	v_pk_fma_f32 v[60:61], v[50:51], v[60:61], v[48:49] op_sel_hi:[1,1,0]
	v_sub_f32_e32 v52, v62, v70
	v_sub_f32_e32 v48, v54, v66
	v_mov_b32_e32 v54, v72
	v_mov_b32_e32 v55, v58
	v_mov_b32_e32 v50, v74
	v_mov_b32_e32 v51, v60
; __device__ __forceinline__ u32x4 pack8(f32x4 a, f32x4 b) { u32x4 r; r[0] = cvt_pk_bf16(a[0], a[1]); r[1] = cvt_pk_bf16(a[2], a[3]); r[2] = cvt_pk_bf16(b[0], b[1]); r[3] = cvt_pk_bf16(b[2], b[3]); return r; }
;     __device__ __forceinline__ void operator()(const AccT& acc, const Unit& u, int wr, int wc, int fr, int fq) const {
;     ...
;                 const int row = row0 + ai * HALF + m * 16;
;                 const f32x4 pa = *(const f32x4*)(ssp + (size_t)row * 16), pb = *(const f32x4*)(ssp + (size_t)row * 16 + 4);
;                 const float ssr = ((pa[0] + pa[1]) + (pa[2] + pa[3])) + ((pb[0] + pb[1]) + (pb[2] + pb[3]));
;                 const float sc = rsqrtf(ssr * (1.0f / 512.0f) + EPS) * (1.4426950408889634f * 0.07216878364870322f);
; #pragma unroll
;                 for (int bj = 0; bj < 2; ++bj) {
;                     const int col = colbase + bj * HALF; f32x4 v0 = acc[ai][bj][m][0], v1 = acc[ai][bj][m][1];
;                     const int d = col % 192;
;                     if (d >= 128) { const int i0 = (d - 128) >> 1;
;                         const f32x4 c4 = *(const f32x4*)(cosT + (size_t)row * 32 + i0), s4 = *(const f32x4*)(sinT + (size_t)row * 32 + i0);
;                         f32x4 o0, o1;
;                         o0[0] = v0[0] * c4[0] - v0[1] * s4[0]; o0[1] = v0[1] * c4[0] + v0[0] * s4[0];
;                         o0[2] = v0[2] * c4[1] - v0[3] * s4[1]; o0[3] = v0[3] * c4[1] + v0[2] * s4[1];
;                         o1[0] = v1[0] * c4[2] - v1[1] * s4[2]; o1[1] = v1[1] * c4[2] + v1[0] * s4[2];
;                         o1[2] = v1[2] * c4[3] - v1[3] * s4[3]; o1[3] = v1[3] * c4[3] + v1[2] * s4[3];
;                         v0 = o0; v1 = o1; }
;                     *(u32x4*)(Q + (size_t)row * NQ + col) = pack8(v0 * sc, v1 * sc); __builtin_amdgcn_sched_barrier(0);
.LBB0_144:
	s_or_b64 exec, exec, s[8:9]
	v_mov_b32_e32 v65, v64
	v_mov_b32_e32 v58, v64
	v_mov_b32_e32 v59, v64
	v_pk_mul_f32 v[54:55], v[58:59], v[54:55]
	v_pk_mul_f32 v[52:53], v[64:65], v[52:53]
	v_pk_mul_f32 v[58:59], v[58:59], v[50:51]
	v_pk_mul_f32 v[50:51], v[64:65], v[48:49]
	v_cvt_pk_bf16_f32 v48, v52, v53
	v_cvt_pk_bf16_f32 v49, v54, v55
	s_nop 0
	v_cvt_pk_bf16_f32 v50, v50, v51
	v_cvt_pk_bf16_f32 v51, v58, v59
	global_store_dwordx4 v[56:57], v[48:51], off offset:256
	v_add_u32_e32 v60, 0x90, v142
	v_ashrrev_i32_e32 v61, 31, v60
	v_readlane_b32 s8, v253, 12
	v_lshlrev_b64 v[48:49], 6, v[60:61]
	v_readlane_b32 s9, v253, 13
	v_lshlrev_b64 v[56:57], 5, v[60:61]
	v_lshlrev_b64 v[56:57], 2, v[56:57]
	v_lshl_add_u64 v[52:53], s[8:9], 0, v[48:49]
	v_mov_b32_e32 v48, 0
	v_mov_b32_e32 v49, 0
	v_mov_b32_e32 v50, 0
	v_mov_b32_e32 v51, 0
	s_nop 0
	v_mov_b32_e32 v52, v184
	v_mov_b32_e32 v53, 0
	v_mov_b32_e32 v54, 0
	v_mov_b32_e32 v55, 0
	v_readlane_b32 s8, v254, 48
	v_readlane_b32 s9, v254, 49
	s_nop 1
	v_lshl_add_u64 v[58:59], s[8:9], 0, v[56:57]
	v_readlane_b32 s8, v253, 14
	v_readlane_b32 s9, v253, 15
	s_nop 1
	v_lshl_add_u64 v[56:57], s[8:9], 0, v[56:57]
	s_and_saveexec_b64 s[8:9], vcc
	s_cbranch_execz .LBB0_146
	v_lshlrev_b64 v[66:67], 2, v[176:177]
	v_lshl_add_u64 v[62:63], v[58:59], 0, v[66:67]
	v_lshl_add_u64 v[66:67], v[56:57], 0, v[66:67]
	v_mov_b32_e32 v62, v234
	v_mov_b32_e32 v63, v235
	v_mov_b32_e32 v64, v236
	v_mov_b32_e32 v65, v237
	s_nop 0
	v_mov_b32_e32 v66, v238
	v_mov_b32_e32 v67, v239
	v_mov_b32_e32 v68, v240
	v_mov_b32_e32 v69, v241
	v_pk_mul_f32 v[70:71], v[44:45], v[62:63]
	v_pk_mul_f32 v[72:73], v[44:45], v[66:67] op_sel:[1,0] op_sel_hi:[0,0]
	v_pk_fma_f32 v[44:45], v[44:45], v[62:63], v[72:73] op_sel_hi:[1,0,1]
	v_mov_b32_e32 v66, v63
	v_mul_f32_e32 v44, v47, v67
	v_pk_fma_f32 v[74:75], v[46:47], v[66:67], v[44:45] op_sel_hi:[1,1,0] neg_lo:[0,0,1] neg_hi:[0,0,1]
	v_mov_b32_e32 v62, v67
	v_mul_f32_e32 v44, v47, v63
	v_pk_mul_f32 v[66:67], v[40:41], v[68:69] op_sel:[1,0] op_sel_hi:[0,0]
	v_pk_fma_f32 v[62:63], v[46:47], v[62:63], v[44:45] op_sel_hi:[1,1,0]
	v_pk_mul_f32 v[46:47], v[40:41], v[64:65]
	v_pk_fma_f32 v[40:41], v[40:41], v[64:65], v[66:67] op_sel_hi:[1,0,1]
	v_mov_b32_e32 v68, v65
	v_mul_f32_e32 v40, v43, v69
	v_pk_fma_f32 v[76:77], v[42:43], v[68:69], v[40:41] op_sel_hi:[1,1,0] neg_lo:[0,0,1] neg_hi:[0,0,1]
	v_mov_b32_e32 v64, v69
	v_mul_f32_e32 v40, v43, v65
	v_pk_fma_f32 v[64:65], v[42:43], v[64:65], v[40:41] op_sel_hi:[1,1,0]
	v_sub_f32_e32 v44, v70, v72
	v_sub_f32_e32 v40, v46, v66
	v_mov_b32_e32 v46, v74
	v_mov_b32_e32 v47, v62
	v_mov_b32_e32 v42, v76
	v_mov_b32_e32 v43, v64
.LBB0_146:
	s_or_b64 exec, exec, s[8:9]
	v_mov_b32_e32 v62, v52
	v_mov_b32_e32 v63, v48
	v_mov_b32_e32 v48, v53
	v_mov_b32_e32 v52, v54
	v_mov_b32_e32 v53, v50
	v_mov_b32_e32 v50, v55
	v_pk_add_f32 v[48:49], v[62:63], v[48:49]
	v_pk_add_f32 v[50:51], v[52:53], v[50:51]
	s_nop 0
	v_pk_add_f32 v[48:49], v[48:49], v[50:51]
	s_nop 0
	v_add_f32_e32 v48, v48, v49
	v_fmamk_f32 v48, v48, 0x3b000000, v252
	v_mul_f32_e32 v49, 0x4b800000, v48
	v_cmp_gt_f32_e64 s[8:9], s25, v48
	s_nop 1
	v_cndmask_b32_e64 v48, v48, v49, s[8:9]
	v_rsq_f32_e32 v48, v48
	s_nop 0
	v_mul_f32_e32 v49, 0x45800000, v48
	v_cndmask_b32_e64 v48, v48, v49, s[8:9]
	v_mul_f32_e32 v48, 0x3dd53b94, v48
	v_pk_mul_f32 v[44:45], v[48:49], v[44:45] op_sel_hi:[0,1]
	v_pk_mul_f32 v[40:41], v[48:49], v[40:41] op_sel_hi:[0,1]
	v_pk_mul_f32 v[46:47], v[48:49], v[46:47] op_sel_hi:[0,1]
	v_pk_mul_f32 v[50:51], v[48:49], v[42:43] op_sel_hi:[0,1]
	v_cvt_pk_bf16_f32 v42, v44, v45
	v_cvt_pk_bf16_f32 v43, v46, v47
	v_cvt_pk_bf16_f32 v44, v40, v41
	v_mov_b64_e32 v[40:41], s[28:29]
	v_mad_i64_i32 v[40:41], s[8:9], v60, s24, v[40:41]
	v_lshl_add_u64 v[40:41], v[140:141], 1, v[40:41]
	v_cvt_pk_bf16_f32 v45, v50, v51
	global_store_dwordx4 v[40:41], v[42:45], off
	s_and_saveexec_b64 s[8:9], s[6:7]
	s_cbranch_execz .LBB0_148
	v_mov_b32_e32 v121, v177
	v_lshlrev_b64 v[46:47], 2, v[120:121]
	v_lshl_add_u64 v[42:43], v[58:59], 0, v[46:47]
	v_lshl_add_u64 v[46:47], v[56:57], 0, v[46:47]
	v_mov_b32_e32 v42, v234
	v_mov_b32_e32 v43, v235
	v_mov_b32_e32 v44, v236
	v_mov_b32_e32 v45, v237
	s_nop 0
	v_mov_b32_e32 v50, v238
	v_mov_b32_e32 v51, v239
	v_mov_b32_e32 v52, v240
	v_mov_b32_e32 v53, v241
	v_pk_mul_f32 v[46:47], v[36:37], v[42:43]
	v_pk_mul_f32 v[54:55], v[36:37], v[50:51] op_sel:[1,0] op_sel_hi:[0,0]
	v_pk_fma_f32 v[36:37], v[36:37], v[42:43], v[54:55] op_sel_hi:[1,0,1]
	v_mov_b32_e32 v50, v43
	v_mul_f32_e32 v36, v39, v51
	v_pk_fma_f32 v[56:57], v[38:39], v[50:51], v[36:37] op_sel_hi:[1,1,0] neg_lo:[0,0,1] neg_hi:[0,0,1]
	v_mov_b32_e32 v42, v51
	v_mul_f32_e32 v36, v39, v43
	v_pk_mul_f32 v[50:51], v[32:33], v[52:53] op_sel:[1,0] op_sel_hi:[0,0]
	v_pk_fma_f32 v[42:43], v[38:39], v[42:43], v[36:37] op_sel_hi:[1,1,0]
	v_pk_mul_f32 v[38:39], v[32:33], v[44:45]
	v_pk_fma_f32 v[32:33], v[32:33], v[44:45], v[50:51] op_sel_hi:[1,0,1]
	v_mov_b32_e32 v52, v45
	v_mul_f32_e32 v32, v35, v53
	v_pk_fma_f32 v[58:59], v[34:35], v[52:53], v[32:33] op_sel_hi:[1,1,0] neg_lo:[0,0,1] neg_hi:[0,0,1]
	v_mov_b32_e32 v44, v53
	v_mul_f32_e32 v32, v35, v45
	v_pk_fma_f32 v[44:45], v[34:35], v[44:45], v[32:33] op_sel_hi:[1,1,0]
	v_sub_f32_e32 v36, v46, v54
	v_sub_f32_e32 v32, v38, v50
	v_mov_b32_e32 v38, v56
	v_mov_b32_e32 v39, v42
	v_mov_b32_e32 v34, v58
	v_mov_b32_e32 v35, v44
; __device__ __forceinline__ u32x4 pack8(f32x4 a, f32x4 b) { u32x4 r; r[0] = cvt_pk_bf16(a[0], a[1]); r[1] = cvt_pk_bf16(a[2], a[3]); r[2] = cvt_pk_bf16(b[0], b[1]); r[3] = cvt_pk_bf16(b[2], b[3]); return r; }
;     __device__ __forceinline__ void operator()(const AccT& acc, const Unit& u, int wr, int wc, int fr, int fq) const {
;     ...
;                 const int row = row0 + ai * HALF + m * 16;
;                 const f32x4 pa = *(const f32x4*)(ssp + (size_t)row * 16), pb = *(const f32x4*)(ssp + (size_t)row * 16 + 4);
;                 const float ssr = ((pa[0] + pa[1]) + (pa[2] + pa[3])) + ((pb[0] + pb[1]) + (pb[2] + pb[3]));
;                 const float sc = rsqrtf(ssr * (1.0f / 512.0f) + EPS) * (1.4426950408889634f * 0.07216878364870322f);
; #pragma unroll
;                 for (int bj = 0; bj < 2; ++bj) {
;                     const int col = colbase + bj * HALF; f32x4 v0 = acc[ai][bj][m][0], v1 = acc[ai][bj][m][1];
;                     const int d = col % 192;
;                     if (d >= 128) { const int i0 = (d - 128) >> 1;
;                         const f32x4 c4 = *(const f32x4*)(cosT + (size_t)row * 32 + i0), s4 = *(const f32x4*)(sinT + (size_t)row * 32 + i0);
;                         f32x4 o0, o1;
;                         o0[0] = v0[0] * c4[0] - v0[1] * s4[0]; o0[1] = v0[1] * c4[0] + v0[0] * s4[0];
;                         o0[2] = v0[2] * c4[1] - v0[3] * s4[1]; o0[3] = v0[3] * c4[1] + v0[2] * s4[1];
;                         o1[0] = v1[0] * c4[2] - v1[1] * s4[2]; o1[1] = v1[1] * c4[2] + v1[0] * s4[2];
;                         o1[2] = v1[2] * c4[3] - v1[3] * s4[3]; o1[3] = v1[3] * c4[3] + v1[2] * s4[3];
;                         v0 = o0; v1 = o1; }
;                     *(u32x4*)(Q + (size_t)row * NQ + col) = pack8(v0 * sc, v1 * sc); __builtin_amdgcn_sched_barrier(0);
.LBB0_148:
	s_or_b64 exec, exec, s[8:9]
	v_mov_b32_e32 v49, v48
	v_mov_b32_e32 v42, v48
	v_mov_b32_e32 v43, v48
	v_pk_mul_f32 v[38:39], v[42:43], v[38:39]
	v_pk_mul_f32 v[36:37], v[48:49], v[36:37]
	v_pk_mul_f32 v[42:43], v[42:43], v[34:35]
	v_pk_mul_f32 v[34:35], v[48:49], v[32:33]
	v_cvt_pk_bf16_f32 v32, v36, v37
	v_cvt_pk_bf16_f32 v33, v38, v39
	s_nop 0
	v_cvt_pk_bf16_f32 v34, v34, v35
	v_cvt_pk_bf16_f32 v35, v42, v43
	global_store_dwordx4 v[40:41], v[32:35], off offset:256
	v_add_u32_e32 v44, 0xa0, v142
	v_ashrrev_i32_e32 v45, 31, v44
	v_readlane_b32 s8, v253, 12
	v_lshlrev_b64 v[32:33], 6, v[44:45]
	v_readlane_b32 s9, v253, 13
	v_lshlrev_b64 v[40:41], 5, v[44:45]
	v_lshlrev_b64 v[40:41], 2, v[40:41]
	v_lshl_add_u64 v[36:37], s[8:9], 0, v[32:33]
	v_mov_b32_e32 v32, 0
	v_mov_b32_e32 v33, 0
	v_mov_b32_e32 v34, 0
	v_mov_b32_e32 v35, 0
	s_nop 0
	v_mov_b32_e32 v36, v185
	v_mov_b32_e32 v37, 0
	v_mov_b32_e32 v38, 0
	v_mov_b32_e32 v39, 0
	v_readlane_b32 s8, v254, 48
	v_readlane_b32 s9, v254, 49
	s_nop 1
	v_lshl_add_u64 v[42:43], s[8:9], 0, v[40:41]
	v_readlane_b32 s8, v253, 14
	v_readlane_b32 s9, v253, 15
	s_nop 1
	v_lshl_add_u64 v[40:41], s[8:9], 0, v[40:41]
	s_and_saveexec_b64 s[8:9], vcc
	s_cbranch_execz .LBB0_150
	v_lshlrev_b64 v[50:51], 2, v[176:177]
	v_lshl_add_u64 v[46:47], v[42:43], 0, v[50:51]
	v_lshl_add_u64 v[50:51], v[40:41], 0, v[50:51]
	v_mov_b32_e32 v46, v242
	v_mov_b32_e32 v47, v243
	v_mov_b32_e32 v48, v244
	v_mov_b32_e32 v49, v245
	s_nop 0
	v_mov_b32_e32 v50, v246
	v_mov_b32_e32 v51, v247
	v_mov_b32_e32 v52, v248
	v_mov_b32_e32 v53, v249
	v_pk_mul_f32 v[54:55], v[28:29], v[46:47]
	v_pk_mul_f32 v[56:57], v[28:29], v[50:51] op_sel:[1,0] op_sel_hi:[0,0]
	v_pk_fma_f32 v[28:29], v[28:29], v[46:47], v[56:57] op_sel_hi:[1,0,1]
	v_mov_b32_e32 v50, v47
	v_mul_f32_e32 v28, v31, v51
	v_pk_fma_f32 v[58:59], v[30:31], v[50:51], v[28:29] op_sel_hi:[1,1,0] neg_lo:[0,0,1] neg_hi:[0,0,1]
	v_mov_b32_e32 v46, v51
	v_mul_f32_e32 v28, v31, v47
	v_pk_mul_f32 v[50:51], v[24:25], v[52:53] op_sel:[1,0] op_sel_hi:[0,0]
	v_pk_fma_f32 v[46:47], v[30:31], v[46:47], v[28:29] op_sel_hi:[1,1,0]
	v_pk_mul_f32 v[30:31], v[24:25], v[48:49]
	v_pk_fma_f32 v[24:25], v[24:25], v[48:49], v[50:51] op_sel_hi:[1,0,1]
	v_mov_b32_e32 v52, v49
	v_mul_f32_e32 v24, v27, v53
	v_pk_fma_f32 v[60:61], v[26:27], v[52:53], v[24:25] op_sel_hi:[1,1,0] neg_lo:[0,0,1] neg_hi:[0,0,1]
	v_mov_b32_e32 v48, v53
	v_mul_f32_e32 v24, v27, v49
	v_pk_fma_f32 v[48:49], v[26:27], v[48:49], v[24:25] op_sel_hi:[1,1,0]
	v_sub_f32_e32 v28, v54, v56
	v_sub_f32_e32 v24, v30, v50
	v_mov_b32_e32 v30, v58
	v_mov_b32_e32 v31, v46
	v_mov_b32_e32 v26, v60
	v_mov_b32_e32 v27, v48
.LBB0_150:
	s_or_b64 exec, exec, s[8:9]
	v_mov_b32_e32 v46, v36
	v_mov_b32_e32 v47, v32
	v_mov_b32_e32 v32, v37
	v_mov_b32_e32 v36, v38
	v_mov_b32_e32 v37, v34
	v_mov_b32_e32 v34, v39
	v_pk_add_f32 v[32:33], v[46:47], v[32:33]
	v_pk_add_f32 v[34:35], v[36:37], v[34:35]
	s_nop 0
	v_pk_add_f32 v[32:33], v[32:33], v[34:35]
	s_nop 0
	v_add_f32_e32 v32, v32, v33
	v_fmamk_f32 v32, v32, 0x3b000000, v252
	v_mul_f32_e32 v33, 0x4b800000, v32
	v_cmp_gt_f32_e64 s[8:9], s25, v32
	s_nop 1
	v_cndmask_b32_e64 v32, v32, v33, s[8:9]
	v_rsq_f32_e32 v32, v32
	s_nop 0
	v_mul_f32_e32 v33, 0x45800000, v32
	v_cndmask_b32_e64 v32, v32, v33, s[8:9]
	v_mul_f32_e32 v32, 0x3dd53b94, v32
	v_pk_mul_f32 v[28:29], v[32:33], v[28:29] op_sel_hi:[0,1]
	v_pk_mul_f32 v[24:25], v[32:33], v[24:25] op_sel_hi:[0,1]
	v_pk_mul_f32 v[30:31], v[32:33], v[30:31] op_sel_hi:[0,1]
	v_pk_mul_f32 v[34:35], v[32:33], v[26:27] op_sel_hi:[0,1]
	v_cvt_pk_bf16_f32 v26, v28, v29
	v_cvt_pk_bf16_f32 v27, v30, v31
	v_cvt_pk_bf16_f32 v28, v24, v25
	v_mov_b64_e32 v[24:25], s[28:29]
	v_mad_i64_i32 v[24:25], s[8:9], v44, s24, v[24:25]
	v_lshl_add_u64 v[24:25], v[140:141], 1, v[24:25]
	v_cvt_pk_bf16_f32 v29, v34, v35
	global_store_dwordx4 v[24:25], v[26:29], off
	s_and_saveexec_b64 s[8:9], s[6:7]
	s_cbranch_execz .LBB0_152
	v_mov_b32_e32 v121, v177
	v_lshlrev_b64 v[30:31], 2, v[120:121]
	v_lshl_add_u64 v[26:27], v[42:43], 0, v[30:31]
	v_lshl_add_u64 v[30:31], v[40:41], 0, v[30:31]
	v_mov_b32_e32 v26, v242
	v_mov_b32_e32 v27, v243
	v_mov_b32_e32 v28, v244
	v_mov_b32_e32 v29, v245
	s_nop 0
	v_mov_b32_e32 v34, v246
	v_mov_b32_e32 v35, v247
	v_mov_b32_e32 v36, v248
	v_mov_b32_e32 v37, v249
	v_pk_mul_f32 v[30:31], v[20:21], v[26:27]
	v_pk_mul_f32 v[38:39], v[20:21], v[34:35] op_sel:[1,0] op_sel_hi:[0,0]
	v_pk_fma_f32 v[20:21], v[20:21], v[26:27], v[38:39] op_sel_hi:[1,0,1]
	v_mov_b32_e32 v34, v27
	v_mul_f32_e32 v20, v23, v35
	v_pk_fma_f32 v[40:41], v[22:23], v[34:35], v[20:21] op_sel_hi:[1,1,0] neg_lo:[0,0,1] neg_hi:[0,0,1]
	v_mov_b32_e32 v26, v35
	v_mul_f32_e32 v20, v23, v27
	v_pk_mul_f32 v[34:35], v[16:17], v[36:37] op_sel:[1,0] op_sel_hi:[0,0]
	v_pk_fma_f32 v[26:27], v[22:23], v[26:27], v[20:21] op_sel_hi:[1,1,0]
	v_pk_mul_f32 v[22:23], v[16:17], v[28:29]
	v_pk_fma_f32 v[16:17], v[16:17], v[28:29], v[34:35] op_sel_hi:[1,0,1]
	v_mov_b32_e32 v36, v29
	v_mul_f32_e32 v16, v19, v37
	v_pk_fma_f32 v[42:43], v[18:19], v[36:37], v[16:17] op_sel_hi:[1,1,0] neg_lo:[0,0,1] neg_hi:[0,0,1]
	v_mov_b32_e32 v28, v37
	v_mul_f32_e32 v16, v19, v29
	v_pk_fma_f32 v[28:29], v[18:19], v[28:29], v[16:17] op_sel_hi:[1,1,0]
	v_sub_f32_e32 v20, v30, v38
	v_sub_f32_e32 v16, v22, v34
	v_mov_b32_e32 v22, v40
	v_mov_b32_e32 v23, v26
	v_mov_b32_e32 v18, v42
	v_mov_b32_e32 v19, v28
; __device__ __forceinline__ u32x4 pack8(f32x4 a, f32x4 b) { u32x4 r; r[0] = cvt_pk_bf16(a[0], a[1]); r[1] = cvt_pk_bf16(a[2], a[3]); r[2] = cvt_pk_bf16(b[0], b[1]); r[3] = cvt_pk_bf16(b[2], b[3]); return r; }
;     __device__ __forceinline__ void operator()(const AccT& acc, const Unit& u, int wr, int wc, int fr, int fq) const {
;     ...
;                 const int row = row0 + ai * HALF + m * 16;
;                 const f32x4 pa = *(const f32x4*)(ssp + (size_t)row * 16), pb = *(const f32x4*)(ssp + (size_t)row * 16 + 4);
;                 const float ssr = ((pa[0] + pa[1]) + (pa[2] + pa[3])) + ((pb[0] + pb[1]) + (pb[2] + pb[3]));
;                 const float sc = rsqrtf(ssr * (1.0f / 512.0f) + EPS) * (1.4426950408889634f * 0.07216878364870322f);
; #pragma unroll
;                 for (int bj = 0; bj < 2; ++bj) {
;                     const int col = colbase + bj * HALF; f32x4 v0 = acc[ai][bj][m][0], v1 = acc[ai][bj][m][1];
;                     const int d = col % 192;
;                     if (d >= 128) { const int i0 = (d - 128) >> 1;
;                         const f32x4 c4 = *(const f32x4*)(cosT + (size_t)row * 32 + i0), s4 = *(const f32x4*)(sinT + (size_t)row * 32 + i0);
;                         f32x4 o0, o1;
;                         o0[0] = v0[0] * c4[0] - v0[1] * s4[0]; o0[1] = v0[1] * c4[0] + v0[0] * s4[0];
;                         o0[2] = v0[2] * c4[1] - v0[3] * s4[1]; o0[3] = v0[3] * c4[1] + v0[2] * s4[1];
;                         o1[0] = v1[0] * c4[2] - v1[1] * s4[2]; o1[1] = v1[1] * c4[2] + v1[0] * s4[2];
;                         o1[2] = v1[2] * c4[3] - v1[3] * s4[3]; o1[3] = v1[3] * c4[3] + v1[2] * s4[3];
;                         v0 = o0; v1 = o1; }
;                     *(u32x4*)(Q + (size_t)row * NQ + col) = pack8(v0 * sc, v1 * sc); __builtin_amdgcn_sched_barrier(0);
.LBB0_152:
	s_or_b64 exec, exec, s[8:9]
	v_mov_b32_e32 v33, v32
	v_mov_b32_e32 v26, v32
	v_mov_b32_e32 v27, v32
	v_pk_mul_f32 v[22:23], v[26:27], v[22:23]
	v_pk_mul_f32 v[20:21], v[32:33], v[20:21]
	v_pk_mul_f32 v[26:27], v[26:27], v[18:19]
	v_pk_mul_f32 v[18:19], v[32:33], v[16:17]
	v_cvt_pk_bf16_f32 v16, v20, v21
	v_cvt_pk_bf16_f32 v17, v22, v23
	s_nop 0
	v_cvt_pk_bf16_f32 v18, v18, v19
	v_cvt_pk_bf16_f32 v19, v26, v27
	global_store_dwordx4 v[24:25], v[16:19], off offset:256
	v_add_u32_e32 v28, 0xb0, v142
	v_ashrrev_i32_e32 v29, 31, v28
	v_readlane_b32 s8, v253, 12
	v_lshlrev_b64 v[16:17], 6, v[28:29]
	v_readlane_b32 s9, v253, 13
	v_lshlrev_b64 v[24:25], 5, v[28:29]
	v_lshlrev_b64 v[24:25], 2, v[24:25]
	v_lshl_add_u64 v[20:21], s[8:9], 0, v[16:17]
	v_mov_b32_e32 v16, 0
	v_mov_b32_e32 v17, 0
	v_mov_b32_e32 v18, 0
	v_mov_b32_e32 v19, 0
	s_nop 0
	v_mov_b32_e32 v20, v186
	v_mov_b32_e32 v21, 0
	v_mov_b32_e32 v22, 0
	v_mov_b32_e32 v23, 0
	v_readlane_b32 s8, v254, 48
	v_readlane_b32 s9, v254, 49
	s_nop 1
	v_lshl_add_u64 v[26:27], s[8:9], 0, v[24:25]
	v_readlane_b32 s8, v253, 14
	v_readlane_b32 s9, v253, 15
	s_nop 1
	v_lshl_add_u64 v[24:25], s[8:9], 0, v[24:25]
	s_and_saveexec_b64 s[8:9], vcc
	s_cbranch_execz .LBB0_154
	v_lshlrev_b64 v[34:35], 2, v[176:177]
	v_lshl_add_u64 v[30:31], v[26:27], 0, v[34:35]
	v_lshl_add_u64 v[34:35], v[24:25], 0, v[34:35]
	v_mov_b32_e32 v30, v168
	v_mov_b32_e32 v31, v169
	v_mov_b32_e32 v32, v170
	v_mov_b32_e32 v33, v171
	s_nop 0
	v_mov_b32_e32 v34, v172
	v_mov_b32_e32 v35, v173
	v_mov_b32_e32 v36, v174
	v_mov_b32_e32 v37, v175
	v_pk_mul_f32 v[38:39], v[12:13], v[30:31]
	v_pk_mul_f32 v[40:41], v[12:13], v[34:35] op_sel:[1,0] op_sel_hi:[0,0]
	v_pk_fma_f32 v[12:13], v[12:13], v[30:31], v[40:41] op_sel_hi:[1,0,1]
	v_mov_b32_e32 v34, v31
	v_mul_f32_e32 v12, v15, v35
	v_pk_fma_f32 v[42:43], v[14:15], v[34:35], v[12:13] op_sel_hi:[1,1,0] neg_lo:[0,0,1] neg_hi:[0,0,1]
	v_mov_b32_e32 v30, v35
	v_mul_f32_e32 v12, v15, v31
	v_pk_mul_f32 v[34:35], v[8:9], v[36:37] op_sel:[1,0] op_sel_hi:[0,0]
	v_pk_fma_f32 v[30:31], v[14:15], v[30:31], v[12:13] op_sel_hi:[1,1,0]
	v_pk_mul_f32 v[14:15], v[8:9], v[32:33]
	v_pk_fma_f32 v[8:9], v[8:9], v[32:33], v[34:35] op_sel_hi:[1,0,1]
	v_mov_b32_e32 v36, v33
	v_mul_f32_e32 v8, v11, v37
	v_pk_fma_f32 v[44:45], v[10:11], v[36:37], v[8:9] op_sel_hi:[1,1,0] neg_lo:[0,0,1] neg_hi:[0,0,1]
	v_mov_b32_e32 v32, v37
	v_mul_f32_e32 v8, v11, v33
	v_pk_fma_f32 v[32:33], v[10:11], v[32:33], v[8:9] op_sel_hi:[1,1,0]
	v_sub_f32_e32 v12, v38, v40
	v_sub_f32_e32 v8, v14, v34
	v_mov_b32_e32 v14, v42
	v_mov_b32_e32 v15, v30
	v_mov_b32_e32 v10, v44
	v_mov_b32_e32 v11, v32
.LBB0_154:
	s_or_b64 exec, exec, s[8:9]
	v_mov_b32_e32 v30, v20
	v_mov_b32_e32 v31, v16
	v_mov_b32_e32 v16, v21
	v_mov_b32_e32 v20, v22
	v_mov_b32_e32 v21, v18
	v_mov_b32_e32 v18, v23
	v_pk_add_f32 v[16:17], v[30:31], v[16:17]
	v_pk_add_f32 v[18:19], v[20:21], v[18:19]
	s_nop 0
	v_pk_add_f32 v[16:17], v[16:17], v[18:19]
	s_nop 0
	v_add_f32_e32 v16, v16, v17
	v_fmamk_f32 v16, v16, 0x3b000000, v252
	v_mul_f32_e32 v17, 0x4b800000, v16
	v_cmp_gt_f32_e32 vcc, s25, v16
	s_nop 1
	v_cndmask_b32_e32 v16, v16, v17, vcc
	v_rsq_f32_e32 v16, v16
	s_nop 0
	v_mul_f32_e32 v17, 0x45800000, v16
	v_cndmask_b32_e32 v16, v16, v17, vcc
	v_mul_f32_e32 v16, 0x3dd53b94, v16
	v_pk_mul_f32 v[12:13], v[16:17], v[12:13] op_sel_hi:[0,1]
	v_pk_mul_f32 v[8:9], v[16:17], v[8:9] op_sel_hi:[0,1]
	v_pk_mul_f32 v[14:15], v[16:17], v[14:15] op_sel_hi:[0,1]
	v_pk_mul_f32 v[18:19], v[16:17], v[10:11] op_sel_hi:[0,1]
	v_cvt_pk_bf16_f32 v10, v12, v13
	v_cvt_pk_bf16_f32 v11, v14, v15
	v_cvt_pk_bf16_f32 v12, v8, v9
	v_mov_b64_e32 v[8:9], s[28:29]
	v_mad_i64_i32 v[8:9], s[8:9], v28, s24, v[8:9]
	v_lshl_add_u64 v[8:9], v[140:141], 1, v[8:9]
	v_cvt_pk_bf16_f32 v13, v18, v19
	global_store_dwordx4 v[8:9], v[10:13], off
	s_and_saveexec_b64 s[8:9], s[6:7]
	s_cbranch_execz .LBB0_119
	v_mov_b32_e32 v121, v177
	v_lshlrev_b64 v[14:15], 2, v[120:121]
	v_lshl_add_u64 v[10:11], v[26:27], 0, v[14:15]
	v_lshl_add_u64 v[14:15], v[24:25], 0, v[14:15]
	v_mov_b32_e32 v10, v168
	v_mov_b32_e32 v11, v169
	v_mov_b32_e32 v12, v170
	v_mov_b32_e32 v13, v171
	s_nop 0
	v_mov_b32_e32 v18, v172
	v_mov_b32_e32 v19, v173
	v_mov_b32_e32 v20, v174
	v_mov_b32_e32 v21, v175
	v_pk_mul_f32 v[14:15], v[4:5], v[10:11]
	v_pk_mul_f32 v[22:23], v[4:5], v[18:19] op_sel:[1,0] op_sel_hi:[0,0]
	v_pk_fma_f32 v[4:5], v[4:5], v[10:11], v[22:23] op_sel_hi:[1,0,1]
	v_mov_b32_e32 v18, v11
	v_mul_f32_e32 v4, v7, v19
	v_pk_fma_f32 v[24:25], v[6:7], v[18:19], v[4:5] op_sel_hi:[1,1,0] neg_lo:[0,0,1] neg_hi:[0,0,1]
	v_mov_b32_e32 v10, v19
	v_mul_f32_e32 v4, v7, v11
	v_pk_mul_f32 v[18:19], v[0:1], v[20:21] op_sel:[1,0] op_sel_hi:[0,0]
	v_pk_fma_f32 v[10:11], v[6:7], v[10:11], v[4:5] op_sel_hi:[1,1,0]
	v_pk_mul_f32 v[6:7], v[0:1], v[12:13]
	v_pk_fma_f32 v[0:1], v[0:1], v[12:13], v[18:19] op_sel_hi:[1,0,1]
	v_mov_b32_e32 v20, v13
	v_mul_f32_e32 v0, v3, v21
	v_pk_fma_f32 v[26:27], v[2:3], v[20:21], v[0:1] op_sel_hi:[1,1,0] neg_lo:[0,0,1] neg_hi:[0,0,1]
	v_mov_b32_e32 v12, v21
	v_mul_f32_e32 v0, v3, v13
	v_pk_fma_f32 v[12:13], v[2:3], v[12:13], v[0:1] op_sel_hi:[1,1,0]
	v_sub_f32_e32 v4, v14, v22
	v_sub_f32_e32 v0, v6, v18
	v_mov_b32_e32 v6, v24
	v_mov_b32_e32 v7, v10
	v_mov_b32_e32 v2, v26
	v_mov_b32_e32 v3, v12
	s_branch .LBB0_119

; #define PG8_STAGE(bufoff, gbase, voff) do { _Pragma("unroll") for (int _i = 0; _i < 2; ++_i) { const char* _gb = (const char*)(gbase) + (size_t)_i * (voff##_q); asm volatile("" : "+s"(_gb)); \
;         __builtin_amdgcn_global_load_lds((const unsigned*)(_gb + (voff)), (LAS unsigned*)(lds + (bufoff) + ldsw + _i * 8192), 16, 0, 0); } } while (0)
; #define PG8_LDA(dst, b, h) do { _Pragma("unroll") for (int m = 0; m < 4; ++m) _Pragma("unroll") for (int k = 0; k < 2; ++k) dst[m][k] = *(const LAS bf16x8*)(lds + PG8_SA(b, h) + aoff + m * 2048 + k * 1024); } while (0)
; #define PG8_LDB(dst, b, h) do { _Pragma("unroll") for (int n = 0; n < 2; ++n) _Pragma("unroll") for (int k = 0; k < 2; ++k) dst[n][k] = *(const LAS bf16x8*)(lds + PG8_SB(b, h) + boff + n * 2048 + k * 1024); } while (0)
; #define PG8_WAIT_V(n) asm volatile("s_waitcnt vmcnt(" #n ")" ::: "memory")
; #define PG8_BAR __builtin_amdgcn_s_barrier()
; template <class Epi, class Sched>
; __device__ __forceinline__ void gemm_phase(int wv, LAS unsigned char* lds, const Gemm g, const Sched& S, const Epi& E) { LIDS
;     ...
;     for (;;) {
;         const bool has_next = S.next(ui + 1, nxt);
;         const char* nA = has_next ? (const char*)g.A + (size_t)nxt.pm * g.tstepA : cA; const char* nB = has_next ? (const char*)g.Bt + (size_t)nxt.pn * g.tstepB : cB;
;         for (int t = 0; t < nt; t += 2) {
;             const bool last = (t == nt - 2);
;             const char* a1 = cA + (size_t)(t + 1) * kstepA;
;             const char* a2 = last ? nA : cA + (size_t)(t + 2) * kstepA; const char* b2 = last ? nB : cB + (size_t)(t + 2) * kstepB;
;             const char* a3 = a2 + kstepA; const char* b3 = b2 + kstepB;
;             asm volatile("" : "+s"(a1), "+s"(a2), "+s"(b2), "+s"(a3), "+s"(b3));
;             PG8_LDB(B0, 0, 0); PG8_SCHED; PG8_LDA(At, 0, 0); PG8_STAGE(PG8_SA(1, 1), a1 + hstepA, voffA);
;             PG8_WAIT_L(8); PG8_BAR; PG8_WAIT_L(0); PG8_MMA(0, 0, At, B0); PG8_BAR; PG8_SCHED;
;             PG8_LDB(B1, 0, 1); PG8_STAGE(PG8_SB(0, 0), b2, voffB);
;             PG8_BAR; PG8_WAIT_L(0); PG8_MMA(0, 1, At, B1); PG8_BAR;
;             PG8_LDA(At, 0, 1); PG8_STAGE(PG8_SA(0, 0), a2, voffA);
;             PG8_BAR; PG8_WAIT_L(0); PG8_MMA(1, 0, At, B0); PG8_BAR; PG8_SCHED;
;             PG8_STAGE(PG8_SB(0, 1), b2 + hstepB, voffB);
;             PG8_WAIT_V(6); PG8_BAR; PG8_MMA(1, 1, At, B1); PG8_BAR;
.LBB0_168:
	s_ashr_i32 s11, s10, 31
	s_lshl_b64 s[12:13], s[10:11], 21
	v_readlane_b32 s9, v253, 16
	v_mov_b64_e32 v[4:5], 0x100
	s_add_u32 s12, s9, s12
	v_readlane_b32 s9, v253, 17
	v_cmp_lt_i64_e32 vcc, s[6:7], v[4:5]
	s_addc_u32 s13, s9, s13
	s_and_b64 s[18:19], vcc, exec
	s_cselect_b32 s73, s13, s87
	s_cselect_b32 s72, s12, s86
	s_ashr_i32 s9, s8, 31
	s_lshl_b64 s[18:19], s[8:9], 17
	v_readlane_b32 s20, v253, 18
	v_readlane_b32 s21, v253, 19
	s_add_u32 s62, s20, s18
	s_addc_u32 s63, s21, s19
	s_and_b64 s[18:19], vcc, exec
	s_cselect_b32 s79, s63, s91
	s_cselect_b32 s78, s62, s90
	s_add_u32 s18, s86, 0x80
	s_addc_u32 s19, s87, 0
	s_add_u32 s88, s86, 0x100
	s_addc_u32 s89, s87, 0
	s_add_u32 s94, s90, 0x100
	s_addc_u32 s95, s91, 0
	s_add_u32 s86, s86, 0x180
	s_addc_u32 s87, s87, 0
	s_add_u32 s90, s90, 0x180
	s_addc_u32 s91, s91, 0
	s_add_i32 s11, 16, 0x10000
	s_mov_b64 s[84:85], s[86:87]
	v_add_u32_e32 v176, s11, v134
	ds_read_b128 v[4:7], v176
	ds_read_b128 v[8:11], v176 offset:1024
	ds_read_b128 v[12:15], v176 offset:2048
	ds_read_b128 v[16:19], v176 offset:3072
	s_add_u32 s20, s18, 0x100000
	s_addc_u32 s21, s19, 0
	s_add_i32 s22, s58, 0xc000
	s_add_u32 s18, s18, 0x180000
	ds_read_b128 v[20:23], v135
	ds_read_b128 v[24:27], v135 offset:1024
	ds_read_b128 v[28:31], v135 offset:2048
	ds_read_b128 v[32:35], v135 offset:3072
	ds_read_b128 v[36:39], v135 offset:4096
	ds_read_b128 v[40:43], v135 offset:5120
	ds_read_b128 v[44:47], v135 offset:6144
	ds_read_b128 v[48:51], v135 offset:7168
	s_mov_b32 m0, s22
	v_lshl_add_u64 v[52:53], s[20:21], 0, v[124:125]
	s_addc_u32 s19, s19, 0
	s_add_i32 s9, s58, 0xe000
	global_load_lds_dwordx4 v[52:53], off
	s_mov_b32 m0, s9
	v_lshl_add_u64 v[52:53], s[18:19], 0, v[124:125]
	global_load_lds_dwordx4 v[52:53], off
	s_waitcnt lgkmcnt(8)
	s_barrier
	s_waitcnt lgkmcnt(0)
	s_setprio 1
	s_waitcnt lgkmcnt(0)
	v_mfma_f32_16x16x32_bf16 v[52:55], v[4:7], v[20:23], v[0:3]
	v_mfma_f32_16x16x32_bf16 v[56:59], v[12:15], v[20:23], v[0:3]
	v_mfma_f32_16x16x32_bf16 v[60:63], v[4:7], v[28:31], v[0:3]
	v_mfma_f32_16x16x32_bf16 v[64:67], v[12:15], v[28:31], v[0:3]
	v_mfma_f32_16x16x32_bf16 v[68:71], v[4:7], v[36:39], v[0:3]
	v_mfma_f32_16x16x32_bf16 v[72:75], v[12:15], v[36:39], v[0:3]
	v_mfma_f32_16x16x32_bf16 v[76:79], v[4:7], v[44:47], v[0:3]
	v_mfma_f32_16x16x32_bf16 v[80:83], v[12:15], v[44:47], v[0:3]
	v_mfma_f32_16x16x32_bf16 v[52:55], v[8:11], v[24:27], v[52:55]
	v_mfma_f32_16x16x32_bf16 v[56:59], v[16:19], v[24:27], v[56:59]
	v_mfma_f32_16x16x32_bf16 v[60:63], v[8:11], v[32:35], v[60:63]
	v_mfma_f32_16x16x32_bf16 v[64:67], v[16:19], v[32:35], v[64:67]
	v_mfma_f32_16x16x32_bf16 v[68:71], v[8:11], v[40:43], v[68:71]
	v_mfma_f32_16x16x32_bf16 v[72:75], v[16:19], v[40:43], v[72:75]
	v_mfma_f32_16x16x32_bf16 v[76:79], v[8:11], v[48:51], v[76:79]
	v_mfma_f32_16x16x32_bf16 v[80:83], v[16:19], v[48:51], v[80:83]
	s_setprio 0
	s_barrier
	s_add_i32 s21, 16, 0x14000
	v_add_u32_e32 v178, s21, v134
	s_mov_b64 s[18:19], s[94:95]
	ds_read_b128 v[84:87], v178
	ds_read_b128 v[88:91], v178 offset:1024
	ds_read_b128 v[92:95], v178 offset:2048
	ds_read_b128 v[96:99], v178 offset:3072
	s_add_i32 s20, s11, s57
	v_lshl_add_u64 v[100:101], s[18:19], 0, v[126:127]
	s_add_u32 s18, s94, 0x8000
	s_mov_b32 m0, s20
	s_addc_u32 s19, s95, 0
	s_add_i32 s11, s20, 0x2000
	global_load_lds_dwordx4 v[100:101], off
	s_mov_b32 m0, s11
	v_lshl_add_u64 v[100:101], s[18:19], 0, v[126:127]
	global_load_lds_dwordx4 v[100:101], off
	s_barrier
	s_waitcnt lgkmcnt(0)
	s_setprio 1
	s_waitcnt lgkmcnt(0)
	v_mfma_f32_16x16x32_bf16 v[100:103], v[84:87], v[20:23], v[0:3]
	v_mfma_f32_16x16x32_bf16 v[20:23], v[92:95], v[20:23], v[0:3]
	v_mfma_f32_16x16x32_bf16 v[100:103], v[88:91], v[24:27], v[100:103]
	v_mfma_f32_16x16x32_bf16 v[20:23], v[96:99], v[24:27], v[20:23]
	v_mfma_f32_16x16x32_bf16 v[24:27], v[84:87], v[28:31], v[0:3]
	v_mfma_f32_16x16x32_bf16 v[28:31], v[92:95], v[28:31], v[0:3]
	v_mfma_f32_16x16x32_bf16 v[24:27], v[88:91], v[32:35], v[24:27]
	v_mfma_f32_16x16x32_bf16 v[28:31], v[96:99], v[32:35], v[28:31]
	v_mfma_f32_16x16x32_bf16 v[32:35], v[84:87], v[36:39], v[0:3]
	v_mfma_f32_16x16x32_bf16 v[36:39], v[92:95], v[36:39], v[0:3]
	v_mfma_f32_16x16x32_bf16 v[32:35], v[88:91], v[40:43], v[32:35]
	v_mfma_f32_16x16x32_bf16 v[36:39], v[96:99], v[40:43], v[36:39]
	v_mfma_f32_16x16x32_bf16 v[40:43], v[84:87], v[44:47], v[0:3]
	v_mfma_f32_16x16x32_bf16 v[44:47], v[92:95], v[44:47], v[0:3]
	v_mfma_f32_16x16x32_bf16 v[40:43], v[88:91], v[48:51], v[40:43]
	v_mfma_f32_16x16x32_bf16 v[44:47], v[96:99], v[48:51], v[44:47]
	s_setprio 0
	s_mov_b64 s[18:19], s[88:89]
	s_barrier
	ds_read_b128 v[48:51], v135 offset:16384
	ds_read_b128 v[104:107], v135 offset:17408
	ds_read_b128 v[108:111], v135 offset:18432
	ds_read_b128 v[112:115], v135 offset:19456
	ds_read_b128 v[116:119], v135 offset:20480
	ds_read_b128 v[120:123], v135 offset:21504
	ds_read_b128 v[128:131], v135 offset:22528
	ds_read_b128 v[136:139], v135 offset:23552
	s_mov_b32 m0, s58
	v_lshl_add_u64 v[132:133], s[18:19], 0, v[124:125]
	s_add_u32 s18, s88, 0x80000
	s_addc_u32 s19, s89, 0
	global_load_lds_dwordx4 v[132:133], off
	s_mov_b32 m0, s77
	v_lshl_add_u64 v[132:133], s[18:19], 0, v[124:125]
	global_load_lds_dwordx4 v[132:133], off
	s_barrier
; #define PG8_STAGE(bufoff, gbase, voff) do { _Pragma("unroll") for (int _i = 0; _i < 2; ++_i) { const char* _gb = (const char*)(gbase) + (size_t)_i * (voff##_q); asm volatile("" : "+s"(_gb)); \
;         __builtin_amdgcn_global_load_lds((const unsigned*)(_gb + (voff)), (LAS unsigned*)(lds + (bufoff) + ldsw + _i * 8192), 16, 0, 0); } } while (0)
; #define PG8_LDA(dst, b, h) do { _Pragma("unroll") for (int m = 0; m < 4; ++m) _Pragma("unroll") for (int k = 0; k < 2; ++k) dst[m][k] = *(const LAS bf16x8*)(lds + PG8_SA(b, h) + aoff + m * 2048 + k * 1024); } while (0)
; #define PG8_LDB(dst, b, h) do { _Pragma("unroll") for (int n = 0; n < 2; ++n) _Pragma("unroll") for (int k = 0; k < 2; ++k) dst[n][k] = *(const LAS bf16x8*)(lds + PG8_SB(b, h) + boff + n * 2048 + k * 1024); } while (0)
; #define PG8_MMA(ai, bj, At, Bt) do { __builtin_amdgcn_s_setprio(1); _Pragma("unroll") for (int m = 0; m < 4; ++m) _Pragma("unroll") for (int n = 0; n < 2; ++n) _Pragma("unroll") for (int k = 0; k < 2; ++k) \
;         acc[ai][bj][m][n] = __builtin_amdgcn_mfma_f32_16x16x32_bf16(Bt[n][k], At[m][k], acc[ai][bj][m][n], 0, 0, 0); __builtin_amdgcn_s_setprio(0); } while (0)
; #define PG8_WAIT_V(n) asm volatile("s_waitcnt vmcnt(" #n ")" ::: "memory")
; #define PG8_WAIT_L(n) asm volatile("s_waitcnt lgkmcnt(" #n ")" ::: "memory")
; #define PG8_BAR __builtin_amdgcn_s_barrier()
; #define PG8_SCHED __builtin_amdgcn_sched_barrier(0)
; template <class Epi, class Sched>
; __device__ __forceinline__ void gemm_phase(int wv, LAS unsigned char* lds, const Gemm g, const Sched& S, const Epi& E) { LIDS
;     ...
;             PG8_WAIT_V(6); PG8_BAR; PG8_MMA(1, 1, At, B1); PG8_BAR;
;             PG8_LDB(B0, 1, 0); PG8_SCHED; PG8_LDA(At, 1, 0); PG8_STAGE(PG8_SA(0, 1), a2 + hstepA, voffA);
;             PG8_WAIT_L(8); PG8_BAR; PG8_WAIT_L(0); PG8_MMA(0, 0, At, B0); PG8_BAR; PG8_SCHED;
	s_waitcnt lgkmcnt(0)
	s_setprio 1
	s_waitcnt lgkmcnt(0)
	v_mfma_f32_16x16x32_bf16 v[140:143], v[4:7], v[48:51], v[0:3]
	v_mfma_f32_16x16x32_bf16 v[148:151], v[4:7], v[108:111], v[0:3]
	v_mfma_f32_16x16x32_bf16 v[156:159], v[4:7], v[116:119], v[0:3]
	v_mfma_f32_16x16x32_bf16 v[4:7], v[4:7], v[128:131], v[0:3]
	v_mfma_f32_16x16x32_bf16 v[140:143], v[8:11], v[104:107], v[140:143]
	v_mfma_f32_16x16x32_bf16 v[144:147], v[12:15], v[48:51], v[0:3]
	v_mfma_f32_16x16x32_bf16 v[148:151], v[8:11], v[112:115], v[148:151]
	v_mfma_f32_16x16x32_bf16 v[152:155], v[12:15], v[108:111], v[0:3]
	v_mfma_f32_16x16x32_bf16 v[156:159], v[8:11], v[120:123], v[156:159]
	v_mfma_f32_16x16x32_bf16 v[160:163], v[12:15], v[116:119], v[0:3]
	v_mfma_f32_16x16x32_bf16 v[4:7], v[8:11], v[136:139], v[4:7]
	v_mfma_f32_16x16x32_bf16 v[8:11], v[12:15], v[128:131], v[0:3]
	v_mfma_f32_16x16x32_bf16 v[144:147], v[16:19], v[104:107], v[144:147]
	v_mfma_f32_16x16x32_bf16 v[152:155], v[16:19], v[112:115], v[152:155]
	v_mfma_f32_16x16x32_bf16 v[160:163], v[16:19], v[120:123], v[160:163]
	v_mfma_f32_16x16x32_bf16 v[8:11], v[16:19], v[136:139], v[8:11]
	s_setprio 0
	s_barrier
	s_add_u32 s18, s94, 0x10000
	s_addc_u32 s19, s95, 0
	s_add_i32 s21, s21, s57
	v_lshl_add_u64 v[12:13], s[18:19], 0, v[126:127]
	s_add_u32 s18, s94, 0x18000
	s_mov_b32 m0, s21
	s_addc_u32 s19, s95, 0
	s_add_i32 s17, s21, 0x2000
	global_load_lds_dwordx4 v[12:13], off
	s_mov_b32 m0, s17
	v_lshl_add_u64 v[12:13], s[18:19], 0, v[126:127]
	global_load_lds_dwordx4 v[12:13], off
	s_waitcnt vmcnt(6)
	s_barrier
	s_setprio 1
	v_mfma_f32_16x16x32_bf16 v[12:15], v[84:87], v[48:51], v[0:3]
	v_mfma_f32_16x16x32_bf16 v[16:19], v[92:95], v[48:51], v[0:3]
	v_mfma_f32_16x16x32_bf16 v[12:15], v[88:91], v[104:107], v[12:15]
	v_mfma_f32_16x16x32_bf16 v[16:19], v[96:99], v[104:107], v[16:19]
	v_mfma_f32_16x16x32_bf16 v[48:51], v[84:87], v[108:111], v[0:3]
	v_mfma_f32_16x16x32_bf16 v[104:107], v[92:95], v[108:111], v[0:3]
	v_mfma_f32_16x16x32_bf16 v[108:111], v[84:87], v[116:119], v[0:3]
	v_mfma_f32_16x16x32_bf16 v[84:87], v[84:87], v[128:131], v[0:3]
	v_mfma_f32_16x16x32_bf16 v[48:51], v[88:91], v[112:115], v[48:51]
	v_mfma_f32_16x16x32_bf16 v[104:107], v[96:99], v[112:115], v[104:107]
	v_mfma_f32_16x16x32_bf16 v[108:111], v[88:91], v[120:123], v[108:111]
	v_mfma_f32_16x16x32_bf16 v[112:115], v[92:95], v[116:119], v[0:3]
	v_mfma_f32_16x16x32_bf16 v[84:87], v[88:91], v[136:139], v[84:87]
	v_mfma_f32_16x16x32_bf16 v[88:91], v[92:95], v[128:131], v[0:3]
	v_mfma_f32_16x16x32_bf16 v[112:115], v[96:99], v[120:123], v[112:115]
	v_mfma_f32_16x16x32_bf16 v[88:91], v[96:99], v[136:139], v[88:91]
	s_setprio 0
	s_add_i32 s23, 16, 0x18000
	v_add_u32_e32 v179, s23, v134
	s_barrier
	ds_read_b128 v[92:95], v179
	ds_read_b128 v[96:99], v179 offset:1024
	ds_read_b128 v[116:119], v179 offset:2048
	ds_read_b128 v[120:123], v179 offset:3072
	s_add_u32 s18, s88, 0x100000
	s_addc_u32 s19, s89, 0
	ds_read_b128 v[128:131], v135 offset:32768
	ds_read_b128 v[136:139], v135 offset:33792
	ds_read_b128 v[164:167], v135 offset:34816
	ds_read_b128 v[168:171], v135 offset:35840
	ds_read_b128 v[172:175], v135 offset:36864
	ds_read_b128 v[194:197], v135 offset:37888
	ds_read_b128 v[198:201], v135 offset:38912
	ds_read_b128 v[202:205], v135 offset:39936
	s_mov_b32 m0, s82
	v_lshl_add_u64 v[132:133], s[18:19], 0, v[124:125]
	s_add_u32 s18, s88, 0x180000
	s_addc_u32 s19, s89, 0
	global_load_lds_dwordx4 v[132:133], off
	s_mov_b32 m0, s56
	v_lshl_add_u64 v[132:133], s[18:19], 0, v[124:125]
	global_load_lds_dwordx4 v[132:133], off
	s_waitcnt lgkmcnt(8)
	s_barrier
	s_waitcnt lgkmcnt(0)
	s_setprio 1
	s_waitcnt lgkmcnt(0)
	v_mfma_f32_16x16x32_bf16 v[52:55], v[92:95], v[128:131], v[52:55]
	v_mfma_f32_16x16x32_bf16 v[56:59], v[116:119], v[128:131], v[56:59]
	v_mfma_f32_16x16x32_bf16 v[60:63], v[92:95], v[164:167], v[60:63]
	v_mfma_f32_16x16x32_bf16 v[64:67], v[116:119], v[164:167], v[64:67]
	v_mfma_f32_16x16x32_bf16 v[68:71], v[92:95], v[172:175], v[68:71]
	v_mfma_f32_16x16x32_bf16 v[72:75], v[116:119], v[172:175], v[72:75]
	v_mfma_f32_16x16x32_bf16 v[76:79], v[92:95], v[198:201], v[76:79]
	v_mfma_f32_16x16x32_bf16 v[80:83], v[116:119], v[198:201], v[80:83]
	v_mfma_f32_16x16x32_bf16 v[52:55], v[96:99], v[136:139], v[52:55]
	v_mfma_f32_16x16x32_bf16 v[56:59], v[120:123], v[136:139], v[56:59]
	v_mfma_f32_16x16x32_bf16 v[60:63], v[96:99], v[168:171], v[60:63]
	v_mfma_f32_16x16x32_bf16 v[64:67], v[120:123], v[168:171], v[64:67]
	v_mfma_f32_16x16x32_bf16 v[68:71], v[96:99], v[194:197], v[68:71]
	v_mfma_f32_16x16x32_bf16 v[72:75], v[120:123], v[194:197], v[72:75]
	v_mfma_f32_16x16x32_bf16 v[76:79], v[96:99], v[202:205], v[76:79]
	v_mfma_f32_16x16x32_bf16 v[80:83], v[120:123], v[202:205], v[80:83]
	s_setprio 0
	s_barrier
	s_add_i32 s26, 16, 0x1c000
	v_add_u32_e32 v190, s26, v134
	s_mov_b64 s[18:19], s[90:91]
	ds_read_b128 v[206:209], v190
	ds_read_b128 v[218:221], v190 offset:1024
	ds_read_b128 v[222:225], v190 offset:2048
	ds_read_b128 v[226:229], v190 offset:3072
	s_add_i32 s23, s23, s57
	v_lshl_add_u64 v[132:133], s[18:19], 0, v[126:127]
	s_add_u32 s18, s90, 0x8000
	s_mov_b32 m0, s23
	s_addc_u32 s19, s91, 0
	global_load_lds_dwordx4 v[132:133], off
	s_nop 0
	v_lshl_add_u64 v[132:133], s[18:19], 0, v[126:127]
	s_add_i32 s18, s23, 0x2000
	s_mov_b32 m0, s18
	s_nop 0
	global_load_lds_dwordx4 v[132:133], off
	s_barrier
; #define PG8_STAGE(bufoff, gbase, voff) do { _Pragma("unroll") for (int _i = 0; _i < 2; ++_i) { const char* _gb = (const char*)(gbase) + (size_t)_i * (voff##_q); asm volatile("" : "+s"(_gb)); \
;         __builtin_amdgcn_global_load_lds((const unsigned*)(_gb + (voff)), (LAS unsigned*)(lds + (bufoff) + ldsw + _i * 8192), 16, 0, 0); } } while (0)
; #define PG8_LDA(dst, b, h) do { _Pragma("unroll") for (int m = 0; m < 4; ++m) _Pragma("unroll") for (int k = 0; k < 2; ++k) dst[m][k] = *(const LAS bf16x8*)(lds + PG8_SA(b, h) + aoff + m * 2048 + k * 1024); } while (0)
; #define PG8_LDB(dst, b, h) do { _Pragma("unroll") for (int n = 0; n < 2; ++n) _Pragma("unroll") for (int k = 0; k < 2; ++k) dst[n][k] = *(const LAS bf16x8*)(lds + PG8_SB(b, h) + boff + n * 2048 + k * 1024); } while (0)
; #define PG8_MMA(ai, bj, At, Bt) do { __builtin_amdgcn_s_setprio(1); _Pragma("unroll") for (int m = 0; m < 4; ++m) _Pragma("unroll") for (int n = 0; n < 2; ++n) _Pragma("unroll") for (int k = 0; k < 2; ++k) \
;         acc[ai][bj][m][n] = __builtin_amdgcn_mfma_f32_16x16x32_bf16(Bt[n][k], At[m][k], acc[ai][bj][m][n], 0, 0, 0); __builtin_amdgcn_s_setprio(0); } while (0)
; #define PG8_WAIT_L(n) asm volatile("s_waitcnt lgkmcnt(" #n ")" ::: "memory")
; #define PG8_BAR __builtin_amdgcn_s_barrier()
; #define PG8_SCHED __builtin_amdgcn_sched_barrier(0)
; template <class Epi, class Sched>
; __device__ __forceinline__ void gemm_phase(int wv, LAS unsigned char* lds, const Gemm g, const Sched& S, const Epi& E) { LIDS
;     ...
;             PG8_WAIT_L(8); PG8_BAR; PG8_WAIT_L(0); PG8_MMA(0, 0, At, B0); PG8_BAR; PG8_SCHED;
;             PG8_LDB(B1, 1, 1); PG8_STAGE(PG8_SB(1, 0), b3, voffB);
;             PG8_BAR; PG8_WAIT_L(0); PG8_MMA(0, 1, At, B1); PG8_BAR;
;             PG8_LDA(At, 1, 1); PG8_STAGE(PG8_SA(1, 0), a3, voffA);
;             PG8_BAR; PG8_WAIT_L(0); PG8_MMA(1, 0, At, B0); PG8_BAR; PG8_SCHED;
	s_waitcnt lgkmcnt(0)
	s_setprio 1
	s_waitcnt lgkmcnt(0)
	v_mfma_f32_16x16x32_bf16 v[100:103], v[206:209], v[128:131], v[100:103]
	v_mfma_f32_16x16x32_bf16 v[20:23], v[222:225], v[128:131], v[20:23]
	v_mfma_f32_16x16x32_bf16 v[24:27], v[206:209], v[164:167], v[24:27]
	v_mfma_f32_16x16x32_bf16 v[28:31], v[222:225], v[164:167], v[28:31]
	v_mfma_f32_16x16x32_bf16 v[32:35], v[206:209], v[172:175], v[32:35]
	v_mfma_f32_16x16x32_bf16 v[36:39], v[222:225], v[172:175], v[36:39]
	v_mfma_f32_16x16x32_bf16 v[40:43], v[206:209], v[198:201], v[40:43]
	v_mfma_f32_16x16x32_bf16 v[44:47], v[222:225], v[198:201], v[44:47]
	v_mfma_f32_16x16x32_bf16 v[100:103], v[218:221], v[136:139], v[100:103]
	v_mfma_f32_16x16x32_bf16 v[20:23], v[226:229], v[136:139], v[20:23]
	v_mfma_f32_16x16x32_bf16 v[24:27], v[218:221], v[168:171], v[24:27]
	v_mfma_f32_16x16x32_bf16 v[28:31], v[226:229], v[168:171], v[28:31]
	v_mfma_f32_16x16x32_bf16 v[32:35], v[218:221], v[194:197], v[32:35]
	v_mfma_f32_16x16x32_bf16 v[36:39], v[226:229], v[194:197], v[36:39]
	v_mfma_f32_16x16x32_bf16 v[40:43], v[218:221], v[202:205], v[40:43]
	v_mfma_f32_16x16x32_bf16 v[44:47], v[226:229], v[202:205], v[44:47]
	s_setprio 0
	s_mov_b64 s[24:25], s[84:85]
	s_barrier
	ds_read_b128 v[128:131], v135 offset:49152
	ds_read_b128 v[136:139], v135 offset:50176
	ds_read_b128 v[164:167], v135 offset:51200
	ds_read_b128 v[168:171], v135 offset:52224
	ds_read_b128 v[172:175], v135 offset:53248
	ds_read_b128 v[194:197], v135 offset:54272
	ds_read_b128 v[198:201], v135 offset:55296
	ds_read_b128 v[202:205], v135 offset:56320
	s_mov_b32 m0, s0
	v_lshl_add_u64 v[132:133], s[24:25], 0, v[124:125]
	s_add_u32 s24, s84, 0x80000
	s_addc_u32 s25, s85, 0
	global_load_lds_dwordx4 v[132:133], off
	s_mov_b32 m0, s59
	v_lshl_add_u64 v[132:133], s[24:25], 0, v[124:125]
	global_load_lds_dwordx4 v[132:133], off
	s_barrier
	s_waitcnt lgkmcnt(0)
	s_setprio 1
	s_waitcnt lgkmcnt(0)
	v_mfma_f32_16x16x32_bf16 v[140:143], v[92:95], v[128:131], v[140:143]
	v_mfma_f32_16x16x32_bf16 v[144:147], v[116:119], v[128:131], v[144:147]
	v_mfma_f32_16x16x32_bf16 v[148:151], v[92:95], v[164:167], v[148:151]
	v_mfma_f32_16x16x32_bf16 v[152:155], v[116:119], v[164:167], v[152:155]
	v_mfma_f32_16x16x32_bf16 v[156:159], v[92:95], v[172:175], v[156:159]
	v_mfma_f32_16x16x32_bf16 v[160:163], v[116:119], v[172:175], v[160:163]
	v_mfma_f32_16x16x32_bf16 v[4:7], v[92:95], v[198:201], v[4:7]
	v_mfma_f32_16x16x32_bf16 v[8:11], v[116:119], v[198:201], v[8:11]
	v_mfma_f32_16x16x32_bf16 v[140:143], v[96:99], v[136:139], v[140:143]
	v_mfma_f32_16x16x32_bf16 v[144:147], v[120:123], v[136:139], v[144:147]
	v_mfma_f32_16x16x32_bf16 v[148:151], v[96:99], v[168:171], v[148:151]
	v_mfma_f32_16x16x32_bf16 v[152:155], v[120:123], v[168:171], v[152:155]
	v_mfma_f32_16x16x32_bf16 v[156:159], v[96:99], v[194:197], v[156:159]
	v_mfma_f32_16x16x32_bf16 v[160:163], v[120:123], v[194:197], v[160:163]
	v_mfma_f32_16x16x32_bf16 v[4:7], v[96:99], v[202:205], v[4:7]
	v_mfma_f32_16x16x32_bf16 v[8:11], v[120:123], v[202:205], v[8:11]
	s_setprio 0
	s_barrier
	s_add_u32 s24, s90, 0x10000
	s_addc_u32 s25, s91, 0
	s_nop 0
	v_lshl_add_u64 v[92:93], s[24:25], 0, v[126:127]
	s_add_i32 s24, s26, s57
	s_add_u32 s26, s90, 0x18000
	s_mov_b32 m0, s24
	s_addc_u32 s27, s91, 0
	s_add_i32 s19, s24, 0x2000
	global_load_lds_dwordx4 v[92:93], off
	s_mov_b32 m0, s19
	v_lshl_add_u64 v[92:93], s[26:27], 0, v[126:127]
	global_load_lds_dwordx4 v[92:93], off
	s_waitcnt vmcnt(6)
	s_barrier
	s_setprio 1
	v_mfma_f32_16x16x32_bf16 v[12:15], v[206:209], v[128:131], v[12:15]
	v_mfma_f32_16x16x32_bf16 v[16:19], v[222:225], v[128:131], v[16:19]
	v_mfma_f32_16x16x32_bf16 v[48:51], v[206:209], v[164:167], v[48:51]
	v_mfma_f32_16x16x32_bf16 v[92:95], v[222:225], v[164:167], v[104:107]
	v_mfma_f32_16x16x32_bf16 v[96:99], v[206:209], v[172:175], v[108:111]
	v_mfma_f32_16x16x32_bf16 v[104:107], v[222:225], v[172:175], v[112:115]
	v_mfma_f32_16x16x32_bf16 v[84:87], v[206:209], v[198:201], v[84:87]
	v_mfma_f32_16x16x32_bf16 v[88:91], v[222:225], v[198:201], v[88:91]
	v_mfma_f32_16x16x32_bf16 v[12:15], v[218:221], v[136:139], v[12:15]
	v_mfma_f32_16x16x32_bf16 v[16:19], v[226:229], v[136:139], v[16:19]
	v_mfma_f32_16x16x32_bf16 v[48:51], v[218:221], v[168:171], v[48:51]
	v_mfma_f32_16x16x32_bf16 v[92:95], v[226:229], v[168:171], v[92:95]
	v_mfma_f32_16x16x32_bf16 v[96:99], v[218:221], v[194:197], v[96:99]
	v_mfma_f32_16x16x32_bf16 v[104:107], v[226:229], v[194:197], v[104:107]
	v_mfma_f32_16x16x32_bf16 v[84:87], v[218:221], v[202:205], v[84:87]
	v_mfma_f32_16x16x32_bf16 v[88:91], v[226:229], v[202:205], v[88:91]
	s_setprio 0
	s_add_u32 s84, s72, 0x80
	s_addc_u32 s85, s73, 0
	s_add_u32 s90, s78, 0x80
	s_addc_u32 s91, s79, 0
	s_barrier
	ds_read_b128 v[108:111], v176
	ds_read_b128 v[112:115], v176 offset:1024
	ds_read_b128 v[116:119], v176 offset:2048
	ds_read_b128 v[120:123], v176 offset:3072
	s_add_u32 s26, s86, 0x100000
	s_addc_u32 s27, s87, 0
	ds_read_b128 v[128:131], v135
	ds_read_b128 v[136:139], v135 offset:1024
	ds_read_b128 v[164:167], v135 offset:2048
	ds_read_b128 v[168:171], v135 offset:3072
	ds_read_b128 v[172:175], v135 offset:4096
	ds_read_b128 v[194:197], v135 offset:5120
	ds_read_b128 v[198:201], v135 offset:6144
	ds_read_b128 v[202:205], v135 offset:7168
	s_mov_b32 m0, s22
	v_lshl_add_u64 v[132:133], s[26:27], 0, v[124:125]
	s_add_u32 s26, s86, 0x180000
	s_addc_u32 s27, s87, 0
	global_load_lds_dwordx4 v[132:133], off
	s_mov_b32 m0, s9
	v_lshl_add_u64 v[132:133], s[26:27], 0, v[124:125]
	global_load_lds_dwordx4 v[132:133], off
	s_waitcnt lgkmcnt(8)
	s_barrier
; #define PG8_STAGE(bufoff, gbase, voff) do { _Pragma("unroll") for (int _i = 0; _i < 2; ++_i) { const char* _gb = (const char*)(gbase) + (size_t)_i * (voff##_q); asm volatile("" : "+s"(_gb)); \
;         __builtin_amdgcn_global_load_lds((const unsigned*)(_gb + (voff)), (LAS unsigned*)(lds + (bufoff) + ldsw + _i * 8192), 16, 0, 0); } } while (0)
; #define PG8_MMA(ai, bj, At, Bt) do { __builtin_amdgcn_s_setprio(1); _Pragma("unroll") for (int m = 0; m < 4; ++m) _Pragma("unroll") for (int n = 0; n < 2; ++n) _Pragma("unroll") for (int k = 0; k < 2; ++k) \
;         acc[ai][bj][m][n] = __builtin_amdgcn_mfma_f32_16x16x32_bf16(Bt[n][k], At[m][k], acc[ai][bj][m][n], 0, 0, 0); __builtin_amdgcn_s_setprio(0); } while (0)
; #define PG8_WAIT_V(n) asm volatile("s_waitcnt vmcnt(" #n ")" ::: "memory")
; #define PG8_WAIT_L(n) asm volatile("s_waitcnt lgkmcnt(" #n ")" ::: "memory")
; #define PG8_BAR __builtin_amdgcn_s_barrier()
; #define PG8_SCHED __builtin_amdgcn_sched_barrier(0)
; template <class Epi, class Sched>
; __device__ __forceinline__ void gemm_phase(int wv, LAS unsigned char* lds, const Gemm g, const Sched& S, const Epi& E) { LIDS
;     ...
;             PG8_BAR; PG8_WAIT_L(0); PG8_MMA(1, 0, At, B0); PG8_BAR; PG8_SCHED;
;             PG8_STAGE(PG8_SB(1, 1), b3 + hstepB, voffB);
;             PG8_WAIT_V(6); PG8_BAR; PG8_MMA(1, 1, At, B1); PG8_BAR;
	s_waitcnt lgkmcnt(0)
	s_setprio 1
	s_waitcnt lgkmcnt(0)
	v_mfma_f32_16x16x32_bf16 v[52:55], v[108:111], v[128:131], v[52:55]
	v_mfma_f32_16x16x32_bf16 v[56:59], v[116:119], v[128:131], v[56:59]
	v_mfma_f32_16x16x32_bf16 v[60:63], v[108:111], v[164:167], v[60:63]
	v_mfma_f32_16x16x32_bf16 v[64:67], v[116:119], v[164:167], v[64:67]
	v_mfma_f32_16x16x32_bf16 v[68:71], v[108:111], v[172:175], v[68:71]
	v_mfma_f32_16x16x32_bf16 v[72:75], v[116:119], v[172:175], v[72:75]
	v_mfma_f32_16x16x32_bf16 v[76:79], v[108:111], v[198:201], v[76:79]
	v_mfma_f32_16x16x32_bf16 v[80:83], v[116:119], v[198:201], v[80:83]
	v_mfma_f32_16x16x32_bf16 v[52:55], v[112:115], v[136:139], v[52:55]
	v_mfma_f32_16x16x32_bf16 v[56:59], v[120:123], v[136:139], v[56:59]
	v_mfma_f32_16x16x32_bf16 v[60:63], v[112:115], v[168:171], v[60:63]
	v_mfma_f32_16x16x32_bf16 v[64:67], v[120:123], v[168:171], v[64:67]
	v_mfma_f32_16x16x32_bf16 v[68:71], v[112:115], v[194:197], v[68:71]
	v_mfma_f32_16x16x32_bf16 v[72:75], v[120:123], v[194:197], v[72:75]
	v_mfma_f32_16x16x32_bf16 v[76:79], v[112:115], v[202:205], v[76:79]
	v_mfma_f32_16x16x32_bf16 v[80:83], v[120:123], v[202:205], v[80:83]
	s_setprio 0
	s_barrier
	s_mov_b64 s[26:27], s[78:79]
	ds_read_b128 v[206:209], v178
	ds_read_b128 v[218:221], v178 offset:1024
	ds_read_b128 v[222:225], v178 offset:2048
	ds_read_b128 v[226:229], v178 offset:3072
	s_mov_b32 m0, s20
	v_lshl_add_u64 v[132:133], s[26:27], 0, v[126:127]
	s_add_u32 s26, s78, 0x8000
	s_addc_u32 s27, s79, 0
	global_load_lds_dwordx4 v[132:133], off
	s_mov_b32 m0, s11
	v_lshl_add_u64 v[132:133], s[26:27], 0, v[126:127]
	global_load_lds_dwordx4 v[132:133], off
	s_barrier
	s_waitcnt lgkmcnt(0)
	s_setprio 1
	s_waitcnt lgkmcnt(0)
	v_mfma_f32_16x16x32_bf16 v[100:103], v[206:209], v[128:131], v[100:103]
	v_mfma_f32_16x16x32_bf16 v[20:23], v[222:225], v[128:131], v[20:23]
	v_mfma_f32_16x16x32_bf16 v[24:27], v[206:209], v[164:167], v[24:27]
	v_mfma_f32_16x16x32_bf16 v[28:31], v[222:225], v[164:167], v[28:31]
	v_mfma_f32_16x16x32_bf16 v[32:35], v[206:209], v[172:175], v[32:35]
	v_mfma_f32_16x16x32_bf16 v[36:39], v[222:225], v[172:175], v[36:39]
	v_mfma_f32_16x16x32_bf16 v[40:43], v[206:209], v[198:201], v[40:43]
	v_mfma_f32_16x16x32_bf16 v[44:47], v[222:225], v[198:201], v[44:47]
	v_mfma_f32_16x16x32_bf16 v[230:233], v[218:221], v[136:139], v[100:103]
	v_mfma_f32_16x16x32_bf16 v[20:23], v[226:229], v[136:139], v[20:23]
	v_mfma_f32_16x16x32_bf16 v[24:27], v[218:221], v[168:171], v[24:27]
	v_mfma_f32_16x16x32_bf16 v[28:31], v[226:229], v[168:171], v[28:31]
	v_mfma_f32_16x16x32_bf16 v[32:35], v[218:221], v[194:197], v[32:35]
	v_mfma_f32_16x16x32_bf16 v[36:39], v[226:229], v[194:197], v[36:39]
	v_mfma_f32_16x16x32_bf16 v[40:43], v[218:221], v[202:205], v[40:43]
	v_mfma_f32_16x16x32_bf16 v[44:47], v[226:229], v[202:205], v[44:47]
	s_setprio 0
	s_mov_b64 s[26:27], s[72:73]
	s_barrier
	ds_read_b128 v[100:103], v135 offset:16384
	ds_read_b128 v[128:131], v135 offset:17408
	ds_read_b128 v[136:139], v135 offset:18432
	ds_read_b128 v[164:167], v135 offset:19456
	ds_read_b128 v[168:171], v135 offset:20480
	ds_read_b128 v[172:175], v135 offset:21504
	ds_read_b128 v[194:197], v135 offset:22528
	ds_read_b128 v[198:201], v135 offset:23552
	s_mov_b32 m0, s58
	v_lshl_add_u64 v[132:133], s[26:27], 0, v[124:125]
	s_add_u32 s26, s72, 0x80000
	s_addc_u32 s27, s73, 0
	global_load_lds_dwordx4 v[132:133], off
	s_mov_b32 m0, s77
	v_lshl_add_u64 v[132:133], s[26:27], 0, v[124:125]
	global_load_lds_dwordx4 v[132:133], off
	s_barrier
	s_waitcnt lgkmcnt(0)
	s_setprio 1
	s_waitcnt lgkmcnt(0)
	v_mfma_f32_16x16x32_bf16 v[140:143], v[108:111], v[100:103], v[140:143]
	v_mfma_f32_16x16x32_bf16 v[144:147], v[116:119], v[100:103], v[144:147]
	v_mfma_f32_16x16x32_bf16 v[148:151], v[108:111], v[136:139], v[148:151]
	v_mfma_f32_16x16x32_bf16 v[152:155], v[116:119], v[136:139], v[152:155]
	v_mfma_f32_16x16x32_bf16 v[156:159], v[108:111], v[168:171], v[156:159]
	v_mfma_f32_16x16x32_bf16 v[160:163], v[116:119], v[168:171], v[160:163]
	v_mfma_f32_16x16x32_bf16 v[4:7], v[108:111], v[194:197], v[4:7]
	v_mfma_f32_16x16x32_bf16 v[8:11], v[116:119], v[194:197], v[8:11]
	v_mfma_f32_16x16x32_bf16 v[140:143], v[112:115], v[128:131], v[140:143]
	v_mfma_f32_16x16x32_bf16 v[144:147], v[120:123], v[128:131], v[144:147]
	v_mfma_f32_16x16x32_bf16 v[148:151], v[112:115], v[164:167], v[148:151]
	v_mfma_f32_16x16x32_bf16 v[152:155], v[120:123], v[164:167], v[152:155]
	v_mfma_f32_16x16x32_bf16 v[156:159], v[112:115], v[172:175], v[156:159]
	v_mfma_f32_16x16x32_bf16 v[160:163], v[120:123], v[172:175], v[160:163]
	v_mfma_f32_16x16x32_bf16 v[4:7], v[112:115], v[198:201], v[4:7]
	v_mfma_f32_16x16x32_bf16 v[8:11], v[120:123], v[198:201], v[8:11]
	s_setprio 0
	s_barrier
	s_add_u32 s20, s78, 0x10000
	s_mov_b32 m0, s21
	s_addc_u32 s21, s79, 0
	s_nop 0
	v_lshl_add_u64 v[108:109], s[20:21], 0, v[126:127]
	s_add_u32 s20, s78, 0x18000
	s_addc_u32 s21, s79, 0
	global_load_lds_dwordx4 v[108:109], off
	s_mov_b32 m0, s17
	v_lshl_add_u64 v[108:109], s[20:21], 0, v[126:127]
	global_load_lds_dwordx4 v[108:109], off
	s_waitcnt vmcnt(6)
	s_barrier
; #define PG8_STAGE(bufoff, gbase, voff) do { _Pragma("unroll") for (int _i = 0; _i < 2; ++_i) { const char* _gb = (const char*)(gbase) + (size_t)_i * (voff##_q); asm volatile("" : "+s"(_gb)); \
;         __builtin_amdgcn_global_load_lds((const unsigned*)(_gb + (voff)), (LAS unsigned*)(lds + (bufoff) + ldsw + _i * 8192), 16, 0, 0); } } while (0)
; #define PG8_LDA(dst, b, h) do { _Pragma("unroll") for (int m = 0; m < 4; ++m) _Pragma("unroll") for (int k = 0; k < 2; ++k) dst[m][k] = *(const LAS bf16x8*)(lds + PG8_SA(b, h) + aoff + m * 2048 + k * 1024); } while (0)
; #define PG8_LDB(dst, b, h) do { _Pragma("unroll") for (int n = 0; n < 2; ++n) _Pragma("unroll") for (int k = 0; k < 2; ++k) dst[n][k] = *(const LAS bf16x8*)(lds + PG8_SB(b, h) + boff + n * 2048 + k * 1024); } while (0)
; #define PG8_MMA(ai, bj, At, Bt) do { __builtin_amdgcn_s_setprio(1); _Pragma("unroll") for (int m = 0; m < 4; ++m) _Pragma("unroll") for (int n = 0; n < 2; ++n) _Pragma("unroll") for (int k = 0; k < 2; ++k) \
;         acc[ai][bj][m][n] = __builtin_amdgcn_mfma_f32_16x16x32_bf16(Bt[n][k], At[m][k], acc[ai][bj][m][n], 0, 0, 0); __builtin_amdgcn_s_setprio(0); } while (0)
; #define PG8_WAIT_V(n) asm volatile("s_waitcnt vmcnt(" #n ")" ::: "memory")
; #define PG8_WAIT_L(n) asm volatile("s_waitcnt lgkmcnt(" #n ")" ::: "memory")
; #define PG8_BAR __builtin_amdgcn_s_barrier()
; #define PG8_SCHED __builtin_amdgcn_sched_barrier(0)
; template <class Epi, class Sched>
; __device__ __forceinline__ void gemm_phase(int wv, LAS unsigned char* lds, const Gemm g, const Sched& S, const Epi& E) { LIDS
;     ...
;             PG8_WAIT_V(6); PG8_BAR; PG8_MMA(1, 1, At, B1); PG8_BAR;
;             PG8_LDB(B0, 1, 0); PG8_SCHED; PG8_LDA(At, 1, 0); PG8_STAGE(PG8_SA(0, 1), a2 + hstepA, voffA);
;             PG8_WAIT_L(8); PG8_BAR; PG8_WAIT_L(0); PG8_MMA(0, 0, At, B0); PG8_BAR; PG8_SCHED;
;             PG8_LDB(B1, 1, 1); PG8_STAGE(PG8_SB(1, 0), b3, voffB);
;             PG8_BAR; PG8_WAIT_L(0); PG8_MMA(0, 1, At, B1); PG8_BAR;
;             PG8_LDA(At, 1, 1); PG8_STAGE(PG8_SA(1, 0), a3, voffA);
;             PG8_BAR; PG8_WAIT_L(0); PG8_MMA(1, 0, At, B0); PG8_BAR; PG8_SCHED;
;     ...
;             PG8_WAIT_V(6); PG8_BAR; PG8_MMA(1, 1, At, B1); PG8_BAR;
	s_setprio 1
	v_mfma_f32_16x16x32_bf16 v[12:15], v[206:209], v[100:103], v[12:15]
	v_mfma_f32_16x16x32_bf16 v[16:19], v[222:225], v[100:103], v[16:19]
	v_mfma_f32_16x16x32_bf16 v[92:95], v[222:225], v[136:139], v[92:95]
	v_mfma_f32_16x16x32_bf16 v[12:15], v[218:221], v[128:131], v[12:15]
	v_mfma_f32_16x16x32_bf16 v[16:19], v[226:229], v[128:131], v[16:19]
	v_mfma_f32_16x16x32_bf16 v[128:131], v[226:229], v[164:167], v[92:95]
	v_mfma_f32_16x16x32_bf16 v[92:95], v[206:209], v[168:171], v[96:99]
	v_mfma_f32_16x16x32_bf16 v[84:87], v[206:209], v[194:197], v[84:87]
	v_mfma_f32_16x16x32_bf16 v[48:51], v[206:209], v[136:139], v[48:51]
	v_mfma_f32_16x16x32_bf16 v[136:139], v[218:221], v[172:175], v[92:95]
	v_mfma_f32_16x16x32_bf16 v[92:95], v[222:225], v[168:171], v[104:107]
	v_mfma_f32_16x16x32_bf16 v[168:171], v[218:221], v[198:201], v[84:87]
	v_mfma_f32_16x16x32_bf16 v[84:87], v[222:225], v[194:197], v[88:91]
	v_mfma_f32_16x16x32_bf16 v[48:51], v[218:221], v[164:167], v[48:51]
	v_mfma_f32_16x16x32_bf16 v[164:167], v[226:229], v[172:175], v[92:95]
	v_mfma_f32_16x16x32_bf16 v[172:175], v[226:229], v[198:201], v[84:87]
	s_setprio 0
	s_barrier
	ds_read_b128 v[194:197], v179
	ds_read_b128 v[198:201], v179 offset:1024
	ds_read_b128 v[202:205], v179 offset:2048
	ds_read_b128 v[206:209], v179 offset:3072
	s_add_u32 s20, s72, 0x100000
	s_addc_u32 s21, s73, 0
	ds_read_b128 v[92:95], v135 offset:32768
	ds_read_b128 v[96:99], v135 offset:33792
	ds_read_b128 v[112:115], v135 offset:34816
	ds_read_b128 v[218:221], v135 offset:35840
	ds_read_b128 v[222:225], v135 offset:36864
	ds_read_b128 v[226:229], v135 offset:37888
	ds_read_b128 v[234:237], v135 offset:38912
	ds_read_b128 v[238:241], v135 offset:39936
	s_mov_b32 m0, s82
	v_lshl_add_u64 v[84:85], s[20:21], 0, v[124:125]
	s_add_u32 s20, s72, 0x180000
	s_addc_u32 s21, s73, 0
	global_load_lds_dwordx4 v[84:85], off
	s_mov_b32 m0, s56
	v_lshl_add_u64 v[84:85], s[20:21], 0, v[124:125]
	global_load_lds_dwordx4 v[84:85], off
	s_waitcnt lgkmcnt(8)
	s_barrier
	s_waitcnt lgkmcnt(0)
	s_setprio 1
	s_waitcnt lgkmcnt(0)
	v_mfma_f32_16x16x32_bf16 v[52:55], v[194:197], v[92:95], v[52:55]
	v_mfma_f32_16x16x32_bf16 v[242:245], v[198:201], v[96:99], v[52:55]
	v_mfma_f32_16x16x32_bf16 v[52:55], v[202:205], v[92:95], v[56:59]
	v_mfma_f32_16x16x32_bf16 v[246:249], v[206:209], v[96:99], v[52:55]
	v_mfma_f32_16x16x32_bf16 v[52:55], v[194:197], v[112:115], v[60:63]
	v_mfma_f32_16x16x32_bf16 v[100:103], v[198:201], v[218:221], v[52:55]
	v_mfma_f32_16x16x32_bf16 v[52:55], v[202:205], v[112:115], v[64:67]
	v_mfma_f32_16x16x32_bf16 v[104:107], v[206:209], v[218:221], v[52:55]
	v_mfma_f32_16x16x32_bf16 v[52:55], v[194:197], v[222:225], v[68:71]
	v_mfma_f32_16x16x32_bf16 v[84:87], v[198:201], v[226:229], v[52:55]
	v_mfma_f32_16x16x32_bf16 v[52:55], v[202:205], v[222:225], v[72:75]
	v_mfma_f32_16x16x32_bf16 v[88:91], v[206:209], v[226:229], v[52:55]
	v_mfma_f32_16x16x32_bf16 v[52:55], v[194:197], v[234:237], v[76:79]
	v_mfma_f32_16x16x32_bf16 v[68:71], v[198:201], v[238:241], v[52:55]
	v_mfma_f32_16x16x32_bf16 v[52:55], v[202:205], v[234:237], v[80:83]
	v_mfma_f32_16x16x32_bf16 v[72:75], v[206:209], v[238:241], v[52:55]
	s_setprio 0
	s_barrier
	s_mov_b64 s[20:21], s[90:91]
	ds_read_b128 v[182:185], v190
	ds_read_b128 v[178:181], v190 offset:1024
	ds_read_b128 v[186:189], v190 offset:2048
	ds_read_b128 v[190:193], v190 offset:3072
	s_mov_b32 m0, s23
	v_lshl_add_u64 v[52:53], s[20:21], 0, v[126:127]
	s_add_u32 s20, s90, 0x8000
	s_addc_u32 s21, s91, 0
	global_load_lds_dwordx4 v[52:53], off
	s_mov_b32 m0, s18
	v_lshl_add_u64 v[52:53], s[20:21], 0, v[126:127]
	global_load_lds_dwordx4 v[52:53], off
	s_barrier
	s_waitcnt lgkmcnt(0)
	s_setprio 1
	s_waitcnt lgkmcnt(0)
	v_mfma_f32_16x16x32_bf16 v[20:23], v[186:189], v[92:95], v[20:23]
	v_mfma_f32_16x16x32_bf16 v[120:123], v[190:193], v[96:99], v[20:23]
	v_mfma_f32_16x16x32_bf16 v[20:23], v[182:185], v[112:115], v[24:27]
	v_mfma_f32_16x16x32_bf16 v[108:111], v[178:181], v[218:221], v[20:23]
	v_mfma_f32_16x16x32_bf16 v[20:23], v[186:189], v[112:115], v[28:31]
	v_mfma_f32_16x16x32_bf16 v[112:115], v[190:193], v[218:221], v[20:23]
	v_mfma_f32_16x16x32_bf16 v[20:23], v[182:185], v[222:225], v[32:35]
	v_mfma_f32_16x16x32_bf16 v[52:55], v[182:185], v[92:95], v[230:233]
	v_mfma_f32_16x16x32_bf16 v[92:95], v[178:181], v[226:229], v[20:23]
	v_mfma_f32_16x16x32_bf16 v[20:23], v[186:189], v[222:225], v[36:39]
	v_mfma_f32_16x16x32_bf16 v[116:119], v[178:181], v[96:99], v[52:55]
	v_mfma_f32_16x16x32_bf16 v[96:99], v[190:193], v[226:229], v[20:23]
	v_mfma_f32_16x16x32_bf16 v[20:23], v[182:185], v[234:237], v[40:43]
	v_mfma_f32_16x16x32_bf16 v[76:79], v[178:181], v[238:241], v[20:23]
	v_mfma_f32_16x16x32_bf16 v[20:23], v[186:189], v[234:237], v[44:47]
	v_mfma_f32_16x16x32_bf16 v[80:83], v[190:193], v[238:241], v[20:23]
	s_setprio 0
	s_mov_b64 s[20:21], s[84:85]
	s_barrier
	ds_read_b128 v[28:31], v135 offset:49152
	ds_read_b128 v[32:35], v135 offset:50176
	ds_read_b128 v[218:221], v135 offset:51200
	ds_read_b128 v[222:225], v135 offset:52224
	ds_read_b128 v[226:229], v135 offset:53248
	ds_read_b128 v[230:233], v135 offset:54272
	ds_read_b128 v[234:237], v135 offset:55296
	ds_read_b128 v[238:241], v135 offset:56320
	s_mov_b32 m0, s0
	v_lshl_add_u64 v[20:21], s[20:21], 0, v[124:125]
	s_add_u32 s20, s84, 0x80000
	s_addc_u32 s21, s85, 0
	global_load_lds_dwordx4 v[20:21], off
	s_mov_b32 m0, s59
	v_lshl_add_u64 v[20:21], s[20:21], 0, v[124:125]
	global_load_lds_dwordx4 v[20:21], off
	s_barrier
; __device__ __forceinline__ u32x4 pack8(f32x4 a, f32x4 b) { u32x4 r; r[0] = cvt_pk_bf16(a[0], a[1]); r[1] = cvt_pk_bf16(a[2], a[3]); r[2] = cvt_pk_bf16(b[0], b[1]); r[3] = cvt_pk_bf16(b[2], b[3]); return r; }
; #define PG8_MMA(ai, bj, At, Bt) do { __builtin_amdgcn_s_setprio(1); _Pragma("unroll") for (int m = 0; m < 4; ++m) _Pragma("unroll") for (int n = 0; n < 2; ++n) _Pragma("unroll") for (int k = 0; k < 2; ++k) \
;         acc[ai][bj][m][n] = __builtin_amdgcn_mfma_f32_16x16x32_bf16(Bt[n][k], At[m][k], acc[ai][bj][m][n], 0, 0, 0); __builtin_amdgcn_s_setprio(0); } while (0)
; #define PG8_WAIT_V(n) asm volatile("s_waitcnt vmcnt(" #n ")" ::: "memory")
; #define PG8_BAR __builtin_amdgcn_s_barrier()
; template <class Epi, class Sched>
; __device__ __forceinline__ void gemm_phase(int wv, LAS unsigned char* lds, const Gemm g, const Sched& S, const Epi& E) { LIDS
;     ...
;             PG8_WAIT_V(6); PG8_BAR; PG8_MMA(1, 1, At, B1); PG8_BAR;
;     __device__ __forceinline__ void operator()(const AccT& acc, const Unit& u, int wr, int wc, int fr, int fq) const {
;     ...
;         for (int ai = 0; ai < 2; ++ai)
; #pragma unroll
;             for (int m = 0; m < 4; ++m) {
;                 const int row = row0 + ai * HALF + m * 16;
;                 const f32x4 pc = *(const f32x4*)(ssp + (size_t)row * 16 + 8);
;                 const float sc = rsqrtf(((pc[0] + pc[1]) + (pc[2] + pc[3])) * (1.0f / 256.0f) + EPS);
; #pragma unroll
;                 for (int bj = 0; bj < 2; ++bj) {
;                     const int col = colbase + bj * HALF, head = col >> 7, d = col & 127;
;                     *(u32x4*)(Kf + (size_t)row * NKF + head * 192 + d) = pack8(acc[ai][bj][m][0] * sc, acc[ai][bj][m][1] * sc);
	s_waitcnt lgkmcnt(0)
	s_setprio 1
	s_waitcnt lgkmcnt(0)
	v_mfma_f32_16x16x32_bf16 v[20:23], v[194:197], v[28:31], v[140:143]
	v_mfma_f32_16x16x32_bf16 v[52:55], v[198:201], v[32:35], v[20:23]
	v_mfma_f32_16x16x32_bf16 v[20:23], v[202:205], v[28:31], v[144:147]
	v_mfma_f32_16x16x32_bf16 v[56:59], v[206:209], v[32:35], v[20:23]
	v_mfma_f32_16x16x32_bf16 v[20:23], v[194:197], v[218:221], v[148:151]
	v_mfma_f32_16x16x32_bf16 v[36:39], v[198:201], v[222:225], v[20:23]
	v_mfma_f32_16x16x32_bf16 v[20:23], v[202:205], v[218:221], v[152:155]
	v_mfma_f32_16x16x32_bf16 v[40:43], v[206:209], v[222:225], v[20:23]
	v_mfma_f32_16x16x32_bf16 v[20:23], v[194:197], v[226:229], v[156:159]
	v_mfma_f32_16x16x32_bf16 v[24:27], v[202:205], v[226:229], v[160:163]
	v_mfma_f32_16x16x32_bf16 v[4:7], v[194:197], v[234:237], v[4:7]
	v_mfma_f32_16x16x32_bf16 v[8:11], v[202:205], v[234:237], v[8:11]
	v_mfma_f32_16x16x32_bf16 v[20:23], v[198:201], v[230:233], v[20:23]
	v_mfma_f32_16x16x32_bf16 v[24:27], v[206:209], v[230:233], v[24:27]
	v_mfma_f32_16x16x32_bf16 v[4:7], v[198:201], v[238:241], v[4:7]
	v_mfma_f32_16x16x32_bf16 v[8:11], v[206:209], v[238:241], v[8:11]
	s_setprio 0
	s_barrier
	s_add_u32 s20, s90, 0x10000
	s_addc_u32 s21, s91, 0
	s_mov_b32 m0, s24
	v_lshl_add_u64 v[44:45], s[20:21], 0, v[126:127]
	s_add_u32 s20, s90, 0x18000
	s_addc_u32 s21, s91, 0
	global_load_lds_dwordx4 v[44:45], off
	s_mov_b32 m0, s19
	v_lshl_add_u64 v[44:45], s[20:21], 0, v[126:127]
	global_load_lds_dwordx4 v[44:45], off
	s_waitcnt vmcnt(6)
	s_barrier
	s_setprio 1
	v_mfma_f32_16x16x32_bf16 v[12:15], v[182:185], v[28:31], v[12:15]
	v_mfma_f32_16x16x32_bf16 v[60:63], v[178:181], v[32:35], v[12:15]
	v_mfma_f32_16x16x32_bf16 v[12:15], v[186:189], v[28:31], v[16:19]
	v_mfma_f32_16x16x32_bf16 v[64:67], v[190:193], v[32:35], v[12:15]
	v_mfma_f32_16x16x32_bf16 v[12:15], v[182:185], v[218:221], v[48:51]
	v_mfma_f32_16x16x32_bf16 v[44:47], v[178:181], v[222:225], v[12:15]
	v_mfma_f32_16x16x32_bf16 v[12:15], v[186:189], v[218:221], v[128:131]
	v_mfma_f32_16x16x32_bf16 v[48:51], v[190:193], v[222:225], v[12:15]
	v_mfma_f32_16x16x32_bf16 v[12:15], v[182:185], v[226:229], v[136:139]
	v_mfma_f32_16x16x32_bf16 v[28:31], v[178:181], v[230:233], v[12:15]
	v_mfma_f32_16x16x32_bf16 v[12:15], v[186:189], v[226:229], v[164:167]
	v_mfma_f32_16x16x32_bf16 v[32:35], v[190:193], v[230:233], v[12:15]
	v_mfma_f32_16x16x32_bf16 v[12:15], v[182:185], v[234:237], v[168:171]
	v_mfma_f32_16x16x32_bf16 v[16:19], v[186:189], v[234:237], v[172:175]
	v_mfma_f32_16x16x32_bf16 v[12:15], v[178:181], v[238:241], v[12:15]
	v_mfma_f32_16x16x32_bf16 v[16:19], v[190:193], v[238:241], v[16:19]
	s_setprio 0
	s_lshl_b32 s9, s68, 8
	s_barrier
	v_mbcnt_lo_u32_b32 v129, -1, 0
	v_mbcnt_hi_u32_b32 v129, -1, v129
	s_add_i32 s9, s9, s83
	v_and_or_b32 v128, v129, 15, s9
	s_lshl_b32 s9, s16, 8
	v_ashrrev_i32_e32 v129, 1, v129
	s_or_b32 s9, s9, s92
	v_and_b32_e32 v129, -8, v129
	v_add_u32_e32 v141, s9, v129
	v_ashrrev_i32_e32 v129, 31, v128
	v_readlane_b32 s18, v253, 12
	v_lshlrev_b64 v[130:131], 6, v[128:129]
	v_readlane_b32 s19, v253, 13
	v_ashrrev_i32_e32 v144, 7, v141
	s_movk_i32 s9, 0xc0
	v_lshl_add_u64 v[130:131], s[18:19], 0, v[130:131]
	global_load_dwordx4 v[194:197], v[130:131], off offset:32
	global_load_dwordx4 v[198:201], v[130:131], off offset:1056
	global_load_dwordx4 v[202:205], v[130:131], off offset:2080
	global_load_dwordx4 v[206:209], v[130:131], off offset:3104
	v_add_co_u32_e32 v234, vcc, 0x2000, v130
	v_addc_co_u32_e32 v235, vcc, 0, v131, vcc
	global_load_dwordx4 v[218:221], v[234:235], off offset:32
	global_load_dwordx4 v[222:225], v[234:235], off offset:1056
	global_load_dwordx4 v[226:229], v[234:235], off offset:2080
	global_load_dwordx4 v[230:233], v[234:235], off offset:3104
	v_and_b32_e32 v146, 0x78, v141
	v_lshlrev_b32_e32 v176, 1, v146
	s_add_i32 s69, s69, s55
	s_mov_b32 s68, s10
	s_mov_b64 s[90:91], s[62:63]
	s_mov_b64 s[86:87], s[12:13]
	s_waitcnt vmcnt(0)
	v_mov_b32_e32 v130, v194
	v_mov_b32_e32 v131, v195
	v_mov_b32_e32 v132, v196
	v_mov_b32_e32 v133, v197
	v_mov_b32_e32 v136, v131
	v_mov_b32_e32 v137, v132
	v_mov_b32_e32 v131, v133
	v_pk_add_f32 v[130:131], v[136:137], v[130:131]
	s_nop 0
	v_add_f32_e32 v129, v130, v131
	v_fmamk_f32 v129, v129, 0x3b800000, v252
	v_cmp_gt_f32_e32 vcc, s53, v129
	v_mul_f32_e32 v130, 0x4b800000, v129
	s_nop 0
	v_cndmask_b32_e32 v129, v129, v130, vcc
	v_rsq_f32_e32 v129, v129
	s_nop 0
	v_mul_f32_e32 v130, 0x45800000, v129
	v_cndmask_b32_e32 v140, v129, v130, vcc
	v_pk_mul_f32 v[132:133], v[242:243], v[140:141] op_sel_hi:[1,0]
	v_pk_mul_f32 v[130:131], v[244:245], v[140:141] op_sel_hi:[1,0]
	v_cvt_pk_bf16_f32 v136, v132, v133
	v_mul_lo_u32 v132, v144, s9
	v_pk_mul_f32 v[142:143], v[248:249], v[140:141] op_sel_hi:[1,0]
	v_pk_mul_f32 v[138:139], v[246:247], v[140:141] op_sel_hi:[1,0]
	v_cvt_pk_bf16_f32 v137, v130, v131
	v_mov_b64_e32 v[130:131], s[30:31]
	v_ashrrev_i32_e32 v133, 31, v132
	v_cvt_pk_bf16_f32 v138, v138, v139
	v_cvt_pk_bf16_f32 v139, v142, v143
	v_mad_i64_i32 v[142:143], s[16:17], v128, s52, v[130:131]
	v_lshlrev_b64 v[132:133], 1, v[132:133]
	v_lshl_add_u64 v[144:145], v[142:143], 0, v[132:133]
	v_add_u32_e32 v129, 0x80, v141
	v_lshl_add_u64 v[144:145], v[144:145], 0, v[176:177]
	v_ashrrev_i32_e32 v129, 7, v129
	v_pk_mul_f32 v[116:117], v[116:117], v[140:141] op_sel_hi:[1,0]
	global_store_dwordx4 v[144:145], v[136:139], off
	v_pk_mul_f32 v[122:123], v[122:123], v[140:141] op_sel_hi:[1,0]
	v_pk_mul_f32 v[120:121], v[120:121], v[140:141] op_sel_hi:[1,0]
	v_pk_mul_f32 v[136:137], v[118:119], v[140:141] op_sel_hi:[1,0]
	v_cvt_pk_bf16_f32 v118, v116, v117
; __device__ __forceinline__ u32x4 pack8(f32x4 a, f32x4 b) { u32x4 r; r[0] = cvt_pk_bf16(a[0], a[1]); r[1] = cvt_pk_bf16(a[2], a[3]); r[2] = cvt_pk_bf16(b[0], b[1]); r[3] = cvt_pk_bf16(b[2], b[3]); return r; }
;     __device__ __forceinline__ void operator()(const AccT& acc, const Unit& u, int wr, int wc, int fr, int fq) const {
;     ...
;             for (int m = 0; m < 4; ++m) {
;                 const int row = row0 + ai * HALF + m * 16;
;                 const f32x4 pc = *(const f32x4*)(ssp + (size_t)row * 16 + 8);
;                 const float sc = rsqrtf(((pc[0] + pc[1]) + (pc[2] + pc[3])) * (1.0f / 256.0f) + EPS);
; #pragma unroll
;                 for (int bj = 0; bj < 2; ++bj) {
;                     const int col = colbase + bj * HALF, head = col >> 7, d = col & 127;
;                     *(u32x4*)(Kf + (size_t)row * NKF + head * 192 + d) = pack8(acc[ai][bj][m][0] * sc, acc[ai][bj][m][1] * sc);
	v_mul_lo_u32 v116, v129, s9
	v_ashrrev_i32_e32 v117, 31, v116
	v_lshlrev_b64 v[116:117], 1, v[116:117]
	v_cvt_pk_bf16_f32 v119, v136, v137
	v_cvt_pk_bf16_f32 v120, v120, v121
	v_cvt_pk_bf16_f32 v121, v122, v123
	v_lshl_add_u64 v[122:123], v[142:143], 0, v[116:117]
	v_lshl_add_u64 v[122:123], v[122:123], 0, v[176:177]
	global_store_dwordx4 v[122:123], v[118:121], off
	v_or_b32_e32 v122, 16, v128
	v_ashrrev_i32_e32 v123, 31, v122
	v_lshlrev_b64 v[118:119], 6, v[122:123]
	v_lshl_add_u64 v[118:119], s[18:19], 0, v[118:119]
	v_mov_b32_e32 v118, v198
	v_mov_b32_e32 v119, v199
	v_mov_b32_e32 v120, v200
	v_mov_b32_e32 v121, v201
	v_mov_b32_e32 v136, v119
	v_mov_b32_e32 v137, v120
	v_mov_b32_e32 v119, v121
	v_pk_add_f32 v[118:119], v[136:137], v[118:119]
	s_nop 0
	v_add_f32_e32 v118, v118, v119
	v_fmamk_f32 v118, v118, 0x3b800000, v252
	v_cmp_gt_f32_e32 vcc, s53, v118
	v_mul_f32_e32 v119, 0x4b800000, v118
	s_nop 0
	v_cndmask_b32_e32 v118, v118, v119, vcc
	v_rsq_f32_e32 v118, v118
	s_nop 0
	v_mul_f32_e32 v119, 0x45800000, v118
	v_cndmask_b32_e32 v118, v118, v119, vcc
	v_pk_mul_f32 v[102:103], v[102:103], v[118:119] op_sel_hi:[1,0]
	v_pk_mul_f32 v[100:101], v[100:101], v[118:119] op_sel_hi:[1,0]
	v_pk_mul_f32 v[104:105], v[104:105], v[118:119] op_sel_hi:[1,0]
	v_pk_mul_f32 v[106:107], v[106:107], v[118:119] op_sel_hi:[1,0]
	v_cvt_pk_bf16_f32 v100, v100, v101
	v_cvt_pk_bf16_f32 v101, v102, v103
	v_cvt_pk_bf16_f32 v102, v104, v105
	v_mad_i64_i32 v[104:105], s[16:17], v122, s52, v[130:131]
	v_cvt_pk_bf16_f32 v103, v106, v107
	v_lshl_add_u64 v[106:107], v[104:105], 0, v[132:133]
	v_lshl_add_u64 v[106:107], v[106:107], 0, v[176:177]
	v_lshl_add_u64 v[104:105], v[104:105], 0, v[116:117]
	global_store_dwordx4 v[106:107], v[100:103], off
	v_lshl_add_u64 v[104:105], v[104:105], 0, v[176:177]
	v_pk_mul_f32 v[106:107], v[114:115], v[118:119] op_sel_hi:[1,0]
	v_pk_mul_f32 v[102:103], v[110:111], v[118:119] op_sel_hi:[1,0]
	v_pk_mul_f32 v[100:101], v[108:109], v[118:119] op_sel_hi:[1,0]
	v_pk_mul_f32 v[108:109], v[112:113], v[118:119] op_sel_hi:[1,0]
	v_cvt_pk_bf16_f32 v100, v100, v101
	v_cvt_pk_bf16_f32 v101, v102, v103
	s_nop 0
	v_cvt_pk_bf16_f32 v102, v108, v109
	v_cvt_pk_bf16_f32 v103, v106, v107
	global_store_dwordx4 v[104:105], v[100:103], off
	v_or_b32_e32 v104, 32, v128
	v_ashrrev_i32_e32 v105, 31, v104
	v_lshlrev_b64 v[100:101], 6, v[104:105]
	v_lshl_add_u64 v[100:101], s[18:19], 0, v[100:101]
	v_mov_b32_e32 v100, v202
	v_mov_b32_e32 v101, v203
	v_mov_b32_e32 v102, v204
	v_mov_b32_e32 v103, v205
	v_mov_b32_e32 v106, v101
	v_mov_b32_e32 v107, v102
	v_mov_b32_e32 v101, v103
	v_pk_add_f32 v[100:101], v[106:107], v[100:101]
	s_nop 0
	v_add_f32_e32 v100, v100, v101
	v_fmamk_f32 v100, v100, 0x3b800000, v252
	v_cmp_gt_f32_e32 vcc, s53, v100
	v_mul_f32_e32 v101, 0x4b800000, v100
	s_nop 0
	v_cndmask_b32_e32 v100, v100, v101, vcc
	v_rsq_f32_e32 v100, v100
	s_nop 0
	v_mul_f32_e32 v101, 0x45800000, v100
	v_cndmask_b32_e32 v100, v100, v101, vcc
	v_pk_mul_f32 v[86:87], v[86:87], v[100:101] op_sel_hi:[1,0]
	v_pk_mul_f32 v[84:85], v[84:85], v[100:101] op_sel_hi:[1,0]
	v_pk_mul_f32 v[88:89], v[88:89], v[100:101] op_sel_hi:[1,0]
	v_pk_mul_f32 v[90:91], v[90:91], v[100:101] op_sel_hi:[1,0]
	v_cvt_pk_bf16_f32 v84, v84, v85
	v_cvt_pk_bf16_f32 v85, v86, v87
	v_cvt_pk_bf16_f32 v86, v88, v89
	v_mad_i64_i32 v[88:89], s[16:17], v104, s52, v[130:131]
	v_cvt_pk_bf16_f32 v87, v90, v91
	v_lshl_add_u64 v[90:91], v[88:89], 0, v[132:133]
	v_lshl_add_u64 v[90:91], v[90:91], 0, v[176:177]
	v_lshl_add_u64 v[88:89], v[88:89], 0, v[116:117]
	global_store_dwordx4 v[90:91], v[84:87], off
	v_lshl_add_u64 v[88:89], v[88:89], 0, v[176:177]
	v_pk_mul_f32 v[90:91], v[98:99], v[100:101] op_sel_hi:[1,0]
	v_pk_mul_f32 v[86:87], v[94:95], v[100:101] op_sel_hi:[1,0]
	v_pk_mul_f32 v[84:85], v[92:93], v[100:101] op_sel_hi:[1,0]
	v_pk_mul_f32 v[92:93], v[96:97], v[100:101] op_sel_hi:[1,0]
	v_cvt_pk_bf16_f32 v84, v84, v85
	v_cvt_pk_bf16_f32 v85, v86, v87
	s_nop 0
	v_cvt_pk_bf16_f32 v86, v92, v93
	v_cvt_pk_bf16_f32 v87, v90, v91
	global_store_dwordx4 v[88:89], v[84:87], off
	v_or_b32_e32 v88, 48, v128
	v_ashrrev_i32_e32 v89, 31, v88
	v_lshlrev_b64 v[84:85], 6, v[88:89]
	v_lshl_add_u64 v[84:85], s[18:19], 0, v[84:85]
	v_mov_b32_e32 v84, v206
	v_mov_b32_e32 v85, v207
	v_mov_b32_e32 v86, v208
	v_mov_b32_e32 v87, v209
	v_mov_b32_e32 v90, v85
	v_mov_b32_e32 v91, v86
	v_mov_b32_e32 v85, v87
	v_pk_add_f32 v[84:85], v[90:91], v[84:85]
	s_nop 0
	v_add_f32_e32 v84, v84, v85
	v_fmamk_f32 v84, v84, 0x3b800000, v252
	v_cmp_gt_f32_e32 vcc, s53, v84
	v_mul_f32_e32 v85, 0x4b800000, v84
	s_nop 0
	v_cndmask_b32_e32 v84, v84, v85, vcc
	v_rsq_f32_e32 v84, v84
	s_nop 0
	v_mul_f32_e32 v85, 0x45800000, v84
	v_cndmask_b32_e32 v84, v84, v85, vcc
	v_pk_mul_f32 v[70:71], v[70:71], v[84:85] op_sel_hi:[1,0]
	v_pk_mul_f32 v[68:69], v[68:69], v[84:85] op_sel_hi:[1,0]
	v_pk_mul_f32 v[72:73], v[72:73], v[84:85] op_sel_hi:[1,0]
	v_pk_mul_f32 v[74:75], v[74:75], v[84:85] op_sel_hi:[1,0]
	v_cvt_pk_bf16_f32 v68, v68, v69
	v_cvt_pk_bf16_f32 v69, v70, v71
	v_cvt_pk_bf16_f32 v70, v72, v73
	v_mad_i64_i32 v[72:73], s[16:17], v88, s52, v[130:131]
	v_cvt_pk_bf16_f32 v71, v74, v75
	v_lshl_add_u64 v[74:75], v[72:73], 0, v[132:133]
	v_lshl_add_u64 v[74:75], v[74:75], 0, v[176:177]
	v_lshl_add_u64 v[72:73], v[72:73], 0, v[116:117]
	global_store_dwordx4 v[74:75], v[68:71], off
	v_lshl_add_u64 v[72:73], v[72:73], 0, v[176:177]
	v_pk_mul_f32 v[74:75], v[82:83], v[84:85] op_sel_hi:[1,0]
	v_pk_mul_f32 v[70:71], v[78:79], v[84:85] op_sel_hi:[1,0]
	v_pk_mul_f32 v[68:69], v[76:77], v[84:85] op_sel_hi:[1,0]
	v_pk_mul_f32 v[76:77], v[80:81], v[84:85] op_sel_hi:[1,0]
; __device__ __forceinline__ u32x4 pack8(f32x4 a, f32x4 b) { u32x4 r; r[0] = cvt_pk_bf16(a[0], a[1]); r[1] = cvt_pk_bf16(a[2], a[3]); r[2] = cvt_pk_bf16(b[0], b[1]); r[3] = cvt_pk_bf16(b[2], b[3]); return r; }
;     __device__ __forceinline__ void operator()(const AccT& acc, const Unit& u, int wr, int wc, int fr, int fq) const {
;     ...
;             for (int m = 0; m < 4; ++m) {
;                 const int row = row0 + ai * HALF + m * 16;
;                 const f32x4 pc = *(const f32x4*)(ssp + (size_t)row * 16 + 8);
;                 const float sc = rsqrtf(((pc[0] + pc[1]) + (pc[2] + pc[3])) * (1.0f / 256.0f) + EPS);
; #pragma unroll
;                 for (int bj = 0; bj < 2; ++bj) {
;                     const int col = colbase + bj * HALF, head = col >> 7, d = col & 127;
;                     *(u32x4*)(Kf + (size_t)row * NKF + head * 192 + d) = pack8(acc[ai][bj][m][0] * sc, acc[ai][bj][m][1] * sc);
	v_cvt_pk_bf16_f32 v68, v68, v69
	v_cvt_pk_bf16_f32 v69, v70, v71
	s_nop 0
	v_cvt_pk_bf16_f32 v70, v76, v77
	v_cvt_pk_bf16_f32 v71, v74, v75
	global_store_dwordx4 v[72:73], v[68:71], off
	v_add_u32_e32 v72, 0x80, v128
	v_ashrrev_i32_e32 v73, 31, v72
	v_lshlrev_b64 v[68:69], 6, v[72:73]
	v_lshl_add_u64 v[68:69], s[18:19], 0, v[68:69]
	v_mov_b32_e32 v68, v218
	v_mov_b32_e32 v69, v219
	v_mov_b32_e32 v70, v220
	v_mov_b32_e32 v71, v221
	v_mov_b32_e32 v74, v69
	v_mov_b32_e32 v75, v70
	v_mov_b32_e32 v69, v71
	v_pk_add_f32 v[68:69], v[74:75], v[68:69]
	s_nop 0
	v_add_f32_e32 v68, v68, v69
	v_fmamk_f32 v68, v68, 0x3b800000, v252
	v_cmp_gt_f32_e32 vcc, s53, v68
	v_mul_f32_e32 v69, 0x4b800000, v68
	s_nop 0
	v_cndmask_b32_e32 v68, v68, v69, vcc
	v_rsq_f32_e32 v68, v68
	s_nop 0
	v_mul_f32_e32 v69, 0x45800000, v68
	v_cndmask_b32_e32 v68, v68, v69, vcc
	v_pk_mul_f32 v[54:55], v[54:55], v[68:69] op_sel_hi:[1,0]
	v_pk_mul_f32 v[52:53], v[52:53], v[68:69] op_sel_hi:[1,0]
	v_pk_mul_f32 v[56:57], v[56:57], v[68:69] op_sel_hi:[1,0]
	v_pk_mul_f32 v[58:59], v[58:59], v[68:69] op_sel_hi:[1,0]
	v_cvt_pk_bf16_f32 v52, v52, v53
	v_cvt_pk_bf16_f32 v53, v54, v55
	v_cvt_pk_bf16_f32 v54, v56, v57
	v_mad_i64_i32 v[56:57], s[16:17], v72, s52, v[130:131]
	v_cvt_pk_bf16_f32 v55, v58, v59
	v_lshl_add_u64 v[58:59], v[56:57], 0, v[132:133]
	v_lshl_add_u64 v[58:59], v[58:59], 0, v[176:177]
	v_lshl_add_u64 v[56:57], v[56:57], 0, v[116:117]
	global_store_dwordx4 v[58:59], v[52:55], off
	v_lshl_add_u64 v[56:57], v[56:57], 0, v[176:177]
	v_pk_mul_f32 v[58:59], v[66:67], v[68:69] op_sel_hi:[1,0]
	v_pk_mul_f32 v[54:55], v[62:63], v[68:69] op_sel_hi:[1,0]
	v_pk_mul_f32 v[52:53], v[60:61], v[68:69] op_sel_hi:[1,0]
	v_pk_mul_f32 v[60:61], v[64:65], v[68:69] op_sel_hi:[1,0]
	v_cvt_pk_bf16_f32 v52, v52, v53
	v_cvt_pk_bf16_f32 v53, v54, v55
	s_nop 0
	v_cvt_pk_bf16_f32 v54, v60, v61
	v_cvt_pk_bf16_f32 v55, v58, v59
	global_store_dwordx4 v[56:57], v[52:55], off
	v_add_u32_e32 v56, 0x90, v128
	v_ashrrev_i32_e32 v57, 31, v56
	v_lshlrev_b64 v[52:53], 6, v[56:57]
	v_lshl_add_u64 v[52:53], s[18:19], 0, v[52:53]
	v_mov_b32_e32 v52, v222
	v_mov_b32_e32 v53, v223
	v_mov_b32_e32 v54, v224
	v_mov_b32_e32 v55, v225
	v_mov_b32_e32 v58, v53
	v_mov_b32_e32 v59, v54
	v_mov_b32_e32 v53, v55
	v_pk_add_f32 v[52:53], v[58:59], v[52:53]
	s_nop 0
	v_add_f32_e32 v52, v52, v53
	v_fmamk_f32 v52, v52, 0x3b800000, v252
	v_cmp_gt_f32_e32 vcc, s53, v52
	v_mul_f32_e32 v53, 0x4b800000, v52
	s_nop 0
	v_cndmask_b32_e32 v52, v52, v53, vcc
	v_rsq_f32_e32 v52, v52
	s_nop 0
	v_mul_f32_e32 v53, 0x45800000, v52
	v_cndmask_b32_e32 v52, v52, v53, vcc
	v_pk_mul_f32 v[38:39], v[38:39], v[52:53] op_sel_hi:[1,0]
	v_pk_mul_f32 v[36:37], v[36:37], v[52:53] op_sel_hi:[1,0]
	v_pk_mul_f32 v[40:41], v[40:41], v[52:53] op_sel_hi:[1,0]
	v_pk_mul_f32 v[42:43], v[42:43], v[52:53] op_sel_hi:[1,0]
	v_cvt_pk_bf16_f32 v36, v36, v37
	v_cvt_pk_bf16_f32 v37, v38, v39
	v_cvt_pk_bf16_f32 v38, v40, v41
	v_mad_i64_i32 v[40:41], s[16:17], v56, s52, v[130:131]
	v_cvt_pk_bf16_f32 v39, v42, v43
	v_lshl_add_u64 v[42:43], v[40:41], 0, v[132:133]
	v_lshl_add_u64 v[42:43], v[42:43], 0, v[176:177]
	v_lshl_add_u64 v[40:41], v[40:41], 0, v[116:117]
	global_store_dwordx4 v[42:43], v[36:39], off
	v_lshl_add_u64 v[40:41], v[40:41], 0, v[176:177]
	v_pk_mul_f32 v[42:43], v[50:51], v[52:53] op_sel_hi:[1,0]
	v_pk_mul_f32 v[38:39], v[46:47], v[52:53] op_sel_hi:[1,0]
	v_pk_mul_f32 v[36:37], v[44:45], v[52:53] op_sel_hi:[1,0]
	v_pk_mul_f32 v[44:45], v[48:49], v[52:53] op_sel_hi:[1,0]
	v_cvt_pk_bf16_f32 v36, v36, v37
	v_cvt_pk_bf16_f32 v37, v38, v39
	s_nop 0
	v_cvt_pk_bf16_f32 v38, v44, v45
	v_cvt_pk_bf16_f32 v39, v42, v43
; __device__ __forceinline__ u32x4 pack8(f32x4 a, f32x4 b) { u32x4 r; r[0] = cvt_pk_bf16(a[0], a[1]); r[1] = cvt_pk_bf16(a[2], a[3]); r[2] = cvt_pk_bf16(b[0], b[1]); r[3] = cvt_pk_bf16(b[2], b[3]); return r; }
; template <class Epi, class Sched>
; __device__ __forceinline__ void gemm_phase(int wv, LAS unsigned char* lds, const Gemm g, const Sched& S, const Epi& E) { LIDS
;     ...
;         if (!has_next) break;
;     __device__ __forceinline__ void operator()(const AccT& acc, const Unit& u, int wr, int wc, int fr, int fq) const {
;     ...
;             for (int m = 0; m < 4; ++m) {
;                 const int row = row0 + ai * HALF + m * 16;
;                 const f32x4 pc = *(const f32x4*)(ssp + (size_t)row * 16 + 8);
;                 const float sc = rsqrtf(((pc[0] + pc[1]) + (pc[2] + pc[3])) * (1.0f / 256.0f) + EPS);
; #pragma unroll
;                 for (int bj = 0; bj < 2; ++bj) {
;                     const int col = colbase + bj * HALF, head = col >> 7, d = col & 127;
;                     *(u32x4*)(Kf + (size_t)row * NKF + head * 192 + d) = pack8(acc[ai][bj][m][0] * sc, acc[ai][bj][m][1] * sc);
	global_store_dwordx4 v[40:41], v[36:39], off
	v_add_u32_e32 v40, 0xa0, v128
	v_ashrrev_i32_e32 v41, 31, v40
	v_lshlrev_b64 v[36:37], 6, v[40:41]
	v_lshl_add_u64 v[36:37], s[18:19], 0, v[36:37]
	v_mov_b32_e32 v36, v226
	v_mov_b32_e32 v37, v227
	v_mov_b32_e32 v38, v228
	v_mov_b32_e32 v39, v229
	v_mov_b32_e32 v42, v37
	v_mov_b32_e32 v43, v38
	v_mov_b32_e32 v37, v39
	v_pk_add_f32 v[36:37], v[42:43], v[36:37]
	s_nop 0
	v_add_f32_e32 v36, v36, v37
	v_fmamk_f32 v36, v36, 0x3b800000, v252
	v_cmp_gt_f32_e32 vcc, s53, v36
	v_mul_f32_e32 v37, 0x4b800000, v36
	s_nop 0
	v_cndmask_b32_e32 v36, v36, v37, vcc
	v_rsq_f32_e32 v36, v36
	s_nop 0
	v_mul_f32_e32 v37, 0x45800000, v36
	v_cndmask_b32_e32 v36, v36, v37, vcc
	v_pk_mul_f32 v[22:23], v[22:23], v[36:37] op_sel_hi:[1,0]
	v_pk_mul_f32 v[20:21], v[20:21], v[36:37] op_sel_hi:[1,0]
	v_pk_mul_f32 v[24:25], v[24:25], v[36:37] op_sel_hi:[1,0]
	v_pk_mul_f32 v[26:27], v[26:27], v[36:37] op_sel_hi:[1,0]
	v_cvt_pk_bf16_f32 v20, v20, v21
	v_cvt_pk_bf16_f32 v21, v22, v23
	v_cvt_pk_bf16_f32 v22, v24, v25
	v_mad_i64_i32 v[24:25], s[16:17], v40, s52, v[130:131]
	v_cvt_pk_bf16_f32 v23, v26, v27
	v_lshl_add_u64 v[26:27], v[24:25], 0, v[132:133]
	v_lshl_add_u64 v[26:27], v[26:27], 0, v[176:177]
	v_lshl_add_u64 v[24:25], v[24:25], 0, v[116:117]
	global_store_dwordx4 v[26:27], v[20:23], off
	v_lshl_add_u64 v[24:25], v[24:25], 0, v[176:177]
	v_pk_mul_f32 v[26:27], v[34:35], v[36:37] op_sel_hi:[1,0]
	v_pk_mul_f32 v[22:23], v[30:31], v[36:37] op_sel_hi:[1,0]
	v_pk_mul_f32 v[20:21], v[28:29], v[36:37] op_sel_hi:[1,0]
	v_pk_mul_f32 v[28:29], v[32:33], v[36:37] op_sel_hi:[1,0]
	v_cvt_pk_bf16_f32 v20, v20, v21
	v_cvt_pk_bf16_f32 v21, v22, v23
	s_nop 0
	v_cvt_pk_bf16_f32 v22, v28, v29
	v_cvt_pk_bf16_f32 v23, v26, v27
	global_store_dwordx4 v[24:25], v[20:23], off
	v_add_u32_e32 v24, 0xb0, v128
	v_ashrrev_i32_e32 v25, 31, v24
	v_lshlrev_b64 v[20:21], 6, v[24:25]
	v_lshl_add_u64 v[20:21], s[18:19], 0, v[20:21]
	v_mov_b32_e32 v20, v230
	v_mov_b32_e32 v21, v231
	v_mov_b32_e32 v22, v232
	v_mov_b32_e32 v23, v233
	v_mov_b32_e32 v26, v21
	v_mov_b32_e32 v27, v22
	v_mov_b32_e32 v21, v23
	v_pk_add_f32 v[20:21], v[26:27], v[20:21]
	s_nop 0
	v_add_f32_e32 v20, v20, v21
	v_fmamk_f32 v20, v20, 0x3b800000, v252
	v_cmp_gt_f32_e32 vcc, s53, v20
	v_mul_f32_e32 v21, 0x4b800000, v20
	s_nop 0
	v_cndmask_b32_e32 v20, v20, v21, vcc
	v_rsq_f32_e32 v20, v20
	s_nop 0
	v_mul_f32_e32 v21, 0x45800000, v20
	v_cndmask_b32_e32 v20, v20, v21, vcc
	v_pk_mul_f32 v[6:7], v[6:7], v[20:21] op_sel_hi:[1,0]
	v_pk_mul_f32 v[4:5], v[4:5], v[20:21] op_sel_hi:[1,0]
	v_pk_mul_f32 v[8:9], v[8:9], v[20:21] op_sel_hi:[1,0]
	v_pk_mul_f32 v[10:11], v[10:11], v[20:21] op_sel_hi:[1,0]
	v_cvt_pk_bf16_f32 v4, v4, v5
	v_cvt_pk_bf16_f32 v5, v6, v7
	v_cvt_pk_bf16_f32 v6, v8, v9
	v_mad_i64_i32 v[8:9], s[16:17], v24, s52, v[130:131]
	v_cvt_pk_bf16_f32 v7, v10, v11
	v_lshl_add_u64 v[10:11], v[8:9], 0, v[132:133]
	v_lshl_add_u64 v[10:11], v[10:11], 0, v[176:177]
	v_lshl_add_u64 v[8:9], v[8:9], 0, v[116:117]
	global_store_dwordx4 v[10:11], v[4:7], off
	v_lshl_add_u64 v[8:9], v[8:9], 0, v[176:177]
	s_andn2_b64 vcc, exec, s[4:5]
	v_pk_mul_f32 v[6:7], v[14:15], v[20:21] op_sel_hi:[1,0]
	v_pk_mul_f32 v[4:5], v[12:13], v[20:21] op_sel_hi:[1,0]
	s_mov_b32 s16, s8
	v_readlane_b32 s4, v254, 46
	v_pk_mul_f32 v[10:11], v[18:19], v[20:21] op_sel_hi:[1,0]
	v_pk_mul_f32 v[12:13], v[16:17], v[20:21] op_sel_hi:[1,0]
	v_cvt_pk_bf16_f32 v4, v4, v5
	v_cvt_pk_bf16_f32 v5, v6, v7
	v_readlane_b32 s5, v254, 47
	v_cvt_pk_bf16_f32 v6, v12, v13
	v_cvt_pk_bf16_f32 v7, v10, v11
	global_store_dwordx4 v[8:9], v[4:7], off
	s_cbranch_vccz .LBB0_174
